# E phases: row loop unrolled 3x with rotated register names (no per-row rotation moves); on top of v14
# speedup vs baseline: 1.0042x; 1.0039x over previous
; #define GAS __attribute__((address_space(1)))
; DI unsigned pk2(float lo, float hi) { f32x2_t v = {lo, hi}; bf16x2_t b = __builtin_convertvector(v, bf16x2_t); return __builtin_bit_cast(unsigned, b); }
; DI void phase_e(const Ctx& C, int nslab, int has_post, int pl, int ps, float pw, int has_pre, int ql, int qs, int nrows,
;                 const GAS float* xsrc, const GAS float* csrc, GAS float* xdst, GAS float* cdst, bool xs16, bool xd16) {
;     ...
;         if (has_pre) {
;             float ss = 0.f;
; #pragma unroll
;             for (int j = 0; j < 4; ++j) ss += (v[j][0] * v[j][0] + v[j][1] * v[j][1]) + (v[j][2] * v[j][2] + v[j][3] * v[j][3]);
;             const float r = rsqrtf(wave_sum(ss) * (1.0f / 1024.0f) + EPS);
; #pragma unroll
;             for (int j = 0; j < 4; ++j) { const f32x4 h = ((v[j] * r) * gpr[j]) * (1.0f + sc[j]) + sh[j];
;                 u32x2 w; w.x = pk2(h[0], h[1]); w.y = pk2(h[2], h[3]); *(GAS u32x2*)(H + (size_t)row * 1024 + 256 * j + 4 * lane) = w; }
;         }
.LBB0_189:
	v_pk_mul_f32 v[110:111], v[96:97], v[96:97]
	v_pk_mul_f32 v[112:113], v[94:95], v[94:95]
	s_ashr_i32 s3, s2, 31
	v_pk_mov_b32 v[114:115], v[112:113], v[110:111] op_sel:[1,0]
	v_mov_b32_e32 v113, v111
	v_pk_add_f32 v[110:111], v[114:115], v[112:113]
	v_pk_mul_f32 v[112:113], v[92:93], v[92:93]
	v_pk_add_f32 v[110:111], v[110:111], v[110:111] op_sel_hi:[0,1]
	v_pk_mul_f32 v[114:115], v[90:91], v[90:91]
	v_mul_f32_e32 v110, v22, v22
	v_pk_mov_b32 v[116:117], v[114:115], v[112:113] op_sel:[1,0]
	v_mov_b32_e32 v115, v113
	v_pk_add_f32 v[112:113], v[116:117], v[114:115]
	v_pk_fma_f32 v[114:115], v[22:23], v[22:23], v[110:111] op_sel_hi:[1,1,0]
	v_mul_f32_e32 v110, v24, v24
	v_pk_add_f32 v[112:113], v[112:113], v[112:113] op_sel_hi:[0,1]
	v_pk_fma_f32 v[116:117], v[24:25], v[24:25], v[110:111] op_sel_hi:[1,1,0]
	v_mul_f32_e32 v114, v82, v82
	v_mul_f32_e32 v116, v83, v83
	v_mul_f32_e32 v112, v84, v84
	v_mul_f32_e32 v110, v85, v85
	v_pk_add_f32 v[114:115], v[114:115], v[116:117]
	v_pk_add_f32 v[110:111], v[112:113], v[110:111]
	s_lshl_b64 s[2:3], s[2:3], 11
	v_pk_add_f32 v[110:111], v[114:115], v[110:111]
	v_lshl_add_u64 v[114:115], v[100:101], 0, s[2:3]
	v_add_f32_e32 v109, v110, v111
	s_nop 1
	v_add_f32_dpp v109, v109, v109 quad_perm:[1,0,3,2] row_mask:0xf bank_mask:0xf
	s_nop 1
	v_add_f32_dpp v109, v109, v109 quad_perm:[2,3,0,1] row_mask:0xf bank_mask:0xf
	s_nop 1
	v_add_f32_dpp v109, v109, v109 row_half_mirror row_mask:0xf bank_mask:0xf
	s_nop 1
	v_add_f32_dpp v109, v109, v109 row_mirror row_mask:0xf bank_mask:0xf
	s_nop 1
	v_add_f32_dpp v109, v109, v109 row_bcast:15 row_mask:0xa bank_mask:0xf
	s_nop 1
	v_add_f32_dpp v109, v109, v109 row_bcast:31 row_mask:0xc bank_mask:0xf
	s_nop 0
	v_readlane_b32 s64, v109, 63
	s_nop 1
	v_mov_b32_e32 v109, s64
	s_waitcnt lgkmcnt(0)
	s_add_i32 s6, s6, 8
	s_cmp_lt_i32 s6, s8
	s_waitcnt vmcnt(3)
	v_pk_add_f32 v[110:111], v[68:69], 1.0 op_sel_hi:[1,0]
	v_fmamk_f32 v109, v109, 0x3a800000, v108
	v_mul_f32_e32 v112, 0x4b800000, v109
	v_cmp_gt_f32_e32 vcc, s22, v109
	s_nop 1
	v_cndmask_b32_e32 v109, v109, v112, vcc
	v_rsq_f32_e32 v109, v109
	v_pk_add_f32 v[112:113], v[66:67], 1.0 op_sel_hi:[1,0]
	v_mul_f32_e32 v116, 0x45800000, v109
	v_cndmask_b32_e32 v116, v109, v116, vcc
	v_pk_mul_f32 v[96:97], v[96:97], v[116:117] op_sel_hi:[1,0]
	v_pk_mul_f32 v[94:95], v[94:95], v[116:117] op_sel_hi:[1,0]
	v_pk_mul_f32 v[96:97], v[4:5], v[96:97]
	v_pk_mul_f32 v[94:95], v[2:3], v[94:95]
	v_pk_fma_f32 v[96:97], v[110:111], v[96:97], v[64:65]
	v_pk_fma_f32 v[94:95], v[112:113], v[94:95], v[62:63]
	v_pk_mul_f32 v[92:93], v[92:93], v[116:117] op_sel_hi:[1,0]
	v_cvt_pk_bf16_f32 v94, v94, v95
	v_cvt_pk_bf16_f32 v95, v96, v97
	v_pk_mul_f32 v[90:91], v[90:91], v[116:117] op_sel_hi:[1,0]
	global_store_dwordx2 v[114:115], v[94:95], off
	v_pk_mul_f32 v[90:91], v[6:7], v[90:91]
	v_pk_mul_f32 v[92:93], v[8:9], v[92:93]
	v_pk_add_f32 v[94:95], v[60:61], 1.0 op_sel_hi:[1,0]
	v_pk_add_f32 v[96:97], v[58:59], 1.0 op_sel_hi:[1,0]
	v_pk_fma_f32 v[92:93], v[94:95], v[92:93], v[72:73]
	v_pk_fma_f32 v[90:91], v[96:97], v[90:91], v[70:71]
	v_pk_mul_f32 v[24:25], v[24:25], v[116:117] op_sel_hi:[1,0]
	v_cvt_pk_bf16_f32 v90, v90, v91
	v_cvt_pk_bf16_f32 v91, v92, v93
	v_pk_mul_f32 v[22:23], v[22:23], v[116:117] op_sel_hi:[1,0]
	global_store_dwordx2 v[114:115], v[90:91], off offset:512
	v_pk_mul_f32 v[22:23], v[10:11], v[22:23]
	v_pk_mul_f32 v[24:25], v[12:13], v[24:25]
	v_pk_add_f32 v[90:91], v[56:57], 1.0 op_sel_hi:[1,0]
	v_pk_add_f32 v[92:93], v[54:55], 1.0 op_sel_hi:[1,0]
	s_waitcnt vmcnt(3)
	v_pk_fma_f32 v[24:25], v[90:91], v[24:25], v[80:81]
	v_pk_fma_f32 v[22:23], v[92:93], v[22:23], v[78:79]
	v_pk_mul_f32 v[84:85], v[84:85], v[116:117] op_sel_hi:[1,0]
	v_cvt_pk_bf16_f32 v22, v22, v23
	v_cvt_pk_bf16_f32 v23, v24, v25
	v_pk_mul_f32 v[82:83], v[82:83], v[116:117] op_sel_hi:[1,0]
	global_store_dwordx2 v[114:115], v[22:23], off offset:1024
	v_pk_mul_f32 v[82:83], v[14:15], v[82:83]
	v_pk_mul_f32 v[84:85], v[16:17], v[84:85]
	v_pk_add_f32 v[22:23], v[52:53], 1.0 op_sel_hi:[1,0]
	v_pk_add_f32 v[24:25], v[50:51], 1.0 op_sel_hi:[1,0]
	s_waitcnt vmcnt(3)
	v_pk_fma_f32 v[84:85], v[22:23], v[84:85], v[76:77]
	v_pk_fma_f32 v[82:83], v[24:25], v[82:83], v[74:75]
	v_mov_b64_e32 v[22:23], v[38:39]
	v_cvt_pk_bf16_f32 v82, v82, v83
	v_cvt_pk_bf16_f32 v83, v84, v85
	global_store_dwordx2 v[114:115], v[82:83], off offset:1536
	v_mov_b64_e32 v[24:25], v[40:41]
	v_mov_b64_e32 v[38:39], v[86:87]
	v_mov_b64_e32 v[40:41], v[88:89]
	s_cbranch_scc0 .LBB0_194

; #define GAS __attribute__((address_space(1)))
; DI unsigned pk2(float lo, float hi) { f32x2_t v = {lo, hi}; bf16x2_t b = __builtin_convertvector(v, bf16x2_t); return __builtin_bit_cast(unsigned, b); }
; DI void phase_e(const Ctx& C, int nslab, int has_post, int pl, int ps, float pw, int has_pre, int ql, int qs, int nrows,
;                 const GAS float* xsrc, const GAS float* csrc, GAS float* xdst, GAS float* cdst, bool xs16, bool xd16) {
;     ...
;     int i = C.wave;
;     if (i < total) E_LOAD(i, vN, yN);
;     if (i + 8 < total) E_LOAD(i + 8, vM, yM);
;     for (; i < total; i += 8) {
;         const int row = E_ROW(i);
;         const bool isx = row < MX; const int mi = isx ? (row >> 13) : 4;
;         f32x4 v[4]; u32x2 yw[4];
; #pragma unroll
;         for (int j = 0; j < 4; ++j) { v[j] = vN[j]; yw[j] = yN[j]; vN[j] = vM[j]; yN[j] = yM[j]; }
;         if (i + 16 < total) E_LOAD(i + 16, vM, yM);
;     ...
;         if (has_pre) {
;             float ss = 0.f;
; #pragma unroll
;             for (int j = 0; j < 4; ++j) ss += (v[j][0] * v[j][0] + v[j][1] * v[j][1]) + (v[j][2] * v[j][2] + v[j][3] * v[j][3]);
;             const float r = rsqrtf(wave_sum(ss) * (1.0f / 1024.0f) + EPS);
; #pragma unroll
;             for (int j = 0; j < 4; ++j) { const f32x4 h = ((v[j] * r) * gpr[j]) * (1.0f + sc[j]) + sh[j];
;                 u32x2 w; w.x = pk2(h[0], h[1]); w.y = pk2(h[2], h[3]); *(GAS u32x2*)(H + (size_t)row * 1024 + 256 * j + 4 * lane) = w; }
;         }
.LBB0_189_u0:
	v_pk_mul_f32 v[110:111], v[48:49], v[48:49]
	v_pk_mul_f32 v[112:113], v[46:47], v[46:47]
	s_ashr_i32 s3, s2, 31
	v_pk_mov_b32 v[114:115], v[112:113], v[110:111] op_sel:[1,0]
	v_mov_b32_e32 v113, v111
	v_pk_add_f32 v[110:111], v[114:115], v[112:113]
	v_pk_mul_f32 v[112:113], v[28:29], v[28:29]
	v_pk_add_f32 v[110:111], v[110:111], v[110:111] op_sel_hi:[0,1]
	v_pk_mul_f32 v[114:115], v[26:27], v[26:27]
	v_mul_f32_e32 v110, v22, v22
	v_pk_mov_b32 v[116:117], v[114:115], v[112:113] op_sel:[1,0]
	v_mov_b32_e32 v115, v113
	v_pk_add_f32 v[112:113], v[116:117], v[114:115]
	v_pk_fma_f32 v[114:115], v[22:23], v[22:23], v[110:111] op_sel_hi:[1,1,0]
	v_mul_f32_e32 v110, v24, v24
	v_pk_add_f32 v[112:113], v[112:113], v[112:113] op_sel_hi:[0,1]
	v_pk_fma_f32 v[116:117], v[24:25], v[24:25], v[110:111] op_sel_hi:[1,1,0]
	v_mul_f32_e32 v114, v18, v18
	v_mul_f32_e32 v116, v19, v19
	v_mul_f32_e32 v112, v20, v20
	v_mul_f32_e32 v110, v21, v21
	v_pk_add_f32 v[114:115], v[114:115], v[116:117]
	v_pk_add_f32 v[110:111], v[112:113], v[110:111]
	s_lshl_b64 s[2:3], s[2:3], 11
	v_pk_add_f32 v[110:111], v[114:115], v[110:111]
	v_lshl_add_u64 v[114:115], v[100:101], 0, s[2:3]
	v_add_f32_e32 v109, v110, v111
	s_nop 1
	v_add_f32_dpp v109, v109, v109 quad_perm:[1,0,3,2] row_mask:0xf bank_mask:0xf
	s_nop 1
	v_add_f32_dpp v109, v109, v109 quad_perm:[2,3,0,1] row_mask:0xf bank_mask:0xf
	s_nop 1
	v_add_f32_dpp v109, v109, v109 row_half_mirror row_mask:0xf bank_mask:0xf
	s_nop 1
	v_add_f32_dpp v109, v109, v109 row_mirror row_mask:0xf bank_mask:0xf
	s_nop 1
	v_add_f32_dpp v109, v109, v109 row_bcast:15 row_mask:0xa bank_mask:0xf
	s_nop 1
	v_add_f32_dpp v109, v109, v109 row_bcast:31 row_mask:0xc bank_mask:0xf
	s_nop 0
	v_readlane_b32 s64, v109, 63
	s_nop 1
	v_mov_b32_e32 v109, s64
	s_waitcnt lgkmcnt(0)
	s_add_i32 s6, s6, 8
	s_cmp_lt_i32 s6, s8
	s_waitcnt vmcnt(3)
	v_pk_add_f32 v[110:111], v[68:69], 1.0 op_sel_hi:[1,0]
	v_fmamk_f32 v109, v109, 0x3a800000, v108
	v_mul_f32_e32 v112, 0x4b800000, v109
	v_cmp_gt_f32_e32 vcc, s22, v109
	s_nop 1
	v_cndmask_b32_e32 v109, v109, v112, vcc
	v_rsq_f32_e32 v109, v109
	v_pk_add_f32 v[112:113], v[66:67], 1.0 op_sel_hi:[1,0]
	v_mul_f32_e32 v116, 0x45800000, v109
	v_cndmask_b32_e32 v116, v109, v116, vcc
	v_pk_mul_f32 v[48:49], v[48:49], v[116:117] op_sel_hi:[1,0]
	v_pk_mul_f32 v[46:47], v[46:47], v[116:117] op_sel_hi:[1,0]
	v_pk_mul_f32 v[48:49], v[4:5], v[48:49]
	v_pk_mul_f32 v[46:47], v[2:3], v[46:47]
	v_pk_fma_f32 v[48:49], v[110:111], v[48:49], v[64:65]
	v_pk_fma_f32 v[46:47], v[112:113], v[46:47], v[62:63]
	v_pk_mul_f32 v[28:29], v[28:29], v[116:117] op_sel_hi:[1,0]
	v_cvt_pk_bf16_f32 v46, v46, v47
	v_cvt_pk_bf16_f32 v47, v48, v49
	v_pk_mul_f32 v[26:27], v[26:27], v[116:117] op_sel_hi:[1,0]
	global_store_dwordx2 v[114:115], v[46:47], off
	v_pk_mul_f32 v[26:27], v[6:7], v[26:27]
	v_pk_mul_f32 v[28:29], v[8:9], v[28:29]
	v_pk_add_f32 v[46:47], v[60:61], 1.0 op_sel_hi:[1,0]
	v_pk_add_f32 v[48:49], v[58:59], 1.0 op_sel_hi:[1,0]
	v_pk_fma_f32 v[28:29], v[46:47], v[28:29], v[72:73]
	v_pk_fma_f32 v[26:27], v[48:49], v[26:27], v[70:71]
	v_pk_mul_f32 v[24:25], v[24:25], v[116:117] op_sel_hi:[1,0]
	v_cvt_pk_bf16_f32 v26, v26, v27
	v_cvt_pk_bf16_f32 v27, v28, v29
	v_pk_mul_f32 v[22:23], v[22:23], v[116:117] op_sel_hi:[1,0]
	global_store_dwordx2 v[114:115], v[26:27], off offset:512
	v_pk_mul_f32 v[22:23], v[10:11], v[22:23]
	v_pk_mul_f32 v[24:25], v[12:13], v[24:25]
	v_pk_add_f32 v[26:27], v[56:57], 1.0 op_sel_hi:[1,0]
	v_pk_add_f32 v[28:29], v[54:55], 1.0 op_sel_hi:[1,0]
	s_waitcnt vmcnt(3)
	v_pk_fma_f32 v[24:25], v[26:27], v[24:25], v[80:81]
	v_pk_fma_f32 v[22:23], v[28:29], v[22:23], v[78:79]
	v_pk_mul_f32 v[20:21], v[20:21], v[116:117] op_sel_hi:[1,0]
	v_cvt_pk_bf16_f32 v22, v22, v23
	v_cvt_pk_bf16_f32 v23, v24, v25
	v_pk_mul_f32 v[18:19], v[18:19], v[116:117] op_sel_hi:[1,0]
	global_store_dwordx2 v[114:115], v[22:23], off offset:1024
	v_pk_mul_f32 v[18:19], v[14:15], v[18:19]
	v_pk_mul_f32 v[20:21], v[16:17], v[20:21]
	v_pk_add_f32 v[22:23], v[52:53], 1.0 op_sel_hi:[1,0]
	v_pk_add_f32 v[24:25], v[50:51], 1.0 op_sel_hi:[1,0]
	s_waitcnt vmcnt(3)
	v_pk_fma_f32 v[20:21], v[22:23], v[20:21], v[76:77]
	v_pk_fma_f32 v[18:19], v[24:25], v[18:19], v[74:75]
	v_mov_b64_e32 v[22:23], v[38:39]
	v_cvt_pk_bf16_f32 v18, v18, v19
	v_cvt_pk_bf16_f32 v19, v20, v21
	global_store_dwordx2 v[114:115], v[18:19], off offset:1536
	v_mov_b64_e32 v[24:25], v[40:41]
	v_mov_b64_e32 v[38:39], v[86:87]
	v_mov_b64_e32 v[40:41], v[88:89]
	s_cbranch_scc0 .LBB0_194
.LBB0_190_u1:
	s_add_i32 s2, s6, 16
	s_cmp_ge_i32 s2, s8
	s_cbranch_scc1 .LBB0_192_u1
	s_add_i32 s23, s11, s6
	s_add_i32 s3, s12, s6
	s_add_i32 s23, s23, 0x8010
	s_cmp_lt_i32 s2, s7
	s_cselect_b32 s2, s3, s23
	s_add_i32 s23, s2, 0xffff8000
	s_ashr_i32 s3, s2, 31
	s_cmp_lt_i32 s2, 0x8000
	s_cselect_b32 s3, s3, 0
	s_cselect_b32 s2, s2, s23
	s_cselect_b32 s23, s37, s41
	s_cselect_b32 s24, s36, s40
	s_lshl_b64 s[2:3], s[2:3], 12
	s_add_u32 s2, s24, s2
	s_addc_u32 s3, s23, s3
	global_load_dwordx4 v[46:49], v98, s[2:3] nt
	global_load_dwordx4 v[26:29], v98, s[2:3] offset:1024 nt
	global_load_dwordx4 v[86:89], v98, s[2:3] offset:2048 nt
	global_load_dwordx4 v[18:21], v98, s[2:3] offset:3072 nt

; #define GAS __attribute__((address_space(1)))
; DI unsigned pk2(float lo, float hi) { f32x2_t v = {lo, hi}; bf16x2_t b = __builtin_convertvector(v, bf16x2_t); return __builtin_bit_cast(unsigned, b); }
; DI void phase_e(const Ctx& C, int nslab, int has_post, int pl, int ps, float pw, int has_pre, int ql, int qs, int nrows,
;                 const GAS float* xsrc, const GAS float* csrc, GAS float* xdst, GAS float* cdst, bool xs16, bool xd16) {
;     ...
;         if (has_pre) {
;             float ss = 0.f;
; #pragma unroll
;             for (int j = 0; j < 4; ++j) ss += (v[j][0] * v[j][0] + v[j][1] * v[j][1]) + (v[j][2] * v[j][2] + v[j][3] * v[j][3]);
;             const float r = rsqrtf(wave_sum(ss) * (1.0f / 1024.0f) + EPS);
; #pragma unroll
;             for (int j = 0; j < 4; ++j) { const f32x4 h = ((v[j] * r) * gpr[j]) * (1.0f + sc[j]) + sh[j];
;                 u32x2 w; w.x = pk2(h[0], h[1]); w.y = pk2(h[2], h[3]); *(GAS u32x2*)(H + (size_t)row * 1024 + 256 * j + 4 * lane) = w; }
.LBB0_189_u1:
	v_pk_mul_f32 v[110:111], v[32:33], v[32:33]
	v_pk_mul_f32 v[112:113], v[30:31], v[30:31]
	s_ashr_i32 s3, s2, 31
	v_pk_mov_b32 v[114:115], v[112:113], v[110:111] op_sel:[1,0]
	v_mov_b32_e32 v113, v111
	v_pk_add_f32 v[110:111], v[114:115], v[112:113]
	v_pk_mul_f32 v[112:113], v[36:37], v[36:37]
	v_pk_add_f32 v[110:111], v[110:111], v[110:111] op_sel_hi:[0,1]
	v_pk_mul_f32 v[114:115], v[34:35], v[34:35]
	v_mul_f32_e32 v110, v22, v22
	v_pk_mov_b32 v[116:117], v[114:115], v[112:113] op_sel:[1,0]
	v_mov_b32_e32 v115, v113
	v_pk_add_f32 v[112:113], v[116:117], v[114:115]
	v_pk_fma_f32 v[114:115], v[22:23], v[22:23], v[110:111] op_sel_hi:[1,1,0]
	v_mul_f32_e32 v110, v24, v24
	v_pk_add_f32 v[112:113], v[112:113], v[112:113] op_sel_hi:[0,1]
	v_pk_fma_f32 v[116:117], v[24:25], v[24:25], v[110:111] op_sel_hi:[1,1,0]
	v_mul_f32_e32 v114, v42, v42
	v_mul_f32_e32 v116, v43, v43
	v_mul_f32_e32 v112, v44, v44
	v_mul_f32_e32 v110, v45, v45
	v_pk_add_f32 v[114:115], v[114:115], v[116:117]
	v_pk_add_f32 v[110:111], v[112:113], v[110:111]
	s_lshl_b64 s[2:3], s[2:3], 11
	v_pk_add_f32 v[110:111], v[114:115], v[110:111]
	v_lshl_add_u64 v[114:115], v[100:101], 0, s[2:3]
	v_add_f32_e32 v109, v110, v111
	s_nop 1
	v_add_f32_dpp v109, v109, v109 quad_perm:[1,0,3,2] row_mask:0xf bank_mask:0xf
	s_nop 1
	v_add_f32_dpp v109, v109, v109 quad_perm:[2,3,0,1] row_mask:0xf bank_mask:0xf
	s_nop 1
	v_add_f32_dpp v109, v109, v109 row_half_mirror row_mask:0xf bank_mask:0xf
	s_nop 1
	v_add_f32_dpp v109, v109, v109 row_mirror row_mask:0xf bank_mask:0xf
	s_nop 1
	v_add_f32_dpp v109, v109, v109 row_bcast:15 row_mask:0xa bank_mask:0xf
	s_nop 1
	v_add_f32_dpp v109, v109, v109 row_bcast:31 row_mask:0xc bank_mask:0xf
	s_nop 0
	v_readlane_b32 s64, v109, 63
	s_nop 1
	v_mov_b32_e32 v109, s64
	s_waitcnt lgkmcnt(0)
	s_add_i32 s6, s6, 8
	s_cmp_lt_i32 s6, s8
	s_waitcnt vmcnt(3)
	v_pk_add_f32 v[110:111], v[68:69], 1.0 op_sel_hi:[1,0]
	v_fmamk_f32 v109, v109, 0x3a800000, v108
	v_mul_f32_e32 v112, 0x4b800000, v109
	v_cmp_gt_f32_e32 vcc, s22, v109
	s_nop 1
	v_cndmask_b32_e32 v109, v109, v112, vcc
	v_rsq_f32_e32 v109, v109
	v_pk_add_f32 v[112:113], v[66:67], 1.0 op_sel_hi:[1,0]
	v_mul_f32_e32 v116, 0x45800000, v109
	v_cndmask_b32_e32 v116, v109, v116, vcc
	v_pk_mul_f32 v[32:33], v[32:33], v[116:117] op_sel_hi:[1,0]
	v_pk_mul_f32 v[30:31], v[30:31], v[116:117] op_sel_hi:[1,0]
	v_pk_mul_f32 v[32:33], v[4:5], v[32:33]
	v_pk_mul_f32 v[30:31], v[2:3], v[30:31]
	v_pk_fma_f32 v[32:33], v[110:111], v[32:33], v[64:65]
	v_pk_fma_f32 v[30:31], v[112:113], v[30:31], v[62:63]
	v_pk_mul_f32 v[36:37], v[36:37], v[116:117] op_sel_hi:[1,0]
	v_cvt_pk_bf16_f32 v30, v30, v31
	v_cvt_pk_bf16_f32 v31, v32, v33
	v_pk_mul_f32 v[34:35], v[34:35], v[116:117] op_sel_hi:[1,0]
	global_store_dwordx2 v[114:115], v[30:31], off
	v_pk_mul_f32 v[34:35], v[6:7], v[34:35]
	v_pk_mul_f32 v[36:37], v[8:9], v[36:37]
	v_pk_add_f32 v[30:31], v[60:61], 1.0 op_sel_hi:[1,0]
	v_pk_add_f32 v[32:33], v[58:59], 1.0 op_sel_hi:[1,0]
	v_pk_fma_f32 v[36:37], v[30:31], v[36:37], v[72:73]
	v_pk_fma_f32 v[34:35], v[32:33], v[34:35], v[70:71]
	v_pk_mul_f32 v[24:25], v[24:25], v[116:117] op_sel_hi:[1,0]
	v_cvt_pk_bf16_f32 v34, v34, v35
	v_cvt_pk_bf16_f32 v35, v36, v37
	v_pk_mul_f32 v[22:23], v[22:23], v[116:117] op_sel_hi:[1,0]
	global_store_dwordx2 v[114:115], v[34:35], off offset:512
	v_pk_mul_f32 v[22:23], v[10:11], v[22:23]
	v_pk_mul_f32 v[24:25], v[12:13], v[24:25]
	v_pk_add_f32 v[34:35], v[56:57], 1.0 op_sel_hi:[1,0]
	v_pk_add_f32 v[36:37], v[54:55], 1.0 op_sel_hi:[1,0]
	s_waitcnt vmcnt(3)
	v_pk_fma_f32 v[24:25], v[34:35], v[24:25], v[80:81]
	v_pk_fma_f32 v[22:23], v[36:37], v[22:23], v[78:79]
	v_pk_mul_f32 v[44:45], v[44:45], v[116:117] op_sel_hi:[1,0]
	v_cvt_pk_bf16_f32 v22, v22, v23
	v_cvt_pk_bf16_f32 v23, v24, v25
	v_pk_mul_f32 v[42:43], v[42:43], v[116:117] op_sel_hi:[1,0]
	global_store_dwordx2 v[114:115], v[22:23], off offset:1024
	v_pk_mul_f32 v[42:43], v[14:15], v[42:43]
	v_pk_mul_f32 v[44:45], v[16:17], v[44:45]
	v_pk_add_f32 v[22:23], v[52:53], 1.0 op_sel_hi:[1,0]
	v_pk_add_f32 v[24:25], v[50:51], 1.0 op_sel_hi:[1,0]
	s_waitcnt vmcnt(3)
	v_pk_fma_f32 v[44:45], v[22:23], v[44:45], v[76:77]
	v_pk_fma_f32 v[42:43], v[24:25], v[42:43], v[74:75]
	v_mov_b64_e32 v[22:23], v[38:39]
	v_cvt_pk_bf16_f32 v42, v42, v43
	v_cvt_pk_bf16_f32 v43, v44, v45
	global_store_dwordx2 v[114:115], v[42:43], off offset:1536
	v_mov_b64_e32 v[24:25], v[40:41]
	v_mov_b64_e32 v[38:39], v[86:87]
	v_mov_b64_e32 v[40:41], v[88:89]
	s_cbranch_scc0 .LBB0_194
.LBB0_190_u2:
	s_add_i32 s2, s6, 16
	s_cmp_ge_i32 s2, s8
	s_cbranch_scc1 .LBB0_192_u2
	s_add_i32 s23, s11, s6
	s_add_i32 s3, s12, s6
	s_add_i32 s23, s23, 0x8010
	s_cmp_lt_i32 s2, s7
	s_cselect_b32 s2, s3, s23
	s_add_i32 s23, s2, 0xffff8000
	s_ashr_i32 s3, s2, 31
	s_cmp_lt_i32 s2, 0x8000
	s_cselect_b32 s3, s3, 0
	s_cselect_b32 s2, s2, s23
	s_cselect_b32 s23, s37, s41
	s_cselect_b32 s24, s36, s40
	s_lshl_b64 s[2:3], s[2:3], 12
	s_add_u32 s2, s24, s2
	s_addc_u32 s3, s23, s3
	global_load_dwordx4 v[30:33], v98, s[2:3] nt
	global_load_dwordx4 v[34:37], v98, s[2:3] offset:1024 nt
	global_load_dwordx4 v[86:89], v98, s[2:3] offset:2048 nt
	global_load_dwordx4 v[42:45], v98, s[2:3] offset:3072 nt

; #define GAS __attribute__((address_space(1)))
; DI unsigned pk2(float lo, float hi) { f32x2_t v = {lo, hi}; bf16x2_t b = __builtin_convertvector(v, bf16x2_t); return __builtin_bit_cast(unsigned, b); }
; DI void phase_e(const Ctx& C, int nslab, int has_post, int pl, int ps, float pw, int has_pre, int ql, int qs, int nrows,
;                 const GAS float* xsrc, const GAS float* csrc, GAS float* xdst, GAS float* cdst, bool xs16, bool xd16) {
;     ...
;         if (has_pre) {
;             float ss = 0.f;
; #pragma unroll
;             for (int j = 0; j < 4; ++j) ss += (v[j][0] * v[j][0] + v[j][1] * v[j][1]) + (v[j][2] * v[j][2] + v[j][3] * v[j][3]);
;             const float r = rsqrtf(wave_sum(ss) * (1.0f / 1024.0f) + EPS);
; #pragma unroll
;             for (int j = 0; j < 4; ++j) { const f32x4 h = ((v[j] * r) * gpr[j]) * (1.0f + sc[j]) + sh[j];
;                 u32x2 w; w.x = pk2(h[0], h[1]); w.y = pk2(h[2], h[3]); *(GAS u32x2*)(H + (size_t)row * 1024 + 256 * j + 4 * lane) = w; }
.LBB0_424:
	v_pk_mul_f32 v[114:115], v[124:125], v[124:125]
	v_pk_mul_f32 v[116:117], v[122:123], v[122:123]
	v_pk_mul_f32 v[110:111], v[132:133], v[132:133]
	v_pk_mul_f32 v[112:113], v[130:131], v[130:131]
	v_pk_mov_b32 v[118:119], v[116:117], v[114:115] op_sel:[1,0]
	v_mov_b32_e32 v117, v115
	v_pk_add_f32 v[114:115], v[118:119], v[116:117]
	v_pk_mov_b32 v[116:117], v[112:113], v[110:111] op_sel:[1,0]
	v_mov_b32_e32 v113, v111
	v_pk_add_f32 v[110:111], v[116:117], v[112:113]
	v_pk_add_f32 v[114:115], v[114:115], v[114:115] op_sel_hi:[0,1]
	v_pk_add_f32 v[110:111], v[110:111], v[110:111] op_sel_hi:[0,1]
	v_mul_f32_e32 v110, v134, v134
	v_pk_fma_f32 v[112:113], v[134:135], v[134:135], v[110:111] op_sel_hi:[1,1,0]
	v_mul_f32_e32 v110, v136, v136
	v_pk_fma_f32 v[116:117], v[136:137], v[136:137], v[110:111] op_sel_hi:[1,1,0]
	v_mul_f32_e32 v112, v138, v138
	v_mul_f32_e32 v116, v139, v139
	v_mul_f32_e32 v114, v140, v140
	v_mul_f32_e32 v110, v141, v141
	v_pk_add_f32 v[112:113], v[112:113], v[116:117]
	v_pk_add_f32 v[110:111], v[114:115], v[110:111]
	v_pk_add_f32 v[114:115], v[66:67], 1.0 op_sel_hi:[1,0]
	v_pk_add_f32 v[110:111], v[112:113], v[110:111]
	v_pk_add_f32 v[112:113], v[68:69], 1.0 op_sel_hi:[1,0]
	v_add_f32_e32 v110, v110, v111
	s_nop 1
	v_add_f32_dpp v110, v110, v110 quad_perm:[1,0,3,2] row_mask:0xf bank_mask:0xf
	s_nop 1
	v_add_f32_dpp v110, v110, v110 quad_perm:[2,3,0,1] row_mask:0xf bank_mask:0xf
	s_nop 1
	v_add_f32_dpp v110, v110, v110 row_half_mirror row_mask:0xf bank_mask:0xf
	s_nop 1
	v_add_f32_dpp v110, v110, v110 row_mirror row_mask:0xf bank_mask:0xf
	s_nop 1
	v_add_f32_dpp v110, v110, v110 row_bcast:15 row_mask:0xa bank_mask:0xf
	s_nop 1
	v_add_f32_dpp v110, v110, v110 row_bcast:31 row_mask:0xc bank_mask:0xf
	s_nop 0
	v_readlane_b32 s64, v110, 63
	s_nop 1
	v_mov_b32_e32 v110, s64
	s_waitcnt lgkmcnt(0)
	s_add_i32 s0, s43, 8
	s_add_i32 s1, s43, -8
	s_cmp_lt_i32 s1, s27
	s_mov_b32 s43, s0
	v_mov_b64_e32 v[170:171], v[144:145]
	s_waitcnt vmcnt(3)
	v_mov_b64_e32 v[144:145], v[162:163]
	v_fmamk_f32 v110, v110, 0x3a800000, v197
	v_mul_f32_e32 v111, 0x4b800000, v110
	v_cmp_gt_f32_e32 vcc, s47, v110
	s_nop 1
	v_cndmask_b32_e32 v110, v110, v111, vcc
	v_rsq_f32_e32 v116, v110
	v_lshl_add_u64 v[110:111], v[158:159], 0, s[2:3]
	v_mul_f32_e32 v117, 0x45800000, v116
	v_cndmask_b32_e32 v116, v116, v117, vcc
	v_pk_mul_f32 v[118:119], v[124:125], v[116:117] op_sel_hi:[1,0]
	v_pk_mul_f32 v[120:121], v[122:123], v[116:117] op_sel_hi:[1,0]
	v_pk_mul_f32 v[118:119], v[12:13], v[118:119]
	v_pk_mul_f32 v[120:121], v[10:11], v[120:121]
	v_pk_fma_f32 v[112:113], v[112:113], v[118:119], v[72:73]
	v_pk_fma_f32 v[114:115], v[114:115], v[120:121], v[70:71]
	v_pk_mul_f32 v[122:123], v[132:133], v[116:117] op_sel_hi:[1,0]
	v_pk_mul_f32 v[124:125], v[130:131], v[116:117] op_sel_hi:[1,0]
	v_cvt_pk_bf16_f32 v114, v114, v115
	v_cvt_pk_bf16_f32 v115, v112, v113
	v_pk_mul_f32 v[124:125], v[14:15], v[124:125]
	global_store_dwordx2 v[110:111], v[114:115], off
	v_pk_mul_f32 v[112:113], v[16:17], v[122:123]
	v_pk_add_f32 v[114:115], v[76:77], 1.0 op_sel_hi:[1,0]
	v_pk_add_f32 v[118:119], v[74:75], 1.0 op_sel_hi:[1,0]
	v_pk_fma_f32 v[112:113], v[114:115], v[112:113], v[80:81]
	v_pk_fma_f32 v[114:115], v[118:119], v[124:125], v[78:79]
	v_pk_add_f32 v[118:119], v[84:85], 1.0 op_sel_hi:[1,0]
	v_cvt_pk_bf16_f32 v114, v114, v115
	v_cvt_pk_bf16_f32 v115, v112, v113
	global_store_dwordx2 v[110:111], v[114:115], off offset:512
	v_pk_mul_f32 v[112:113], v[136:137], v[116:117] op_sel_hi:[1,0]
	v_pk_mul_f32 v[114:115], v[134:135], v[116:117] op_sel_hi:[1,0]
	v_pk_mul_f32 v[112:113], v[28:29], v[112:113]
	v_pk_mul_f32 v[114:115], v[26:27], v[114:115]
	v_pk_add_f32 v[120:121], v[82:83], 1.0 op_sel_hi:[1,0]
	s_waitcnt vmcnt(3)
	v_pk_fma_f32 v[112:113], v[118:119], v[112:113], v[92:93]
	v_pk_fma_f32 v[114:115], v[120:121], v[114:115], v[90:91]
	v_pk_add_f32 v[118:119], v[62:63], 1.0 op_sel_hi:[1,0]
	v_cvt_pk_bf16_f32 v114, v114, v115
	v_cvt_pk_bf16_f32 v115, v112, v113
	global_store_dwordx2 v[110:111], v[114:115], off offset:1024
	v_pk_mul_f32 v[112:113], v[140:141], v[116:117] op_sel_hi:[1,0]
	v_pk_mul_f32 v[114:115], v[138:139], v[116:117] op_sel_hi:[1,0]
	v_pk_mul_f32 v[112:113], v[32:33], v[112:113]
	v_pk_mul_f32 v[114:115], v[30:31], v[114:115]
	v_pk_add_f32 v[116:117], v[64:65], 1.0 op_sel_hi:[1,0]
	s_waitcnt vmcnt(3)
	v_pk_fma_f32 v[114:115], v[118:119], v[114:115], v[86:87]
	v_pk_fma_f32 v[112:113], v[116:117], v[112:113], v[88:89]
	v_cvt_pk_bf16_f32 v114, v114, v115
	v_cvt_pk_bf16_f32 v115, v112, v113
	global_store_dwordx2 v[110:111], v[114:115], off offset:1536
	v_mov_b64_e32 v[130:131], v[150:151]
	v_mov_b64_e32 v[132:133], v[148:149]
	v_mov_b64_e32 v[134:135], v[146:147]
	v_mov_b64_e32 v[150:151], v[168:169]
	v_mov_b64_e32 v[148:149], v[166:167]
	v_mov_b64_e32 v[146:147], v[164:165]
	s_cbranch_scc0 .LBB0_450

; #define GAS __attribute__((address_space(1)))
; DI unsigned pk2(float lo, float hi) { f32x2_t v = {lo, hi}; bf16x2_t b = __builtin_convertvector(v, bf16x2_t); return __builtin_bit_cast(unsigned, b); }
; DI void phase_e(const Ctx& C, int nslab, int has_post, int pl, int ps, float pw, int has_pre, int ql, int qs, int nrows,
;                 const GAS float* xsrc, const GAS float* csrc, GAS float* xdst, GAS float* cdst, bool xs16, bool xd16) {
;     ...
;     int i = C.wave;
;     if (i < total) E_LOAD(i, vN, yN);
;     if (i + 8 < total) E_LOAD(i + 8, vM, yM);
;     for (; i < total; i += 8) {
;         const int row = E_ROW(i);
;         const bool isx = row < MX; const int mi = isx ? (row >> 13) : 4;
;         f32x4 v[4]; u32x2 yw[4];
; #pragma unroll
;         for (int j = 0; j < 4; ++j) { v[j] = vN[j]; yw[j] = yN[j]; vN[j] = vM[j]; yN[j] = yM[j]; }
;         if (i + 16 < total) E_LOAD(i + 16, vM, yM);
;     ...
;         if (has_pre) {
;             float ss = 0.f;
; #pragma unroll
;             for (int j = 0; j < 4; ++j) ss += (v[j][0] * v[j][0] + v[j][1] * v[j][1]) + (v[j][2] * v[j][2] + v[j][3] * v[j][3]);
;             const float r = rsqrtf(wave_sum(ss) * (1.0f / 1024.0f) + EPS);
; #pragma unroll
;             for (int j = 0; j < 4; ++j) { const f32x4 h = ((v[j] * r) * gpr[j]) * (1.0f + sc[j]) + sh[j];
;                 u32x2 w; w.x = pk2(h[0], h[1]); w.y = pk2(h[2], h[3]); *(GAS u32x2*)(H + (size_t)row * 1024 + 256 * j + 4 * lane) = w; }
.LBB0_424_u0:
	v_pk_mul_f32 v[54:55], v[128:129], v[128:129]
	v_pk_mul_f32 v[56:57], v[126:127], v[126:127]
	v_pk_mul_f32 v[50:51], v[132:133], v[132:133]
	v_pk_mul_f32 v[52:53], v[130:131], v[130:131]
	v_pk_mov_b32 v[58:59], v[56:57], v[54:55] op_sel:[1,0]
	v_mov_b32_e32 v57, v55
	v_pk_add_f32 v[54:55], v[58:59], v[56:57]
	v_pk_mov_b32 v[56:57], v[52:53], v[50:51] op_sel:[1,0]
	v_mov_b32_e32 v53, v51
	v_pk_add_f32 v[50:51], v[56:57], v[52:53]
	v_pk_add_f32 v[54:55], v[54:55], v[54:55] op_sel_hi:[0,1]
	v_pk_add_f32 v[50:51], v[50:51], v[50:51] op_sel_hi:[0,1]
	v_mul_f32_e32 v50, v134, v134
	v_pk_fma_f32 v[52:53], v[134:135], v[134:135], v[50:51] op_sel_hi:[1,1,0]
	v_mul_f32_e32 v50, v136, v136
	v_pk_fma_f32 v[56:57], v[136:137], v[136:137], v[50:51] op_sel_hi:[1,1,0]
	v_mul_f32_e32 v52, v138, v138
	v_mul_f32_e32 v56, v139, v139
	v_mul_f32_e32 v54, v140, v140
	v_mul_f32_e32 v50, v141, v141
	v_pk_add_f32 v[52:53], v[52:53], v[56:57]
	v_pk_add_f32 v[50:51], v[54:55], v[50:51]
	v_pk_add_f32 v[54:55], v[66:67], 1.0 op_sel_hi:[1,0]
	v_pk_add_f32 v[50:51], v[52:53], v[50:51]
	v_pk_add_f32 v[52:53], v[68:69], 1.0 op_sel_hi:[1,0]
	v_add_f32_e32 v50, v50, v51
	s_nop 1
	v_add_f32_dpp v50, v50, v50 quad_perm:[1,0,3,2] row_mask:0xf bank_mask:0xf
	s_nop 1
	v_add_f32_dpp v50, v50, v50 quad_perm:[2,3,0,1] row_mask:0xf bank_mask:0xf
	s_nop 1
	v_add_f32_dpp v50, v50, v50 row_half_mirror row_mask:0xf bank_mask:0xf
	s_nop 1
	v_add_f32_dpp v50, v50, v50 row_mirror row_mask:0xf bank_mask:0xf
	s_nop 1
	v_add_f32_dpp v50, v50, v50 row_bcast:15 row_mask:0xa bank_mask:0xf
	s_nop 1
	v_add_f32_dpp v50, v50, v50 row_bcast:31 row_mask:0xc bank_mask:0xf
	s_nop 0
	v_readlane_b32 s64, v50, 63
	s_nop 1
	v_mov_b32_e32 v50, s64
	s_waitcnt lgkmcnt(0)
	s_add_i32 s0, s43, 8
	s_add_i32 s1, s43, -8
	s_cmp_lt_i32 s1, s27
	s_mov_b32 s43, s0
	v_mov_b64_e32 v[170:171], v[144:145]
	s_waitcnt vmcnt(3)
	v_mov_b64_e32 v[144:145], v[162:163]
	v_fmamk_f32 v50, v50, 0x3a800000, v197
	v_mul_f32_e32 v51, 0x4b800000, v50
	v_cmp_gt_f32_e32 vcc, s47, v50
	s_nop 1
	v_cndmask_b32_e32 v50, v50, v51, vcc
	v_rsq_f32_e32 v56, v50
	v_lshl_add_u64 v[50:51], v[158:159], 0, s[2:3]
	v_mul_f32_e32 v57, 0x45800000, v56
	v_cndmask_b32_e32 v56, v56, v57, vcc
	v_pk_mul_f32 v[58:59], v[128:129], v[56:57] op_sel_hi:[1,0]
	v_pk_mul_f32 v[60:61], v[126:127], v[56:57] op_sel_hi:[1,0]
	v_pk_mul_f32 v[58:59], v[12:13], v[58:59]
	v_pk_mul_f32 v[60:61], v[10:11], v[60:61]
	v_pk_fma_f32 v[52:53], v[52:53], v[58:59], v[72:73]
	v_pk_fma_f32 v[54:55], v[54:55], v[60:61], v[70:71]
	v_pk_mul_f32 v[126:127], v[132:133], v[56:57] op_sel_hi:[1,0]
	v_pk_mul_f32 v[128:129], v[130:131], v[56:57] op_sel_hi:[1,0]
	v_cvt_pk_bf16_f32 v54, v54, v55
	v_cvt_pk_bf16_f32 v55, v52, v53
	v_pk_mul_f32 v[128:129], v[14:15], v[128:129]
	global_store_dwordx2 v[50:51], v[54:55], off
	v_pk_mul_f32 v[52:53], v[16:17], v[126:127]
	v_pk_add_f32 v[54:55], v[76:77], 1.0 op_sel_hi:[1,0]
	v_pk_add_f32 v[58:59], v[74:75], 1.0 op_sel_hi:[1,0]
	v_pk_fma_f32 v[52:53], v[54:55], v[52:53], v[80:81]
	v_pk_fma_f32 v[54:55], v[58:59], v[128:129], v[78:79]
	v_pk_add_f32 v[58:59], v[84:85], 1.0 op_sel_hi:[1,0]
	v_cvt_pk_bf16_f32 v54, v54, v55
	v_cvt_pk_bf16_f32 v55, v52, v53
	global_store_dwordx2 v[50:51], v[54:55], off offset:512
	v_pk_mul_f32 v[52:53], v[136:137], v[56:57] op_sel_hi:[1,0]
	v_pk_mul_f32 v[54:55], v[134:135], v[56:57] op_sel_hi:[1,0]
	v_pk_mul_f32 v[52:53], v[28:29], v[52:53]
	v_pk_mul_f32 v[54:55], v[26:27], v[54:55]
	v_pk_add_f32 v[60:61], v[82:83], 1.0 op_sel_hi:[1,0]
	s_waitcnt vmcnt(3)
	v_pk_fma_f32 v[52:53], v[58:59], v[52:53], v[92:93]
	v_pk_fma_f32 v[54:55], v[60:61], v[54:55], v[90:91]
	v_pk_add_f32 v[58:59], v[62:63], 1.0 op_sel_hi:[1,0]
	v_cvt_pk_bf16_f32 v54, v54, v55
	v_cvt_pk_bf16_f32 v55, v52, v53
	global_store_dwordx2 v[50:51], v[54:55], off offset:1024
	v_pk_mul_f32 v[52:53], v[140:141], v[56:57] op_sel_hi:[1,0]
	v_pk_mul_f32 v[54:55], v[138:139], v[56:57] op_sel_hi:[1,0]
	v_pk_mul_f32 v[52:53], v[32:33], v[52:53]
	v_pk_mul_f32 v[54:55], v[30:31], v[54:55]
	v_pk_add_f32 v[56:57], v[64:65], 1.0 op_sel_hi:[1,0]
	s_waitcnt vmcnt(3)
	v_pk_fma_f32 v[54:55], v[58:59], v[54:55], v[86:87]
	v_pk_fma_f32 v[52:53], v[56:57], v[52:53], v[88:89]
	v_cvt_pk_bf16_f32 v54, v54, v55
	v_cvt_pk_bf16_f32 v55, v52, v53
	global_store_dwordx2 v[50:51], v[54:55], off offset:1536
	v_mov_b64_e32 v[130:131], v[150:151]
	v_mov_b64_e32 v[132:133], v[148:149]
	v_mov_b64_e32 v[134:135], v[146:147]
	v_mov_b64_e32 v[150:151], v[168:169]
	v_mov_b64_e32 v[148:149], v[166:167]
	v_mov_b64_e32 v[146:147], v[164:165]
	s_cbranch_scc0 .LBB0_450
.LBB0_425_u1:
	s_cmp_ge_i32 s43, s27
	s_cbranch_scc1 .LBB0_428_u1
	s_add_i32 s1, s42, s43
	s_add_i32 s0, s39, s43
	s_add_i32 s1, s1, 0x8000
	s_cmp_lt_i32 s43, s26
	s_cselect_b32 s0, s0, s1
	s_add_i32 s2, s0, 0xffff8000
	s_ashr_i32 s1, s0, 31
	v_readlane_b32 s80, v237, 22
	s_cmp_lt_i32 s0, 0x8000
	v_readlane_b32 s81, v237, 23
	v_readlane_b32 s84, v237, 26
	v_readlane_b32 s85, v237, 27
	s_cselect_b32 s3, s1, 0
	s_cselect_b32 s2, s0, s2
	s_mov_b64 s[36:37], s[80:81]
	s_mov_b64 s[40:41], s[84:85]
	s_cselect_b32 s6, s37, s41
	s_cselect_b32 s12, s36, s40
	s_lshl_b64 s[2:3], s[2:3], 12
	s_add_u32 s2, s12, s2
	s_addc_u32 s3, s6, s3
	global_load_dwordx4 v[126:129], v142, s[2:3] nt
	global_load_dwordx4 v[58:61], v142, s[2:3] offset:1024 nt
	global_load_dwordx4 v[54:57], v142, s[2:3] offset:2048 nt
	global_load_dwordx4 v[50:53], v142, s[2:3] offset:3072 nt
	s_cmpk_gt_i32 s0, 0x7fff
	v_mov_b64_e32 v[162:163], v[144:145]
	v_mov_b64_e32 v[164:165], v[146:147]
	v_mov_b64_e32 v[166:167], v[148:149]
	v_mov_b64_e32 v[168:169], v[150:151]
	v_readlane_b32 s82, v237, 24
	v_readlane_b32 s83, v237, 25
	v_readlane_b32 s86, v237, 28
	v_readlane_b32 s87, v237, 29
	v_readlane_b32 s88, v237, 30
	v_readlane_b32 s89, v237, 31
	v_readlane_b32 s90, v237, 32
	v_readlane_b32 s91, v237, 33
	v_readlane_b32 s92, v237, 34
	v_readlane_b32 s93, v237, 35
	v_readlane_b32 s94, v237, 36
	v_readlane_b32 s95, v237, 37
	s_cbranch_scc1 .LBB0_428_u1
	s_lshl_b64 s[0:1], s[0:1], 11
	v_lshl_add_u64 v[136:137], v[152:153], 0, s[0:1]
	global_load_dwordx2 v[162:163], v[136:137], off nt
	global_load_dwordx2 v[164:165], v[136:137], off offset:512 nt
	global_load_dwordx2 v[166:167], v[136:137], off offset:1024 nt
	global_load_dwordx2 v[168:169], v[136:137], off offset:1536 nt

; #define GAS __attribute__((address_space(1)))
; DI unsigned pk2(float lo, float hi) { f32x2_t v = {lo, hi}; bf16x2_t b = __builtin_convertvector(v, bf16x2_t); return __builtin_bit_cast(unsigned, b); }
; DI float bflo(unsigned w) { return __uint_as_float(w << 16); }
; DI float bfhi(unsigned w) { return __uint_as_float(w & 0xffff0000u); }
; DI void phase_e(const Ctx& C, int nslab, int has_post, int pl, int ps, float pw, int has_pre, int ql, int qs, int nrows,
;                 const GAS float* xsrc, const GAS float* csrc, GAS float* xdst, GAS float* cdst, bool xs16, bool xd16) {
;     ...
;         if (has_post) {
;             f32x4 y[4]; float ss = 0.f;
; #pragma unroll
;             for (int j = 0; j < 4; ++j) {
;                 if (isx || nslab == 0) { y[j] = (f32x4){bflo(yw[j].x), bfhi(yw[j].x), bflo(yw[j].y), bfhi(yw[j].y)}; }
;                 else { y[j] = (f32x4){0.f, 0.f, 0.f, 0.f};
;                     for (int s = 0; s < nslab; ++s) { const u32x2 w = *(const GAS u32x2*)(YS + ((size_t)s * MC + (row - MX)) * 1024 + 256 * j + 4 * lane); y[j] += (f32x4){bflo(w.x), bfhi(w.x), bflo(w.y), bfhi(w.y)}; } }
;                 ss += (y[j][0] * y[j][0] + y[j][1] * y[j][1]) + (y[j][2] * y[j][2] + y[j][3] * y[j][3]); }
;             const float r = rsqrtf(wave_sum(ss) * (1.0f / 1024.0f) + EPS);
;             if (isx && xd16) { GAS bf16* d16 = (GAS bf16*)xdst + (size_t)row * 1024;
; #pragma unroll
;                 for (int j = 0; j < 4; ++j) { v[j] += pw * gt[j] * ((y[j] * r) * gpo[j]); u32x2 w; w.x = pk2(v[j][0], v[j][1]); w.y = pk2(v[j][2], v[j][3]); __builtin_nontemporal_store(w, (GAS u32x2*)(d16 + 256 * j + 4 * lane));
;                     v[j] = (f32x4){bflo(w.x), bfhi(w.x), bflo(w.y), bfhi(w.y)}; }
;             } else { GAS float* dst = isx ? xdst + (size_t)row * 1024 : cdst + (size_t)(row - MX) * 1024;
; #pragma unroll
;                 for (int j = 0; j < 4; ++j) { v[j] += pw * gt[j] * ((y[j] * r) * gpo[j]); __builtin_nontemporal_store(v[j], (GAS f32x4*)(dst + 256 * j + 4 * lane)); } }
;         }
.LBB0_446_u1:
	v_mul_f32_e32 v130, v141, v141
	v_mul_f32_e32 v131, v139, v139
	v_fmac_f32_e32 v130, v140, v140
	v_fmac_f32_e32 v131, v138, v138
	v_add_f32_e32 v130, v130, v131
	v_mul_f32_e32 v131, v171, v171
	v_mul_f32_e32 v132, v173, v173
	v_fmac_f32_e32 v131, v170, v170
	v_fmac_f32_e32 v132, v172, v172
	v_add_f32_e32 v131, v131, v132
	v_add_f32_e32 v130, v130, v131
	v_mul_f32_e32 v131, v175, v175
	v_mul_f32_e32 v132, v177, v177
	v_fmac_f32_e32 v131, v174, v174
	v_fmac_f32_e32 v132, v176, v176
	v_add_f32_e32 v131, v131, v132
	v_add_f32_e32 v136, v130, v131
	v_pk_mul_f32 v[130:131], v[180:181], v[180:181]
	v_pk_mul_f32 v[132:133], v[178:179], v[178:179]
	s_and_b64 s[0:1], exec, s[0:1]
	v_pk_mov_b32 v[134:135], v[132:133], v[130:131] op_sel:[1,0]
	v_mov_b32_e32 v133, v131
	v_pk_add_f32 v[130:131], v[134:135], v[132:133]
	s_ashr_i32 s13, s12, 31
	v_add_f32_e32 v130, v130, v131
	v_add_f32_e32 v130, v136, v130
	s_nop 1
	v_add_f32_dpp v130, v130, v130 quad_perm:[1,0,3,2] row_mask:0xf bank_mask:0xf
	s_nop 1
	v_add_f32_dpp v130, v130, v130 quad_perm:[2,3,0,1] row_mask:0xf bank_mask:0xf
	s_nop 1
	v_add_f32_dpp v130, v130, v130 row_half_mirror row_mask:0xf bank_mask:0xf
	s_nop 1
	v_add_f32_dpp v130, v130, v130 row_mirror row_mask:0xf bank_mask:0xf
	s_nop 1
	v_add_f32_dpp v130, v130, v130 row_bcast:15 row_mask:0xa bank_mask:0xf
	s_nop 1
	v_add_f32_dpp v130, v130, v130 row_bcast:31 row_mask:0xc bank_mask:0xf
	s_nop 0
	v_readlane_b32 s64, v130, 63
	s_nop 1
	v_mov_b32_e32 v132, s64
	s_waitcnt lgkmcnt(0)
	s_mov_b64 s[22:23], -1
	s_waitcnt vmcnt(7)
	v_pk_mul_f32 v[188:189], v[98:99], 0.5 op_sel_hi:[1,0]
	s_waitcnt vmcnt(6)
	v_pk_mul_f32 v[186:187], v[102:103], 0.5 op_sel_hi:[1,0]
	s_waitcnt vmcnt(4)
	v_pk_mul_f32 v[184:185], v[106:107], 0.5 op_sel_hi:[1,0]
	v_pk_mul_f32 v[130:131], v[96:97], 0.5 op_sel_hi:[1,0]
	v_fmamk_f32 v132, v132, 0x3a800000, v197
	v_mul_f32_e32 v133, 0x4b800000, v132
	v_cmp_gt_f32_e32 vcc, s47, v132
	s_nop 1
	v_cndmask_b32_e32 v132, v132, v133, vcc
	v_rsq_f32_e32 v134, v132
	v_pk_mul_f32 v[132:133], v[94:95], 0.5 op_sel_hi:[1,0]
	v_mul_f32_e32 v135, 0x45800000, v134
	v_cndmask_b32_e32 v182, v134, v135, vcc
	v_mov_b32_e32 v183, v182
	v_pk_mul_f32 v[134:135], v[138:139], v[182:183] op_sel_hi:[1,0]
	v_pk_mul_f32 v[136:137], v[140:141], v[182:183] op_sel_hi:[1,0]
	v_pk_mul_f32 v[134:135], v[4:5], v[134:135]
	v_pk_mul_f32 v[136:137], v[2:3], v[136:137]
	v_pk_fma_f32 v[36:37], v[130:131], v[134:135], v[36:37]
	v_pk_fma_f32 v[34:35], v[132:133], v[136:137], v[34:35]
	s_mov_b64 vcc, s[0:1]
	s_cbranch_vccz .LBB0_448_u1
	v_mov_b32_e32 v138, v182
	v_mov_b32_e32 v139, v182
	v_pk_mul_f32 v[132:133], v[172:173], v[138:139]
	v_pk_mul_f32 v[134:135], v[170:171], v[182:183]
	v_pk_mul_f32 v[130:131], v[100:101], 0.5 op_sel_hi:[1,0]
	v_pk_mul_f32 v[132:133], v[8:9], v[132:133]
	v_pk_mul_f32 v[134:135], v[6:7], v[134:135]
	v_pk_mul_f32 v[136:137], v[176:177], v[138:139]
	v_pk_mul_f32 v[140:141], v[174:175], v[182:183]
	v_pk_fma_f32 v[132:133], v[130:131], v[132:133], v[40:41]
	v_pk_fma_f32 v[130:131], v[188:189], v[134:135], v[38:39]
	v_pk_mul_f32 v[134:135], v[104:105], 0.5 op_sel_hi:[1,0]
	v_pk_mul_f32 v[136:137], v[20:21], v[136:137]
	v_pk_mul_f32 v[140:141], v[18:19], v[140:141]
	v_pk_mul_f32 v[138:139], v[180:181], v[138:139]
	v_pk_mul_f32 v[200:201], v[178:179], v[182:183]
	s_lshl_b64 s[0:1], s[6:7], 12
	v_pk_fma_f32 v[136:137], v[134:135], v[136:137], v[44:45]
	v_pk_fma_f32 v[134:135], v[186:187], v[140:141], v[42:43]
	v_pk_mul_f32 v[140:141], v[108:109], 0.5 op_sel_hi:[1,0]
	v_pk_mul_f32 v[138:139], v[24:25], v[138:139]
	v_pk_mul_f32 v[200:201], v[22:23], v[200:201]
	v_lshl_add_u64 v[198:199], v[160:161], 0, s[0:1]
	v_pk_fma_f32 v[140:141], v[140:141], v[138:139], v[48:49]
	v_pk_fma_f32 v[138:139], v[184:185], v[200:201], v[46:47]
	global_store_dwordx4 v[198:199], v[34:37], off nt
	global_store_dwordx4 v[198:199], v[130:133], off offset:1024 nt
	global_store_dwordx4 v[198:199], v[134:137], off offset:2048 nt
	global_store_dwordx4 v[198:199], v[138:141], off offset:3072 nt
	s_lshl_b64 s[2:3], s[12:13], 11
	s_mov_b64 s[22:23], 0
.LBB0_448_u1:
	s_andn2_b64 vcc, exec, s[22:23]
	s_cbranch_vccnz .LBB0_424_u1
	s_lshl_b64 s[2:3], s[12:13], 11
	v_mov_b32_e32 v140, v182
	v_mov_b32_e32 v141, v182
	v_lshl_add_u64 v[138:139], v[156:157], 0, s[2:3]
	v_cvt_pk_bf16_f32 v130, v34, v35
	v_cvt_pk_bf16_f32 v131, v36, v37
	v_pk_mul_f32 v[132:133], v[172:173], v[140:141]
	v_pk_mul_f32 v[134:135], v[170:171], v[182:183]
	global_store_dwordx2 v[138:139], v[130:131], off nt
	v_lshlrev_b32_e32 v34, 16, v130
	v_and_b32_e32 v35, 0xffff0000, v130
	v_lshlrev_b32_e32 v36, 16, v131
	v_and_b32_e32 v37, 0xffff0000, v131
	v_pk_mul_f32 v[130:131], v[100:101], 0.5 op_sel_hi:[1,0]
	v_pk_mul_f32 v[132:133], v[8:9], v[132:133]
	v_pk_mul_f32 v[134:135], v[6:7], v[134:135]
	v_pk_fma_f32 v[40:41], v[130:131], v[132:133], v[40:41]
	v_pk_fma_f32 v[38:39], v[188:189], v[134:135], v[38:39]
	v_pk_mul_f32 v[134:135], v[174:175], v[182:183]
	v_cvt_pk_bf16_f32 v38, v38, v39
	v_cvt_pk_bf16_f32 v39, v40, v41
	v_pk_mul_f32 v[40:41], v[176:177], v[140:141]
	global_store_dwordx2 v[138:139], v[38:39], off offset:512 nt
	v_lshlrev_b32_e32 v130, 16, v38
	v_and_b32_e32 v131, 0xffff0000, v38
	v_lshlrev_b32_e32 v132, 16, v39
	v_and_b32_e32 v133, 0xffff0000, v39
	v_pk_mul_f32 v[38:39], v[104:105], 0.5 op_sel_hi:[1,0]
	v_pk_mul_f32 v[40:41], v[20:21], v[40:41]
	v_pk_mul_f32 v[134:135], v[18:19], v[134:135]
	v_pk_fma_f32 v[44:45], v[38:39], v[40:41], v[44:45]
	v_pk_fma_f32 v[42:43], v[186:187], v[134:135], v[42:43]
	v_pk_mul_f32 v[38:39], v[178:179], v[182:183]
	v_cvt_pk_bf16_f32 v42, v42, v43
	v_cvt_pk_bf16_f32 v43, v44, v45
	v_pk_mul_f32 v[44:45], v[180:181], v[140:141]
	global_store_dwordx2 v[138:139], v[42:43], off offset:1024 nt
	v_lshlrev_b32_e32 v134, 16, v42
	v_and_b32_e32 v135, 0xffff0000, v42
	v_lshlrev_b32_e32 v136, 16, v43
	v_and_b32_e32 v137, 0xffff0000, v43
	v_pk_mul_f32 v[42:43], v[108:109], 0.5 op_sel_hi:[1,0]
	v_pk_mul_f32 v[44:45], v[24:25], v[44:45]
	v_pk_mul_f32 v[38:39], v[22:23], v[38:39]
	v_pk_fma_f32 v[48:49], v[42:43], v[44:45], v[48:49]
	v_pk_fma_f32 v[46:47], v[184:185], v[38:39], v[46:47]
	s_nop 0
	v_cvt_pk_bf16_f32 v46, v46, v47
	v_cvt_pk_bf16_f32 v47, v48, v49
	global_store_dwordx2 v[138:139], v[46:47], off offset:1536 nt
	v_lshlrev_b32_e32 v138, 16, v46
	v_and_b32_e32 v139, 0xffff0000, v46
	v_lshlrev_b32_e32 v140, 16, v47
	v_and_b32_e32 v141, 0xffff0000, v47
	s_branch .LBB0_424_u1
; #define GAS __attribute__((address_space(1)))
; DI unsigned pk2(float lo, float hi) { f32x2_t v = {lo, hi}; bf16x2_t b = __builtin_convertvector(v, bf16x2_t); return __builtin_bit_cast(unsigned, b); }
; DI void phase_e(const Ctx& C, int nslab, int has_post, int pl, int ps, float pw, int has_pre, int ql, int qs, int nrows,
;                 const GAS float* xsrc, const GAS float* csrc, GAS float* xdst, GAS float* cdst, bool xs16, bool xd16) {
;     ...
;     int i = C.wave;
;     if (i < total) E_LOAD(i, vN, yN);
;     if (i + 8 < total) E_LOAD(i + 8, vM, yM);
;     for (; i < total; i += 8) {
;         const int row = E_ROW(i);
;         const bool isx = row < MX; const int mi = isx ? (row >> 13) : 4;
;         f32x4 v[4]; u32x2 yw[4];
; #pragma unroll
;         for (int j = 0; j < 4; ++j) { v[j] = vN[j]; yw[j] = yN[j]; vN[j] = vM[j]; yN[j] = yM[j]; }
;         if (i + 16 < total) E_LOAD(i + 16, vM, yM);
;     ...
;         if (has_pre) {
;             float ss = 0.f;
; #pragma unroll
;             for (int j = 0; j < 4; ++j) ss += (v[j][0] * v[j][0] + v[j][1] * v[j][1]) + (v[j][2] * v[j][2] + v[j][3] * v[j][3]);
;             const float r = rsqrtf(wave_sum(ss) * (1.0f / 1024.0f) + EPS);
; #pragma unroll
;             for (int j = 0; j < 4; ++j) { const f32x4 h = ((v[j] * r) * gpr[j]) * (1.0f + sc[j]) + sh[j];
;                 u32x2 w; w.x = pk2(h[0], h[1]); w.y = pk2(h[2], h[3]); *(GAS u32x2*)(H + (size_t)row * 1024 + 256 * j + 4 * lane) = w; }
.LBB0_424_u1:
	v_pk_mul_f32 v[42:43], v[36:37], v[36:37]
	v_pk_mul_f32 v[44:45], v[34:35], v[34:35]
	v_pk_mul_f32 v[46:47], v[132:133], v[132:133]
	v_pk_mul_f32 v[48:49], v[130:131], v[130:131]
	v_pk_mov_b32 v[38:39], v[44:45], v[42:43] op_sel:[1,0]
	v_mov_b32_e32 v45, v43
	v_pk_add_f32 v[42:43], v[38:39], v[44:45]
	v_pk_mov_b32 v[44:45], v[48:49], v[46:47] op_sel:[1,0]
	v_mov_b32_e32 v49, v47
	v_pk_add_f32 v[46:47], v[44:45], v[48:49]
	v_pk_add_f32 v[42:43], v[42:43], v[42:43] op_sel_hi:[0,1]
	v_pk_add_f32 v[46:47], v[46:47], v[46:47] op_sel_hi:[0,1]
	v_mul_f32_e32 v46, v134, v134
	v_pk_fma_f32 v[48:49], v[134:135], v[134:135], v[46:47] op_sel_hi:[1,1,0]
	v_mul_f32_e32 v46, v136, v136
	v_pk_fma_f32 v[44:45], v[136:137], v[136:137], v[46:47] op_sel_hi:[1,1,0]
	v_mul_f32_e32 v48, v138, v138
	v_mul_f32_e32 v44, v139, v139
	v_mul_f32_e32 v42, v140, v140
	v_mul_f32_e32 v46, v141, v141
	v_pk_add_f32 v[48:49], v[48:49], v[44:45]
	v_pk_add_f32 v[46:47], v[42:43], v[46:47]
	v_pk_add_f32 v[42:43], v[66:67], 1.0 op_sel_hi:[1,0]
	v_pk_add_f32 v[46:47], v[48:49], v[46:47]
	v_pk_add_f32 v[48:49], v[68:69], 1.0 op_sel_hi:[1,0]
	v_add_f32_e32 v46, v46, v47
	s_nop 1
	v_add_f32_dpp v46, v46, v46 quad_perm:[1,0,3,2] row_mask:0xf bank_mask:0xf
	s_nop 1
	v_add_f32_dpp v46, v46, v46 quad_perm:[2,3,0,1] row_mask:0xf bank_mask:0xf
	s_nop 1
	v_add_f32_dpp v46, v46, v46 row_half_mirror row_mask:0xf bank_mask:0xf
	s_nop 1
	v_add_f32_dpp v46, v46, v46 row_mirror row_mask:0xf bank_mask:0xf
	s_nop 1
	v_add_f32_dpp v46, v46, v46 row_bcast:15 row_mask:0xa bank_mask:0xf
	s_nop 1
	v_add_f32_dpp v46, v46, v46 row_bcast:31 row_mask:0xc bank_mask:0xf
	s_nop 0
	v_readlane_b32 s64, v46, 63
	s_nop 1
	v_mov_b32_e32 v46, s64
	s_waitcnt lgkmcnt(0)
	s_add_i32 s0, s43, 8
	s_add_i32 s1, s43, -8
	s_cmp_lt_i32 s1, s27
	s_mov_b32 s43, s0
	v_mov_b64_e32 v[170:171], v[144:145]
	s_waitcnt vmcnt(3)
	v_mov_b64_e32 v[144:145], v[162:163]
	v_fmamk_f32 v46, v46, 0x3a800000, v197
	v_mul_f32_e32 v47, 0x4b800000, v46
	v_cmp_gt_f32_e32 vcc, s47, v46
	s_nop 1
	v_cndmask_b32_e32 v46, v46, v47, vcc
	v_rsq_f32_e32 v44, v46
	v_lshl_add_u64 v[46:47], v[158:159], 0, s[2:3]
	v_mul_f32_e32 v45, 0x45800000, v44
	v_cndmask_b32_e32 v44, v44, v45, vcc
	v_pk_mul_f32 v[38:39], v[36:37], v[44:45] op_sel_hi:[1,0]
	v_pk_mul_f32 v[40:41], v[34:35], v[44:45] op_sel_hi:[1,0]
	v_pk_mul_f32 v[38:39], v[12:13], v[38:39]
	v_pk_mul_f32 v[40:41], v[10:11], v[40:41]
	v_pk_fma_f32 v[48:49], v[48:49], v[38:39], v[72:73]
	v_pk_fma_f32 v[42:43], v[42:43], v[40:41], v[70:71]
	v_pk_mul_f32 v[34:35], v[132:133], v[44:45] op_sel_hi:[1,0]
	v_pk_mul_f32 v[36:37], v[130:131], v[44:45] op_sel_hi:[1,0]
	v_cvt_pk_bf16_f32 v42, v42, v43
	v_cvt_pk_bf16_f32 v43, v48, v49
	v_pk_mul_f32 v[36:37], v[14:15], v[36:37]
	global_store_dwordx2 v[46:47], v[42:43], off
	v_pk_mul_f32 v[48:49], v[16:17], v[34:35]
	v_pk_add_f32 v[42:43], v[76:77], 1.0 op_sel_hi:[1,0]
	v_pk_add_f32 v[38:39], v[74:75], 1.0 op_sel_hi:[1,0]
	v_pk_fma_f32 v[48:49], v[42:43], v[48:49], v[80:81]
	v_pk_fma_f32 v[42:43], v[38:39], v[36:37], v[78:79]
	v_pk_add_f32 v[38:39], v[84:85], 1.0 op_sel_hi:[1,0]
	v_cvt_pk_bf16_f32 v42, v42, v43
	v_cvt_pk_bf16_f32 v43, v48, v49
	global_store_dwordx2 v[46:47], v[42:43], off offset:512
	v_pk_mul_f32 v[48:49], v[136:137], v[44:45] op_sel_hi:[1,0]
	v_pk_mul_f32 v[42:43], v[134:135], v[44:45] op_sel_hi:[1,0]
	v_pk_mul_f32 v[48:49], v[28:29], v[48:49]
	v_pk_mul_f32 v[42:43], v[26:27], v[42:43]
	v_pk_add_f32 v[40:41], v[82:83], 1.0 op_sel_hi:[1,0]
	s_waitcnt vmcnt(3)
	v_pk_fma_f32 v[48:49], v[38:39], v[48:49], v[92:93]
	v_pk_fma_f32 v[42:43], v[40:41], v[42:43], v[90:91]
	v_pk_add_f32 v[38:39], v[62:63], 1.0 op_sel_hi:[1,0]
	v_cvt_pk_bf16_f32 v42, v42, v43
	v_cvt_pk_bf16_f32 v43, v48, v49
	global_store_dwordx2 v[46:47], v[42:43], off offset:1024
	v_pk_mul_f32 v[48:49], v[140:141], v[44:45] op_sel_hi:[1,0]
	v_pk_mul_f32 v[42:43], v[138:139], v[44:45] op_sel_hi:[1,0]
	v_pk_mul_f32 v[48:49], v[32:33], v[48:49]
	v_pk_mul_f32 v[42:43], v[30:31], v[42:43]
	v_pk_add_f32 v[44:45], v[64:65], 1.0 op_sel_hi:[1,0]
	s_waitcnt vmcnt(3)
	v_pk_fma_f32 v[42:43], v[38:39], v[42:43], v[86:87]
	v_pk_fma_f32 v[48:49], v[44:45], v[48:49], v[88:89]
	v_cvt_pk_bf16_f32 v42, v42, v43
	v_cvt_pk_bf16_f32 v43, v48, v49
	global_store_dwordx2 v[46:47], v[42:43], off offset:1536
	v_mov_b64_e32 v[130:131], v[150:151]
	v_mov_b64_e32 v[132:133], v[148:149]
	v_mov_b64_e32 v[134:135], v[146:147]
	v_mov_b64_e32 v[150:151], v[168:169]
	v_mov_b64_e32 v[148:149], v[166:167]
	v_mov_b64_e32 v[146:147], v[164:165]
	s_cbranch_scc0 .LBB0_450
.LBB0_425_u2:
	s_cmp_ge_i32 s43, s27
	s_cbranch_scc1 .LBB0_428_u2
	s_add_i32 s1, s42, s43
	s_add_i32 s0, s39, s43
	s_add_i32 s1, s1, 0x8000
	s_cmp_lt_i32 s43, s26
	s_cselect_b32 s0, s0, s1
	s_add_i32 s2, s0, 0xffff8000
	s_ashr_i32 s1, s0, 31
	v_readlane_b32 s80, v237, 22
	s_cmp_lt_i32 s0, 0x8000
	v_readlane_b32 s81, v237, 23
	v_readlane_b32 s84, v237, 26
	v_readlane_b32 s85, v237, 27
	s_cselect_b32 s3, s1, 0
	s_cselect_b32 s2, s0, s2
	s_mov_b64 s[36:37], s[80:81]
	s_mov_b64 s[40:41], s[84:85]
	s_cselect_b32 s6, s37, s41
	s_cselect_b32 s12, s36, s40
	s_lshl_b64 s[2:3], s[2:3], 12
	s_add_u32 s2, s12, s2
	s_addc_u32 s3, s6, s3
	global_load_dwordx4 v[34:37], v142, s[2:3] nt
	global_load_dwordx4 v[38:41], v142, s[2:3] offset:1024 nt
	global_load_dwordx4 v[42:45], v142, s[2:3] offset:2048 nt
	global_load_dwordx4 v[46:49], v142, s[2:3] offset:3072 nt
	s_cmpk_gt_i32 s0, 0x7fff
	v_mov_b64_e32 v[162:163], v[144:145]
	v_mov_b64_e32 v[164:165], v[146:147]
	v_mov_b64_e32 v[166:167], v[148:149]
	v_mov_b64_e32 v[168:169], v[150:151]
	v_readlane_b32 s82, v237, 24
	v_readlane_b32 s83, v237, 25
	v_readlane_b32 s86, v237, 28
	v_readlane_b32 s87, v237, 29
	v_readlane_b32 s88, v237, 30
	v_readlane_b32 s89, v237, 31
	v_readlane_b32 s90, v237, 32
	v_readlane_b32 s91, v237, 33
	v_readlane_b32 s92, v237, 34
	v_readlane_b32 s93, v237, 35
	v_readlane_b32 s94, v237, 36
	v_readlane_b32 s95, v237, 37
	s_cbranch_scc1 .LBB0_428_u2
	s_lshl_b64 s[0:1], s[0:1], 11
	v_lshl_add_u64 v[136:137], v[152:153], 0, s[0:1]
	global_load_dwordx2 v[162:163], v[136:137], off nt
	global_load_dwordx2 v[164:165], v[136:137], off offset:512 nt
	global_load_dwordx2 v[166:167], v[136:137], off offset:1024 nt
	global_load_dwordx2 v[168:169], v[136:137], off offset:1536 nt

; #define GAS __attribute__((address_space(1)))
; DI unsigned pk2(float lo, float hi) { f32x2_t v = {lo, hi}; bf16x2_t b = __builtin_convertvector(v, bf16x2_t); return __builtin_bit_cast(unsigned, b); }
; DI float bflo(unsigned w) { return __uint_as_float(w << 16); }
; DI float bfhi(unsigned w) { return __uint_as_float(w & 0xffff0000u); }
; DI void phase_e(const Ctx& C, int nslab, int has_post, int pl, int ps, float pw, int has_pre, int ql, int qs, int nrows,
;                 const GAS float* xsrc, const GAS float* csrc, GAS float* xdst, GAS float* cdst, bool xs16, bool xd16) {
;     ...
;         if (has_post) {
;             f32x4 y[4]; float ss = 0.f;
; #pragma unroll
;             for (int j = 0; j < 4; ++j) {
;                 if (isx || nslab == 0) { y[j] = (f32x4){bflo(yw[j].x), bfhi(yw[j].x), bflo(yw[j].y), bfhi(yw[j].y)}; }
;                 else { y[j] = (f32x4){0.f, 0.f, 0.f, 0.f};
;                     for (int s = 0; s < nslab; ++s) { const u32x2 w = *(const GAS u32x2*)(YS + ((size_t)s * MC + (row - MX)) * 1024 + 256 * j + 4 * lane); y[j] += (f32x4){bflo(w.x), bfhi(w.x), bflo(w.y), bfhi(w.y)}; } }
;                 ss += (y[j][0] * y[j][0] + y[j][1] * y[j][1]) + (y[j][2] * y[j][2] + y[j][3] * y[j][3]); }
;             const float r = rsqrtf(wave_sum(ss) * (1.0f / 1024.0f) + EPS);
;             if (isx && xd16) { GAS bf16* d16 = (GAS bf16*)xdst + (size_t)row * 1024;
; #pragma unroll
;                 for (int j = 0; j < 4; ++j) { v[j] += pw * gt[j] * ((y[j] * r) * gpo[j]); u32x2 w; w.x = pk2(v[j][0], v[j][1]); w.y = pk2(v[j][2], v[j][3]); __builtin_nontemporal_store(w, (GAS u32x2*)(d16 + 256 * j + 4 * lane));
;                     v[j] = (f32x4){bflo(w.x), bfhi(w.x), bflo(w.y), bfhi(w.y)}; }
;             } else { GAS float* dst = isx ? xdst + (size_t)row * 1024 : cdst + (size_t)(row - MX) * 1024;
; #pragma unroll
;                 for (int j = 0; j < 4; ++j) { v[j] += pw * gt[j] * ((y[j] * r) * gpo[j]); __builtin_nontemporal_store(v[j], (GAS f32x4*)(dst + 256 * j + 4 * lane)); } }
;         }
.LBB0_446_u2:
	v_mul_f32_e32 v130, v141, v141
	v_mul_f32_e32 v131, v139, v139
	v_fmac_f32_e32 v130, v140, v140
	v_fmac_f32_e32 v131, v138, v138
	v_add_f32_e32 v130, v130, v131
	v_mul_f32_e32 v131, v171, v171
	v_mul_f32_e32 v132, v173, v173
	v_fmac_f32_e32 v131, v170, v170
	v_fmac_f32_e32 v132, v172, v172
	v_add_f32_e32 v131, v131, v132
	v_add_f32_e32 v130, v130, v131
	v_mul_f32_e32 v131, v175, v175
	v_mul_f32_e32 v132, v177, v177
	v_fmac_f32_e32 v131, v174, v174
	v_fmac_f32_e32 v132, v176, v176
	v_add_f32_e32 v131, v131, v132
	v_add_f32_e32 v136, v130, v131
	v_pk_mul_f32 v[130:131], v[180:181], v[180:181]
	v_pk_mul_f32 v[132:133], v[178:179], v[178:179]
	s_and_b64 s[0:1], exec, s[0:1]
	v_pk_mov_b32 v[134:135], v[132:133], v[130:131] op_sel:[1,0]
	v_mov_b32_e32 v133, v131
	v_pk_add_f32 v[130:131], v[134:135], v[132:133]
	s_ashr_i32 s13, s12, 31
	v_add_f32_e32 v130, v130, v131
	v_add_f32_e32 v130, v136, v130
	s_nop 1
	v_add_f32_dpp v130, v130, v130 quad_perm:[1,0,3,2] row_mask:0xf bank_mask:0xf
	s_nop 1
	v_add_f32_dpp v130, v130, v130 quad_perm:[2,3,0,1] row_mask:0xf bank_mask:0xf
	s_nop 1
	v_add_f32_dpp v130, v130, v130 row_half_mirror row_mask:0xf bank_mask:0xf
	s_nop 1
	v_add_f32_dpp v130, v130, v130 row_mirror row_mask:0xf bank_mask:0xf
	s_nop 1
	v_add_f32_dpp v130, v130, v130 row_bcast:15 row_mask:0xa bank_mask:0xf
	s_nop 1
	v_add_f32_dpp v130, v130, v130 row_bcast:31 row_mask:0xc bank_mask:0xf
	s_nop 0
	v_readlane_b32 s64, v130, 63
	s_nop 1
	v_mov_b32_e32 v132, s64
	s_waitcnt lgkmcnt(0)
	s_mov_b64 s[22:23], -1
	s_waitcnt vmcnt(7)
	v_pk_mul_f32 v[188:189], v[98:99], 0.5 op_sel_hi:[1,0]
	s_waitcnt vmcnt(6)
	v_pk_mul_f32 v[186:187], v[102:103], 0.5 op_sel_hi:[1,0]
	s_waitcnt vmcnt(4)
	v_pk_mul_f32 v[184:185], v[106:107], 0.5 op_sel_hi:[1,0]
	v_pk_mul_f32 v[130:131], v[96:97], 0.5 op_sel_hi:[1,0]
	v_fmamk_f32 v132, v132, 0x3a800000, v197
	v_mul_f32_e32 v133, 0x4b800000, v132
	v_cmp_gt_f32_e32 vcc, s47, v132
	s_nop 1
	v_cndmask_b32_e32 v132, v132, v133, vcc
	v_rsq_f32_e32 v134, v132
	v_pk_mul_f32 v[132:133], v[94:95], 0.5 op_sel_hi:[1,0]
	v_mul_f32_e32 v135, 0x45800000, v134
	v_cndmask_b32_e32 v182, v134, v135, vcc
	v_mov_b32_e32 v183, v182
	v_pk_mul_f32 v[134:135], v[138:139], v[182:183] op_sel_hi:[1,0]
	v_pk_mul_f32 v[136:137], v[140:141], v[182:183] op_sel_hi:[1,0]
	v_pk_mul_f32 v[134:135], v[4:5], v[134:135]
	v_pk_mul_f32 v[136:137], v[2:3], v[136:137]
	v_pk_fma_f32 v[124:125], v[130:131], v[134:135], v[124:125]
	v_pk_fma_f32 v[122:123], v[132:133], v[136:137], v[122:123]
	s_mov_b64 vcc, s[0:1]
	s_cbranch_vccz .LBB0_448_u2
	v_mov_b32_e32 v138, v182
	v_mov_b32_e32 v139, v182
	v_pk_mul_f32 v[132:133], v[172:173], v[138:139]
	v_pk_mul_f32 v[134:135], v[170:171], v[182:183]
	v_pk_mul_f32 v[130:131], v[100:101], 0.5 op_sel_hi:[1,0]
	v_pk_mul_f32 v[132:133], v[8:9], v[132:133]
	v_pk_mul_f32 v[134:135], v[6:7], v[134:135]
	v_pk_mul_f32 v[136:137], v[176:177], v[138:139]
	v_pk_mul_f32 v[140:141], v[174:175], v[182:183]
	v_pk_fma_f32 v[132:133], v[130:131], v[132:133], v[120:121]
	v_pk_fma_f32 v[130:131], v[188:189], v[134:135], v[118:119]
	v_pk_mul_f32 v[134:135], v[104:105], 0.5 op_sel_hi:[1,0]
	v_pk_mul_f32 v[136:137], v[20:21], v[136:137]
	v_pk_mul_f32 v[140:141], v[18:19], v[140:141]
	v_pk_mul_f32 v[138:139], v[180:181], v[138:139]
	v_pk_mul_f32 v[200:201], v[178:179], v[182:183]
	s_lshl_b64 s[0:1], s[6:7], 12
	v_pk_fma_f32 v[136:137], v[134:135], v[136:137], v[116:117]
	v_pk_fma_f32 v[134:135], v[186:187], v[140:141], v[114:115]
	v_pk_mul_f32 v[140:141], v[108:109], 0.5 op_sel_hi:[1,0]
	v_pk_mul_f32 v[138:139], v[24:25], v[138:139]
	v_pk_mul_f32 v[200:201], v[22:23], v[200:201]
	v_lshl_add_u64 v[198:199], v[160:161], 0, s[0:1]
	v_pk_fma_f32 v[140:141], v[140:141], v[138:139], v[112:113]
	v_pk_fma_f32 v[138:139], v[184:185], v[200:201], v[110:111]
	global_store_dwordx4 v[198:199], v[122:125], off nt
	global_store_dwordx4 v[198:199], v[130:133], off offset:1024 nt
	global_store_dwordx4 v[198:199], v[134:137], off offset:2048 nt
	global_store_dwordx4 v[198:199], v[138:141], off offset:3072 nt
	s_lshl_b64 s[2:3], s[12:13], 11
	s_mov_b64 s[22:23], 0
.LBB0_448_u2:
	s_andn2_b64 vcc, exec, s[22:23]
	s_cbranch_vccnz .LBB0_424
	s_lshl_b64 s[2:3], s[12:13], 11
	v_mov_b32_e32 v140, v182
	v_mov_b32_e32 v141, v182
	v_lshl_add_u64 v[138:139], v[156:157], 0, s[2:3]
	v_cvt_pk_bf16_f32 v130, v122, v123
	v_cvt_pk_bf16_f32 v131, v124, v125
	v_pk_mul_f32 v[132:133], v[172:173], v[140:141]
	v_pk_mul_f32 v[134:135], v[170:171], v[182:183]
	global_store_dwordx2 v[138:139], v[130:131], off nt
	v_lshlrev_b32_e32 v122, 16, v130
	v_and_b32_e32 v123, 0xffff0000, v130
	v_lshlrev_b32_e32 v124, 16, v131
	v_and_b32_e32 v125, 0xffff0000, v131
	v_pk_mul_f32 v[130:131], v[100:101], 0.5 op_sel_hi:[1,0]
	v_pk_mul_f32 v[132:133], v[8:9], v[132:133]
	v_pk_mul_f32 v[134:135], v[6:7], v[134:135]
	v_pk_fma_f32 v[120:121], v[130:131], v[132:133], v[120:121]
	v_pk_fma_f32 v[118:119], v[188:189], v[134:135], v[118:119]
	v_pk_mul_f32 v[134:135], v[174:175], v[182:183]
	v_cvt_pk_bf16_f32 v118, v118, v119
	v_cvt_pk_bf16_f32 v119, v120, v121
	v_pk_mul_f32 v[120:121], v[176:177], v[140:141]
	global_store_dwordx2 v[138:139], v[118:119], off offset:512 nt
	v_lshlrev_b32_e32 v130, 16, v118
	v_and_b32_e32 v131, 0xffff0000, v118
	v_lshlrev_b32_e32 v132, 16, v119
	v_and_b32_e32 v133, 0xffff0000, v119
	v_pk_mul_f32 v[118:119], v[104:105], 0.5 op_sel_hi:[1,0]
	v_pk_mul_f32 v[120:121], v[20:21], v[120:121]
	v_pk_mul_f32 v[134:135], v[18:19], v[134:135]
	v_pk_fma_f32 v[116:117], v[118:119], v[120:121], v[116:117]
	v_pk_fma_f32 v[114:115], v[186:187], v[134:135], v[114:115]
	v_pk_mul_f32 v[118:119], v[178:179], v[182:183]
	v_cvt_pk_bf16_f32 v114, v114, v115
	v_cvt_pk_bf16_f32 v115, v116, v117
	v_pk_mul_f32 v[116:117], v[180:181], v[140:141]
	global_store_dwordx2 v[138:139], v[114:115], off offset:1024 nt
	v_lshlrev_b32_e32 v134, 16, v114
	v_and_b32_e32 v135, 0xffff0000, v114
	v_lshlrev_b32_e32 v136, 16, v115
	v_and_b32_e32 v137, 0xffff0000, v115
	v_pk_mul_f32 v[114:115], v[108:109], 0.5 op_sel_hi:[1,0]
	v_pk_mul_f32 v[116:117], v[24:25], v[116:117]
	v_pk_mul_f32 v[118:119], v[22:23], v[118:119]
	v_pk_fma_f32 v[112:113], v[114:115], v[116:117], v[112:113]
	v_pk_fma_f32 v[110:111], v[184:185], v[118:119], v[110:111]
	s_nop 0
	v_cvt_pk_bf16_f32 v110, v110, v111
	v_cvt_pk_bf16_f32 v111, v112, v113
	global_store_dwordx2 v[138:139], v[110:111], off offset:1536 nt
	v_lshlrev_b32_e32 v138, 16, v110
	v_and_b32_e32 v139, 0xffff0000, v110
	v_lshlrev_b32_e32 v140, 16, v111
	v_and_b32_e32 v141, 0xffff0000, v111
	s_branch .LBB0_424

; #define GAS __attribute__((address_space(1)))
; DI unsigned pk2(float lo, float hi) { f32x2_t v = {lo, hi}; bf16x2_t b = __builtin_convertvector(v, bf16x2_t); return __builtin_bit_cast(unsigned, b); }
; DI void phase_e(const Ctx& C, int nslab, int has_post, int pl, int ps, float pw, int has_pre, int ql, int qs, int nrows,
;                 const GAS float* xsrc, const GAS float* csrc, GAS float* xdst, GAS float* cdst, bool xs16, bool xd16) {
;     ...
;         if (has_pre) {
;             float ss = 0.f;
; #pragma unroll
;             for (int j = 0; j < 4; ++j) ss += (v[j][0] * v[j][0] + v[j][1] * v[j][1]) + (v[j][2] * v[j][2] + v[j][3] * v[j][3]);
;             const float r = rsqrtf(wave_sum(ss) * (1.0f / 1024.0f) + EPS);
; #pragma unroll
;             for (int j = 0; j < 4; ++j) { const f32x4 h = ((v[j] * r) * gpr[j]) * (1.0f + sc[j]) + sh[j];
;                 u32x2 w; w.x = pk2(h[0], h[1]); w.y = pk2(h[2], h[3]); *(GAS u32x2*)(H + (size_t)row * 1024 + 256 * j + 4 * lane) = w; }
.LBB0_945:
	v_pk_mul_f32 v[122:123], v[116:117], v[116:117]
	v_pk_mul_f32 v[124:125], v[114:115], v[114:115]
	v_pk_mul_f32 v[126:127], v[132:133], v[132:133]
	v_pk_mul_f32 v[128:129], v[130:131], v[130:131]
	v_pk_mov_b32 v[118:119], v[124:125], v[122:123] op_sel:[1,0]
	v_mov_b32_e32 v125, v123
	v_pk_add_f32 v[122:123], v[118:119], v[124:125]
	v_pk_mov_b32 v[124:125], v[128:129], v[126:127] op_sel:[1,0]
	v_mov_b32_e32 v129, v127
	v_pk_add_f32 v[126:127], v[124:125], v[128:129]
	v_pk_add_f32 v[122:123], v[122:123], v[122:123] op_sel_hi:[0,1]
	v_pk_add_f32 v[126:127], v[126:127], v[126:127] op_sel_hi:[0,1]
	v_mul_f32_e32 v126, v134, v134
	v_pk_fma_f32 v[128:129], v[134:135], v[134:135], v[126:127] op_sel_hi:[1,1,0]
	v_mul_f32_e32 v126, v136, v136
	v_pk_fma_f32 v[124:125], v[136:137], v[136:137], v[126:127] op_sel_hi:[1,1,0]
	v_mul_f32_e32 v128, v138, v138
	v_mul_f32_e32 v124, v139, v139
	v_mul_f32_e32 v122, v140, v140
	v_mul_f32_e32 v126, v141, v141
	v_pk_add_f32 v[128:129], v[128:129], v[124:125]
	v_pk_add_f32 v[126:127], v[122:123], v[126:127]
	s_waitcnt vmcnt(10)
	v_pk_add_f32 v[122:123], v[66:67], 1.0 op_sel_hi:[1,0]
	v_pk_add_f32 v[126:127], v[128:129], v[126:127]
	v_pk_add_f32 v[128:129], v[68:69], 1.0 op_sel_hi:[1,0]
	v_add_f32_e32 v126, v126, v127
	s_nop 1
	v_add_f32_dpp v126, v126, v126 quad_perm:[1,0,3,2] row_mask:0xf bank_mask:0xf
	s_nop 1
	v_add_f32_dpp v126, v126, v126 quad_perm:[2,3,0,1] row_mask:0xf bank_mask:0xf
	s_nop 1
	v_add_f32_dpp v126, v126, v126 row_half_mirror row_mask:0xf bank_mask:0xf
	s_nop 1
	v_add_f32_dpp v126, v126, v126 row_mirror row_mask:0xf bank_mask:0xf
	s_nop 1
	v_add_f32_dpp v126, v126, v126 row_bcast:15 row_mask:0xa bank_mask:0xf
	s_nop 1
	v_add_f32_dpp v126, v126, v126 row_bcast:31 row_mask:0xc bank_mask:0xf
	s_nop 0
	v_readlane_b32 s64, v126, 63
	s_nop 1
	v_mov_b32_e32 v126, s64
	s_waitcnt lgkmcnt(0)
	s_add_i32 s0, s23, 8
	s_add_i32 s1, s23, -8
	s_cmp_lt_i32 s1, s17
	s_mov_b32 s23, s0
	v_fmamk_f32 v126, v126, 0x3a800000, v192
	v_mul_f32_e32 v127, 0x4b800000, v126
	v_cmp_gt_f32_e32 vcc, s27, v126
	s_nop 1
	v_cndmask_b32_e32 v126, v126, v127, vcc
	v_rsq_f32_e32 v124, v126
	v_lshl_add_u64 v[126:127], v[158:159], 0, s[2:3]
	v_mul_f32_e32 v125, 0x45800000, v124
	v_cndmask_b32_e32 v124, v124, v125, vcc
	v_pk_mul_f32 v[118:119], v[116:117], v[124:125] op_sel_hi:[1,0]
	v_pk_mul_f32 v[120:121], v[114:115], v[124:125] op_sel_hi:[1,0]
	v_pk_mul_f32 v[118:119], v[12:13], v[118:119]
	v_pk_mul_f32 v[120:121], v[10:11], v[120:121]
	s_waitcnt vmcnt(9)
	v_pk_fma_f32 v[128:129], v[128:129], v[118:119], v[72:73]
	v_pk_fma_f32 v[122:123], v[122:123], v[120:121], v[70:71]
	v_pk_mul_f32 v[114:115], v[132:133], v[124:125] op_sel_hi:[1,0]
	v_pk_mul_f32 v[116:117], v[130:131], v[124:125] op_sel_hi:[1,0]
	v_cvt_pk_bf16_f32 v122, v122, v123
	v_cvt_pk_bf16_f32 v123, v128, v129
	v_pk_mul_f32 v[116:117], v[14:15], v[116:117]
	global_store_dwordx2 v[126:127], v[122:123], off
	v_pk_mul_f32 v[128:129], v[16:17], v[114:115]
	s_waitcnt vmcnt(6)
	v_pk_add_f32 v[122:123], v[76:77], 1.0 op_sel_hi:[1,0]
	v_pk_add_f32 v[118:119], v[74:75], 1.0 op_sel_hi:[1,0]
	v_pk_fma_f32 v[128:129], v[122:123], v[128:129], v[84:85]
	v_pk_fma_f32 v[122:123], v[118:119], v[116:117], v[82:83]
	s_waitcnt vmcnt(4)
	v_pk_add_f32 v[118:119], v[88:89], 1.0 op_sel_hi:[1,0]
	v_cvt_pk_bf16_f32 v122, v122, v123
	v_cvt_pk_bf16_f32 v123, v128, v129
	global_store_dwordx2 v[126:127], v[122:123], off offset:512
	v_pk_mul_f32 v[128:129], v[136:137], v[124:125] op_sel_hi:[1,0]
	v_pk_mul_f32 v[122:123], v[134:135], v[124:125] op_sel_hi:[1,0]
	v_pk_mul_f32 v[128:129], v[28:29], v[128:129]
	v_pk_mul_f32 v[122:123], v[26:27], v[122:123]
	v_pk_add_f32 v[120:121], v[86:87], 1.0 op_sel_hi:[1,0]
	s_waitcnt vmcnt(3)
	v_pk_fma_f32 v[128:129], v[118:119], v[128:129], v[96:97]
	v_pk_fma_f32 v[122:123], v[120:121], v[122:123], v[94:95]
	v_pk_add_f32 v[118:119], v[62:63], 1.0 op_sel_hi:[1,0]
	v_cvt_pk_bf16_f32 v122, v122, v123
	v_cvt_pk_bf16_f32 v123, v128, v129
	global_store_dwordx2 v[126:127], v[122:123], off offset:1024
	v_pk_mul_f32 v[128:129], v[140:141], v[124:125] op_sel_hi:[1,0]
	v_pk_mul_f32 v[122:123], v[138:139], v[124:125] op_sel_hi:[1,0]
	v_pk_mul_f32 v[128:129], v[32:33], v[128:129]
	v_pk_mul_f32 v[122:123], v[30:31], v[122:123]
	v_pk_add_f32 v[124:125], v[64:65], 1.0 op_sel_hi:[1,0]
	s_waitcnt vmcnt(3)
	v_pk_fma_f32 v[122:123], v[118:119], v[122:123], v[90:91]
	v_pk_fma_f32 v[128:129], v[124:125], v[128:129], v[92:93]
	v_cvt_pk_bf16_f32 v122, v122, v123
	v_cvt_pk_bf16_f32 v123, v128, v129
	global_store_dwordx2 v[126:127], v[122:123], off offset:1536
	s_mov_b64 vcc, s[98:99]
	s_cbranch_vccz .Leload_skip_0_u2
	s_waitcnt vmcnt(8)
	v_lshlrev_b32_e32 v34, 16, v36
	v_and_b32_e32 v35, 0xffff0000, v36
	v_lshlrev_b32_e32 v36, 16, v37
	v_and_b32_e32 v37, 0xffff0000, v37
	v_lshlrev_b32_e32 v38, 16, v40
	v_and_b32_e32 v39, 0xffff0000, v40
	v_lshlrev_b32_e32 v40, 16, v41
	v_and_b32_e32 v41, 0xffff0000, v41
	v_lshlrev_b32_e32 v42, 16, v44
	v_and_b32_e32 v43, 0xffff0000, v44
	v_lshlrev_b32_e32 v44, 16, v45
	v_and_b32_e32 v45, 0xffff0000, v45
	v_lshlrev_b32_e32 v50, 16, v52
	v_and_b32_e32 v51, 0xffff0000, v52
	v_lshlrev_b32_e32 v52, 16, v53
	v_and_b32_e32 v53, 0xffff0000, v53
.Leload_skip_0_u2:
	v_mov_b64_e32 v[130:131], v[150:151]
	v_mov_b64_e32 v[132:133], v[148:149]
	v_mov_b64_e32 v[134:135], v[146:147]
	v_mov_b64_e32 v[136:137], v[144:145]
	v_mov_b64_e32 v[150:151], v[168:169]
	v_mov_b64_e32 v[148:149], v[166:167]
	v_mov_b64_e32 v[146:147], v[164:165]
	v_mov_b64_e32 v[144:145], v[162:163]
	s_cbranch_scc0 .LBB0_975

; #define GAS __attribute__((address_space(1)))
; DI unsigned pk2(float lo, float hi) { f32x2_t v = {lo, hi}; bf16x2_t b = __builtin_convertvector(v, bf16x2_t); return __builtin_bit_cast(unsigned, b); }
; DI float bflo(unsigned w) { return __uint_as_float(w << 16); }
; DI float bfhi(unsigned w) { return __uint_as_float(w & 0xffff0000u); }
; DI void phase_e(const Ctx& C, int nslab, int has_post, int pl, int ps, float pw, int has_pre, int ql, int qs, int nrows,
;                 const GAS float* xsrc, const GAS float* csrc, GAS float* xdst, GAS float* cdst, bool xs16, bool xd16) {
;     ...
;             if (isx && xd16) { GAS bf16* d16 = (GAS bf16*)xdst + (size_t)row * 1024;
; #pragma unroll
;                 for (int j = 0; j < 4; ++j) { v[j] += pw * gt[j] * ((y[j] * r) * gpo[j]); u32x2 w; w.x = pk2(v[j][0], v[j][1]); w.y = pk2(v[j][2], v[j][3]); __builtin_nontemporal_store(w, (GAS u32x2*)(d16 + 256 * j + 4 * lane));
;                     v[j] = (f32x4){bflo(w.x), bfhi(w.x), bflo(w.y), bfhi(w.y)}; }
.LBB0_973:
	s_andn2_b64 vcc, exec, s[12:13]
	s_cbranch_vccnz .LBB0_945_u0
	s_lshl_b64 s[2:3], s[10:11], 11
	v_lshl_add_u64 v[138:139], v[152:153], 0, s[2:3]
	v_cvt_pk_bf16_f32 v130, v78, v79
	v_cvt_pk_bf16_f32 v131, v80, v81
	v_mov_b32_e32 v140, v184
	v_mov_b32_e32 v141, v184
	global_store_dwordx2 v[138:139], v[130:131], off nt
	v_lshlrev_b32_e32 v78, 16, v130
	v_and_b32_e32 v79, 0xffff0000, v130
	v_lshlrev_b32_e32 v80, 16, v131
	v_and_b32_e32 v81, 0xffff0000, v131
	v_pk_mul_f32 v[130:131], v[172:173], v[140:141]
	v_pk_mul_f32 v[132:133], v[170:171], v[184:185]
	v_pk_mul_f32 v[130:131], v[8:9], v[130:131]
	v_pk_mul_f32 v[132:133], v[6:7], v[132:133]
	s_waitcnt vmcnt(8)
	v_pk_fma_f32 v[60:61], v[104:105], v[130:131], v[60:61]
	v_pk_fma_f32 v[58:59], v[102:103], v[132:133], v[58:59]
	s_nop 0
	v_cvt_pk_bf16_f32 v58, v58, v59
	v_cvt_pk_bf16_f32 v59, v60, v61
	global_store_dwordx2 v[138:139], v[58:59], off offset:512 nt
	v_lshlrev_b32_e32 v130, 16, v58
	v_and_b32_e32 v131, 0xffff0000, v58
	v_lshlrev_b32_e32 v132, 16, v59
	v_and_b32_e32 v133, 0xffff0000, v59
	v_pk_mul_f32 v[58:59], v[178:179], v[140:141]
	v_pk_mul_f32 v[60:61], v[176:177], v[184:185]
	v_pk_mul_f32 v[58:59], v[20:21], v[58:59]
	v_pk_mul_f32 v[60:61], v[18:19], v[60:61]
	s_waitcnt vmcnt(8)
	v_pk_fma_f32 v[56:57], v[108:109], v[58:59], v[56:57]
	v_pk_fma_f32 v[54:55], v[106:107], v[60:61], v[54:55]
	s_nop 0
	v_cvt_pk_bf16_f32 v54, v54, v55
	v_cvt_pk_bf16_f32 v55, v56, v57
	global_store_dwordx2 v[138:139], v[54:55], off offset:1024 nt
	v_lshlrev_b32_e32 v134, 16, v54
	v_and_b32_e32 v135, 0xffff0000, v54
	v_lshlrev_b32_e32 v136, 16, v55
	v_and_b32_e32 v137, 0xffff0000, v55
	v_pk_mul_f32 v[54:55], v[182:183], v[140:141]
	v_pk_mul_f32 v[56:57], v[180:181], v[184:185]
	v_pk_mul_f32 v[54:55], v[24:25], v[54:55]
	v_pk_mul_f32 v[56:57], v[22:23], v[56:57]
	s_waitcnt vmcnt(7)
	v_pk_fma_f32 v[48:49], v[112:113], v[54:55], v[48:49]
	v_pk_fma_f32 v[46:47], v[110:111], v[56:57], v[46:47]
	s_nop 0
	v_cvt_pk_bf16_f32 v46, v46, v47
	v_cvt_pk_bf16_f32 v47, v48, v49
	global_store_dwordx2 v[138:139], v[46:47], off offset:1536 nt
	v_lshlrev_b32_e32 v138, 16, v46
	v_and_b32_e32 v139, 0xffff0000, v46
	v_lshlrev_b32_e32 v140, 16, v47
	v_and_b32_e32 v141, 0xffff0000, v47
	s_branch .LBB0_945_u0
; #define GAS __attribute__((address_space(1)))
; DI unsigned pk2(float lo, float hi) { f32x2_t v = {lo, hi}; bf16x2_t b = __builtin_convertvector(v, bf16x2_t); return __builtin_bit_cast(unsigned, b); }
; DI void phase_e(const Ctx& C, int nslab, int has_post, int pl, int ps, float pw, int has_pre, int ql, int qs, int nrows,
;                 const GAS float* xsrc, const GAS float* csrc, GAS float* xdst, GAS float* cdst, bool xs16, bool xd16) {
;     ...
;         if (has_pre) {
;             float ss = 0.f;
; #pragma unroll
;             for (int j = 0; j < 4; ++j) ss += (v[j][0] * v[j][0] + v[j][1] * v[j][1]) + (v[j][2] * v[j][2] + v[j][3] * v[j][3]);
;             const float r = rsqrtf(wave_sum(ss) * (1.0f / 1024.0f) + EPS);
; #pragma unroll
;             for (int j = 0; j < 4; ++j) { const f32x4 h = ((v[j] * r) * gpr[j]) * (1.0f + sc[j]) + sh[j];
;                 u32x2 w; w.x = pk2(h[0], h[1]); w.y = pk2(h[2], h[3]); *(GAS u32x2*)(H + (size_t)row * 1024 + 256 * j + 4 * lane) = w; }
.LBB0_945_u0:
	v_pk_mul_f32 v[54:55], v[80:81], v[80:81]
	v_pk_mul_f32 v[56:57], v[78:79], v[78:79]
	v_pk_mul_f32 v[46:47], v[132:133], v[132:133]
	v_pk_mul_f32 v[48:49], v[130:131], v[130:131]
	v_pk_mov_b32 v[58:59], v[56:57], v[54:55] op_sel:[1,0]
	v_mov_b32_e32 v57, v55
	v_pk_add_f32 v[54:55], v[58:59], v[56:57]
	v_pk_mov_b32 v[56:57], v[48:49], v[46:47] op_sel:[1,0]
	v_mov_b32_e32 v49, v47
	v_pk_add_f32 v[46:47], v[56:57], v[48:49]
	v_pk_add_f32 v[54:55], v[54:55], v[54:55] op_sel_hi:[0,1]
	v_pk_add_f32 v[46:47], v[46:47], v[46:47] op_sel_hi:[0,1]
	v_mul_f32_e32 v46, v134, v134
	v_pk_fma_f32 v[48:49], v[134:135], v[134:135], v[46:47] op_sel_hi:[1,1,0]
	v_mul_f32_e32 v46, v136, v136
	v_pk_fma_f32 v[56:57], v[136:137], v[136:137], v[46:47] op_sel_hi:[1,1,0]
	v_mul_f32_e32 v48, v138, v138
	v_mul_f32_e32 v56, v139, v139
	v_mul_f32_e32 v54, v140, v140
	v_mul_f32_e32 v46, v141, v141
	v_pk_add_f32 v[48:49], v[48:49], v[56:57]
	v_pk_add_f32 v[46:47], v[54:55], v[46:47]
	s_waitcnt vmcnt(10)
	v_pk_add_f32 v[54:55], v[66:67], 1.0 op_sel_hi:[1,0]
	v_pk_add_f32 v[46:47], v[48:49], v[46:47]
	v_pk_add_f32 v[48:49], v[68:69], 1.0 op_sel_hi:[1,0]
	v_add_f32_e32 v46, v46, v47
	s_nop 1
	v_add_f32_dpp v46, v46, v46 quad_perm:[1,0,3,2] row_mask:0xf bank_mask:0xf
	s_nop 1
	v_add_f32_dpp v46, v46, v46 quad_perm:[2,3,0,1] row_mask:0xf bank_mask:0xf
	s_nop 1
	v_add_f32_dpp v46, v46, v46 row_half_mirror row_mask:0xf bank_mask:0xf
	s_nop 1
	v_add_f32_dpp v46, v46, v46 row_mirror row_mask:0xf bank_mask:0xf
	s_nop 1
	v_add_f32_dpp v46, v46, v46 row_bcast:15 row_mask:0xa bank_mask:0xf
	s_nop 1
	v_add_f32_dpp v46, v46, v46 row_bcast:31 row_mask:0xc bank_mask:0xf
	s_nop 0
	v_readlane_b32 s64, v46, 63
	s_nop 1
	v_mov_b32_e32 v46, s64
	s_waitcnt lgkmcnt(0)
	s_add_i32 s0, s23, 8
	s_add_i32 s1, s23, -8
	s_cmp_lt_i32 s1, s17
	s_mov_b32 s23, s0
	v_fmamk_f32 v46, v46, 0x3a800000, v192
	v_mul_f32_e32 v47, 0x4b800000, v46
	v_cmp_gt_f32_e32 vcc, s27, v46
	s_nop 1
	v_cndmask_b32_e32 v46, v46, v47, vcc
	v_rsq_f32_e32 v56, v46
	v_lshl_add_u64 v[46:47], v[158:159], 0, s[2:3]
	v_mul_f32_e32 v57, 0x45800000, v56
	v_cndmask_b32_e32 v56, v56, v57, vcc
	v_pk_mul_f32 v[58:59], v[80:81], v[56:57] op_sel_hi:[1,0]
	v_pk_mul_f32 v[60:61], v[78:79], v[56:57] op_sel_hi:[1,0]
	v_pk_mul_f32 v[58:59], v[12:13], v[58:59]
	v_pk_mul_f32 v[60:61], v[10:11], v[60:61]
	s_waitcnt vmcnt(9)
	v_pk_fma_f32 v[48:49], v[48:49], v[58:59], v[72:73]
	v_pk_fma_f32 v[54:55], v[54:55], v[60:61], v[70:71]
	v_pk_mul_f32 v[78:79], v[132:133], v[56:57] op_sel_hi:[1,0]
	v_pk_mul_f32 v[80:81], v[130:131], v[56:57] op_sel_hi:[1,0]
	v_cvt_pk_bf16_f32 v54, v54, v55
	v_cvt_pk_bf16_f32 v55, v48, v49
	v_pk_mul_f32 v[80:81], v[14:15], v[80:81]
	global_store_dwordx2 v[46:47], v[54:55], off
	v_pk_mul_f32 v[48:49], v[16:17], v[78:79]
	s_waitcnt vmcnt(6)
	v_pk_add_f32 v[54:55], v[76:77], 1.0 op_sel_hi:[1,0]
	v_pk_add_f32 v[58:59], v[74:75], 1.0 op_sel_hi:[1,0]
	v_pk_fma_f32 v[48:49], v[54:55], v[48:49], v[84:85]
	v_pk_fma_f32 v[54:55], v[58:59], v[80:81], v[82:83]
	s_waitcnt vmcnt(4)
	v_pk_add_f32 v[58:59], v[88:89], 1.0 op_sel_hi:[1,0]
	v_cvt_pk_bf16_f32 v54, v54, v55
	v_cvt_pk_bf16_f32 v55, v48, v49
	global_store_dwordx2 v[46:47], v[54:55], off offset:512
	v_pk_mul_f32 v[48:49], v[136:137], v[56:57] op_sel_hi:[1,0]
	v_pk_mul_f32 v[54:55], v[134:135], v[56:57] op_sel_hi:[1,0]
	v_pk_mul_f32 v[48:49], v[28:29], v[48:49]
	v_pk_mul_f32 v[54:55], v[26:27], v[54:55]
	v_pk_add_f32 v[60:61], v[86:87], 1.0 op_sel_hi:[1,0]
	s_waitcnt vmcnt(3)
	v_pk_fma_f32 v[48:49], v[58:59], v[48:49], v[96:97]
	v_pk_fma_f32 v[54:55], v[60:61], v[54:55], v[94:95]
	v_pk_add_f32 v[58:59], v[62:63], 1.0 op_sel_hi:[1,0]
	v_cvt_pk_bf16_f32 v54, v54, v55
	v_cvt_pk_bf16_f32 v55, v48, v49
	global_store_dwordx2 v[46:47], v[54:55], off offset:1024
	v_pk_mul_f32 v[48:49], v[140:141], v[56:57] op_sel_hi:[1,0]
	v_pk_mul_f32 v[54:55], v[138:139], v[56:57] op_sel_hi:[1,0]
	v_pk_mul_f32 v[48:49], v[32:33], v[48:49]
	v_pk_mul_f32 v[54:55], v[30:31], v[54:55]
	v_pk_add_f32 v[56:57], v[64:65], 1.0 op_sel_hi:[1,0]
	s_waitcnt vmcnt(3)
	v_pk_fma_f32 v[54:55], v[58:59], v[54:55], v[90:91]
	v_pk_fma_f32 v[48:49], v[56:57], v[48:49], v[92:93]
	v_cvt_pk_bf16_f32 v54, v54, v55
	v_cvt_pk_bf16_f32 v55, v48, v49
	global_store_dwordx2 v[46:47], v[54:55], off offset:1536
	s_mov_b64 vcc, s[98:99]
	s_cbranch_vccz .Leload_skip_0
	s_waitcnt vmcnt(8)
	v_lshlrev_b32_e32 v114, 16, v116
	v_and_b32_e32 v115, 0xffff0000, v116
	v_lshlrev_b32_e32 v116, 16, v117
	v_and_b32_e32 v117, 0xffff0000, v117
	v_lshlrev_b32_e32 v118, 16, v120
	v_and_b32_e32 v119, 0xffff0000, v120
	v_lshlrev_b32_e32 v120, 16, v121
	v_and_b32_e32 v121, 0xffff0000, v121
	v_lshlrev_b32_e32 v122, 16, v124
	v_and_b32_e32 v123, 0xffff0000, v124
	v_lshlrev_b32_e32 v124, 16, v125
	v_and_b32_e32 v125, 0xffff0000, v125
	v_lshlrev_b32_e32 v126, 16, v128
	v_and_b32_e32 v127, 0xffff0000, v128
	v_lshlrev_b32_e32 v128, 16, v129
	v_and_b32_e32 v129, 0xffff0000, v129

.LBB0_946_u1:
	s_mov_b64 s[98:99], 0
	s_cmp_ge_i32 s23, s17
	s_cbranch_scc1 .LBB0_953_u1
	s_add_i32 s1, s22, s23
	s_add_i32 s0, s21, s23
	s_add_i32 s1, s1, 0x8000
	s_cmp_lt_i32 s23, s16
	s_cselect_b32 s0, s0, s1
	s_cmp_lt_i32 s0, 0x8000
	s_cselect_b64 s[2:3], -1, 0
	s_cmpk_gt_i32 s0, 0x7fff
	s_mov_b64 s[10:11], -1
	s_cbranch_scc0 .LBB0_949_u1
	s_add_i32 s4, s0, 0xffff8000
	s_lshl_b64 s[10:11], s[4:5], 12
	v_lshl_add_u64 v[46:47], v[160:161], 0, s[10:11]
	global_load_dwordx4 v[78:81], v[46:47], off nt
	global_load_dwordx4 v[58:61], v[46:47], off offset:1024 nt
	global_load_dwordx4 v[54:57], v[46:47], off offset:2048 nt
	s_nop 0
	global_load_dwordx4 v[46:49], v[46:47], off offset:3072 nt
	s_mov_b64 s[10:11], 0
.LBB0_949_u1:
	s_andn2_b64 vcc, exec, s[10:11]
	s_cbranch_vccnz .LBB0_951_u1
	s_ashr_i32 s1, s0, 31
	s_lshl_b64 s[10:11], s[0:1], 11
	s_waitcnt vmcnt(3)
	v_lshl_add_u64 v[78:79], v[152:153], 0, s[10:11]
	global_load_dwordx2 v[80:81], v[78:79], off nt
	global_load_dwordx2 v[60:61], v[78:79], off offset:512 nt
	global_load_dwordx2 v[56:57], v[78:79], off offset:1024 nt
	global_load_dwordx2 v[48:49], v[78:79], off offset:1536 nt
	s_mov_b64 s[98:99], -1

; #define GAS __attribute__((address_space(1)))
; DI unsigned pk2(float lo, float hi) { f32x2_t v = {lo, hi}; bf16x2_t b = __builtin_convertvector(v, bf16x2_t); return __builtin_bit_cast(unsigned, b); }
; DI float bflo(unsigned w) { return __uint_as_float(w << 16); }
; DI float bfhi(unsigned w) { return __uint_as_float(w & 0xffff0000u); }
; DI void phase_e(const Ctx& C, int nslab, int has_post, int pl, int ps, float pw, int has_pre, int ql, int qs, int nrows,
;                 const GAS float* xsrc, const GAS float* csrc, GAS float* xdst, GAS float* cdst, bool xs16, bool xd16) {
;     ...
;         if (has_post) {
;             f32x4 y[4]; float ss = 0.f;
; #pragma unroll
;             for (int j = 0; j < 4; ++j) {
;                 if (isx || nslab == 0) { y[j] = (f32x4){bflo(yw[j].x), bfhi(yw[j].x), bflo(yw[j].y), bfhi(yw[j].y)}; }
;                 else { y[j] = (f32x4){0.f, 0.f, 0.f, 0.f};
;                     for (int s = 0; s < nslab; ++s) { const u32x2 w = *(const GAS u32x2*)(YS + ((size_t)s * MC + (row - MX)) * 1024 + 256 * j + 4 * lane); y[j] += (f32x4){bflo(w.x), bfhi(w.x), bflo(w.y), bfhi(w.y)}; } }
;                 ss += (y[j][0] * y[j][0] + y[j][1] * y[j][1]) + (y[j][2] * y[j][2] + y[j][3] * y[j][3]); }
;             const float r = rsqrtf(wave_sum(ss) * (1.0f / 1024.0f) + EPS);
;             if (isx && xd16) { GAS bf16* d16 = (GAS bf16*)xdst + (size_t)row * 1024;
; #pragma unroll
;                 for (int j = 0; j < 4; ++j) { v[j] += pw * gt[j] * ((y[j] * r) * gpo[j]); u32x2 w; w.x = pk2(v[j][0], v[j][1]); w.y = pk2(v[j][2], v[j][3]); __builtin_nontemporal_store(w, (GAS u32x2*)(d16 + 256 * j + 4 * lane));
;                     v[j] = (f32x4){bflo(w.x), bfhi(w.x), bflo(w.y), bfhi(w.y)}; }
;             } else { GAS float* dst = isx ? xdst + (size_t)row * 1024 : cdst + (size_t)(row - MX) * 1024;
; #pragma unroll
;                 for (int j = 0; j < 4; ++j) { v[j] += pw * gt[j] * ((y[j] * r) * gpo[j]); __builtin_nontemporal_store(v[j], (GAS f32x4*)(dst + 256 * j + 4 * lane)); } }
;         }
.LBB0_971_u1:
	v_mul_f32_e32 v130, v175, v175
	v_mul_f32_e32 v131, v139, v139
	v_fmac_f32_e32 v130, v174, v174
	v_fmac_f32_e32 v131, v138, v138
	v_add_f32_e32 v130, v130, v131
	v_mul_f32_e32 v131, v171, v171
	v_mul_f32_e32 v132, v173, v173
	v_fmac_f32_e32 v131, v170, v170
	v_fmac_f32_e32 v132, v172, v172
	v_add_f32_e32 v131, v131, v132
	v_add_f32_e32 v130, v130, v131
	v_mul_f32_e32 v131, v177, v177
	v_mul_f32_e32 v132, v179, v179
	v_fmac_f32_e32 v131, v176, v176
	v_fmac_f32_e32 v132, v178, v178
	v_add_f32_e32 v131, v131, v132
	v_add_f32_e32 v136, v130, v131
	v_pk_mul_f32 v[130:131], v[182:183], v[182:183]
	v_pk_mul_f32 v[132:133], v[180:181], v[180:181]
	s_and_b64 s[0:1], exec, s[0:1]
	v_pk_mov_b32 v[134:135], v[132:133], v[130:131] op_sel:[1,0]
	v_mov_b32_e32 v133, v131
	v_pk_add_f32 v[130:131], v[134:135], v[132:133]
	s_ashr_i32 s11, s10, 31
	v_add_f32_e32 v130, v130, v131
	v_add_f32_e32 v130, v136, v130
	s_nop 1
	v_add_f32_dpp v130, v130, v130 quad_perm:[1,0,3,2] row_mask:0xf bank_mask:0xf
	s_nop 1
	v_add_f32_dpp v130, v130, v130 quad_perm:[2,3,0,1] row_mask:0xf bank_mask:0xf
	s_nop 1
	v_add_f32_dpp v130, v130, v130 row_half_mirror row_mask:0xf bank_mask:0xf
	s_nop 1
	v_add_f32_dpp v130, v130, v130 row_mirror row_mask:0xf bank_mask:0xf
	s_nop 1
	v_add_f32_dpp v130, v130, v130 row_bcast:15 row_mask:0xa bank_mask:0xf
	s_nop 1
	v_add_f32_dpp v130, v130, v130 row_bcast:31 row_mask:0xc bank_mask:0xf
	s_nop 0
	v_readlane_b32 s64, v130, 63
	s_nop 1
	v_mov_b32_e32 v130, s64
	s_waitcnt lgkmcnt(0)
	s_mov_b64 s[12:13], -1
	v_fmamk_f32 v130, v130, 0x3a800000, v192
	v_mul_f32_e32 v131, 0x4b800000, v130
	v_cmp_gt_f32_e32 vcc, s27, v130
	s_nop 1
	v_cndmask_b32_e32 v130, v130, v131, vcc
	v_rsq_f32_e32 v130, v130
	s_nop 0
	v_mul_f32_e32 v131, 0x45800000, v130
	v_cndmask_b32_e32 v184, v130, v131, vcc
	v_mov_b32_e32 v185, v184
	v_pk_mul_f32 v[130:131], v[138:139], v[184:185] op_sel_hi:[1,0]
	v_pk_mul_f32 v[134:135], v[174:175], v[184:185] op_sel_hi:[1,0]
	v_pk_mul_f32 v[130:131], v[4:5], v[130:131]
	v_pk_mul_f32 v[134:135], v[2:3], v[134:135]
	s_waitcnt vmcnt(11)
	v_pk_fma_f32 v[36:37], v[100:101], v[130:131], v[36:37]
	v_pk_fma_f32 v[34:35], v[98:99], v[134:135], v[34:35]
	s_mov_b64 vcc, s[0:1]
	s_cbranch_vccz .LBB0_973_u1
	v_mov_b32_e32 v138, v184
	v_mov_b32_e32 v139, v184
	v_pk_mul_f32 v[130:131], v[172:173], v[138:139]
	v_pk_mul_f32 v[132:133], v[170:171], v[184:185]
	v_pk_mul_f32 v[130:131], v[8:9], v[130:131]
	v_pk_mul_f32 v[134:135], v[6:7], v[132:133]
	s_waitcnt vmcnt(7)
	v_pk_fma_f32 v[132:133], v[104:105], v[130:131], v[40:41]
	v_pk_fma_f32 v[130:131], v[102:103], v[134:135], v[38:39]
	v_pk_mul_f32 v[134:135], v[178:179], v[138:139]
	v_pk_mul_f32 v[136:137], v[176:177], v[184:185]
	v_pk_mul_f32 v[134:135], v[20:21], v[134:135]
	v_pk_mul_f32 v[140:141], v[18:19], v[136:137]
	s_waitcnt vmcnt(6)
	v_pk_fma_f32 v[136:137], v[108:109], v[134:135], v[44:45]
	v_pk_fma_f32 v[134:135], v[106:107], v[140:141], v[42:43]
	v_pk_mul_f32 v[138:139], v[182:183], v[138:139]
	v_pk_mul_f32 v[140:141], v[180:181], v[184:185]
	s_lshl_b64 s[0:1], s[4:5], 12
	v_pk_mul_f32 v[138:139], v[24:25], v[138:139]
	v_pk_mul_f32 v[194:195], v[22:23], v[140:141]
	v_lshl_add_u64 v[174:175], v[160:161], 0, s[0:1]
	s_waitcnt vmcnt(4)
	v_pk_fma_f32 v[140:141], v[112:113], v[138:139], v[52:53]
	v_pk_fma_f32 v[138:139], v[110:111], v[194:195], v[50:51]
	global_store_dwordx4 v[174:175], v[34:37], off nt
	global_store_dwordx4 v[174:175], v[130:133], off offset:1024 nt
	global_store_dwordx4 v[174:175], v[134:137], off offset:2048 nt
	global_store_dwordx4 v[174:175], v[138:141], off offset:3072 nt
	s_lshl_b64 s[2:3], s[10:11], 11
	s_mov_b64 s[12:13], 0
.LBB0_973_u1:
	s_andn2_b64 vcc, exec, s[12:13]
	s_cbranch_vccnz .LBB0_945_u1
	s_lshl_b64 s[2:3], s[10:11], 11
	v_lshl_add_u64 v[138:139], v[152:153], 0, s[2:3]
	v_cvt_pk_bf16_f32 v130, v34, v35
	v_cvt_pk_bf16_f32 v131, v36, v37
	v_mov_b32_e32 v140, v184
	v_mov_b32_e32 v141, v184
	global_store_dwordx2 v[138:139], v[130:131], off nt
	v_lshlrev_b32_e32 v34, 16, v130
	v_and_b32_e32 v35, 0xffff0000, v130
	v_lshlrev_b32_e32 v36, 16, v131
	v_and_b32_e32 v37, 0xffff0000, v131
	v_pk_mul_f32 v[130:131], v[172:173], v[140:141]
	v_pk_mul_f32 v[132:133], v[170:171], v[184:185]
	v_pk_mul_f32 v[130:131], v[8:9], v[130:131]
	v_pk_mul_f32 v[132:133], v[6:7], v[132:133]
	s_waitcnt vmcnt(8)
	v_pk_fma_f32 v[40:41], v[104:105], v[130:131], v[40:41]
	v_pk_fma_f32 v[38:39], v[102:103], v[132:133], v[38:39]
	s_nop 0
	v_cvt_pk_bf16_f32 v38, v38, v39
	v_cvt_pk_bf16_f32 v39, v40, v41
	global_store_dwordx2 v[138:139], v[38:39], off offset:512 nt
	v_lshlrev_b32_e32 v130, 16, v38
	v_and_b32_e32 v131, 0xffff0000, v38
	v_lshlrev_b32_e32 v132, 16, v39
	v_and_b32_e32 v133, 0xffff0000, v39
	v_pk_mul_f32 v[38:39], v[178:179], v[140:141]
	v_pk_mul_f32 v[40:41], v[176:177], v[184:185]
	v_pk_mul_f32 v[38:39], v[20:21], v[38:39]
	v_pk_mul_f32 v[40:41], v[18:19], v[40:41]
	s_waitcnt vmcnt(8)
	v_pk_fma_f32 v[44:45], v[108:109], v[38:39], v[44:45]
	v_pk_fma_f32 v[42:43], v[106:107], v[40:41], v[42:43]
	s_nop 0
	v_cvt_pk_bf16_f32 v42, v42, v43
	v_cvt_pk_bf16_f32 v43, v44, v45
	global_store_dwordx2 v[138:139], v[42:43], off offset:1024 nt
	v_lshlrev_b32_e32 v134, 16, v42
	v_and_b32_e32 v135, 0xffff0000, v42
	v_lshlrev_b32_e32 v136, 16, v43
	v_and_b32_e32 v137, 0xffff0000, v43
	v_pk_mul_f32 v[42:43], v[182:183], v[140:141]
	v_pk_mul_f32 v[44:45], v[180:181], v[184:185]
	v_pk_mul_f32 v[42:43], v[24:25], v[42:43]
	v_pk_mul_f32 v[44:45], v[22:23], v[44:45]
	s_waitcnt vmcnt(7)
	v_pk_fma_f32 v[52:53], v[112:113], v[42:43], v[52:53]
	v_pk_fma_f32 v[50:51], v[110:111], v[44:45], v[50:51]
	s_nop 0
	v_cvt_pk_bf16_f32 v50, v50, v51
	v_cvt_pk_bf16_f32 v51, v52, v53
	global_store_dwordx2 v[138:139], v[50:51], off offset:1536 nt
	v_lshlrev_b32_e32 v138, 16, v50
	v_and_b32_e32 v139, 0xffff0000, v50
	v_lshlrev_b32_e32 v140, 16, v51
	v_and_b32_e32 v141, 0xffff0000, v51
	s_branch .LBB0_945_u1
; #define GAS __attribute__((address_space(1)))
; DI unsigned pk2(float lo, float hi) { f32x2_t v = {lo, hi}; bf16x2_t b = __builtin_convertvector(v, bf16x2_t); return __builtin_bit_cast(unsigned, b); }
; DI void phase_e(const Ctx& C, int nslab, int has_post, int pl, int ps, float pw, int has_pre, int ql, int qs, int nrows,
;                 const GAS float* xsrc, const GAS float* csrc, GAS float* xdst, GAS float* cdst, bool xs16, bool xd16) {
;     ...
;         if (has_pre) {
;             float ss = 0.f;
; #pragma unroll
;             for (int j = 0; j < 4; ++j) ss += (v[j][0] * v[j][0] + v[j][1] * v[j][1]) + (v[j][2] * v[j][2] + v[j][3] * v[j][3]);
;             const float r = rsqrtf(wave_sum(ss) * (1.0f / 1024.0f) + EPS);
; #pragma unroll
;             for (int j = 0; j < 4; ++j) { const f32x4 h = ((v[j] * r) * gpr[j]) * (1.0f + sc[j]) + sh[j];
;                 u32x2 w; w.x = pk2(h[0], h[1]); w.y = pk2(h[2], h[3]); *(GAS u32x2*)(H + (size_t)row * 1024 + 256 * j + 4 * lane) = w; }
.LBB0_945_u1:
	v_pk_mul_f32 v[42:43], v[36:37], v[36:37]
	v_pk_mul_f32 v[44:45], v[34:35], v[34:35]
	v_pk_mul_f32 v[50:51], v[132:133], v[132:133]
	v_pk_mul_f32 v[52:53], v[130:131], v[130:131]
	v_pk_mov_b32 v[38:39], v[44:45], v[42:43] op_sel:[1,0]
	v_mov_b32_e32 v45, v43
	v_pk_add_f32 v[42:43], v[38:39], v[44:45]
	v_pk_mov_b32 v[44:45], v[52:53], v[50:51] op_sel:[1,0]
	v_mov_b32_e32 v53, v51
	v_pk_add_f32 v[50:51], v[44:45], v[52:53]
	v_pk_add_f32 v[42:43], v[42:43], v[42:43] op_sel_hi:[0,1]
	v_pk_add_f32 v[50:51], v[50:51], v[50:51] op_sel_hi:[0,1]
	v_mul_f32_e32 v50, v134, v134
	v_pk_fma_f32 v[52:53], v[134:135], v[134:135], v[50:51] op_sel_hi:[1,1,0]
	v_mul_f32_e32 v50, v136, v136
	v_pk_fma_f32 v[44:45], v[136:137], v[136:137], v[50:51] op_sel_hi:[1,1,0]
	v_mul_f32_e32 v52, v138, v138
	v_mul_f32_e32 v44, v139, v139
	v_mul_f32_e32 v42, v140, v140
	v_mul_f32_e32 v50, v141, v141
	v_pk_add_f32 v[52:53], v[52:53], v[44:45]
	v_pk_add_f32 v[50:51], v[42:43], v[50:51]
	s_waitcnt vmcnt(10)
	v_pk_add_f32 v[42:43], v[66:67], 1.0 op_sel_hi:[1,0]
	v_pk_add_f32 v[50:51], v[52:53], v[50:51]
	v_pk_add_f32 v[52:53], v[68:69], 1.0 op_sel_hi:[1,0]
	v_add_f32_e32 v50, v50, v51
	s_nop 1
	v_add_f32_dpp v50, v50, v50 quad_perm:[1,0,3,2] row_mask:0xf bank_mask:0xf
	s_nop 1
	v_add_f32_dpp v50, v50, v50 quad_perm:[2,3,0,1] row_mask:0xf bank_mask:0xf
	s_nop 1
	v_add_f32_dpp v50, v50, v50 row_half_mirror row_mask:0xf bank_mask:0xf
	s_nop 1
	v_add_f32_dpp v50, v50, v50 row_mirror row_mask:0xf bank_mask:0xf
	s_nop 1
	v_add_f32_dpp v50, v50, v50 row_bcast:15 row_mask:0xa bank_mask:0xf
	s_nop 1
	v_add_f32_dpp v50, v50, v50 row_bcast:31 row_mask:0xc bank_mask:0xf
	s_nop 0
	v_readlane_b32 s64, v50, 63
	s_nop 1
	v_mov_b32_e32 v50, s64
	s_waitcnt lgkmcnt(0)
	s_add_i32 s0, s23, 8
	s_add_i32 s1, s23, -8
	s_cmp_lt_i32 s1, s17
	s_mov_b32 s23, s0
	v_fmamk_f32 v50, v50, 0x3a800000, v192
	v_mul_f32_e32 v51, 0x4b800000, v50
	v_cmp_gt_f32_e32 vcc, s27, v50
	s_nop 1
	v_cndmask_b32_e32 v50, v50, v51, vcc
	v_rsq_f32_e32 v44, v50
	v_lshl_add_u64 v[50:51], v[158:159], 0, s[2:3]
	v_mul_f32_e32 v45, 0x45800000, v44
	v_cndmask_b32_e32 v44, v44, v45, vcc
	v_pk_mul_f32 v[38:39], v[36:37], v[44:45] op_sel_hi:[1,0]
	v_pk_mul_f32 v[40:41], v[34:35], v[44:45] op_sel_hi:[1,0]
	v_pk_mul_f32 v[38:39], v[12:13], v[38:39]
	v_pk_mul_f32 v[40:41], v[10:11], v[40:41]
	s_waitcnt vmcnt(9)
	v_pk_fma_f32 v[52:53], v[52:53], v[38:39], v[72:73]
	v_pk_fma_f32 v[42:43], v[42:43], v[40:41], v[70:71]
	v_pk_mul_f32 v[34:35], v[132:133], v[44:45] op_sel_hi:[1,0]
	v_pk_mul_f32 v[36:37], v[130:131], v[44:45] op_sel_hi:[1,0]
	v_cvt_pk_bf16_f32 v42, v42, v43
	v_cvt_pk_bf16_f32 v43, v52, v53
	v_pk_mul_f32 v[36:37], v[14:15], v[36:37]
	global_store_dwordx2 v[50:51], v[42:43], off
	v_pk_mul_f32 v[52:53], v[16:17], v[34:35]
	s_waitcnt vmcnt(6)
	v_pk_add_f32 v[42:43], v[76:77], 1.0 op_sel_hi:[1,0]
	v_pk_add_f32 v[38:39], v[74:75], 1.0 op_sel_hi:[1,0]
	v_pk_fma_f32 v[52:53], v[42:43], v[52:53], v[84:85]
	v_pk_fma_f32 v[42:43], v[38:39], v[36:37], v[82:83]
	s_waitcnt vmcnt(4)
	v_pk_add_f32 v[38:39], v[88:89], 1.0 op_sel_hi:[1,0]
	v_cvt_pk_bf16_f32 v42, v42, v43
	v_cvt_pk_bf16_f32 v43, v52, v53
	global_store_dwordx2 v[50:51], v[42:43], off offset:512
	v_pk_mul_f32 v[52:53], v[136:137], v[44:45] op_sel_hi:[1,0]
	v_pk_mul_f32 v[42:43], v[134:135], v[44:45] op_sel_hi:[1,0]
	v_pk_mul_f32 v[52:53], v[28:29], v[52:53]
	v_pk_mul_f32 v[42:43], v[26:27], v[42:43]
	v_pk_add_f32 v[40:41], v[86:87], 1.0 op_sel_hi:[1,0]
	s_waitcnt vmcnt(3)
	v_pk_fma_f32 v[52:53], v[38:39], v[52:53], v[96:97]
	v_pk_fma_f32 v[42:43], v[40:41], v[42:43], v[94:95]
	v_pk_add_f32 v[38:39], v[62:63], 1.0 op_sel_hi:[1,0]
	v_cvt_pk_bf16_f32 v42, v42, v43
	v_cvt_pk_bf16_f32 v43, v52, v53
	global_store_dwordx2 v[50:51], v[42:43], off offset:1024
	v_pk_mul_f32 v[52:53], v[140:141], v[44:45] op_sel_hi:[1,0]
	v_pk_mul_f32 v[42:43], v[138:139], v[44:45] op_sel_hi:[1,0]
	v_pk_mul_f32 v[52:53], v[32:33], v[52:53]
	v_pk_mul_f32 v[42:43], v[30:31], v[42:43]
	v_pk_add_f32 v[44:45], v[64:65], 1.0 op_sel_hi:[1,0]
	s_waitcnt vmcnt(3)
	v_pk_fma_f32 v[42:43], v[38:39], v[42:43], v[90:91]
	v_pk_fma_f32 v[52:53], v[44:45], v[52:53], v[92:93]
	v_cvt_pk_bf16_f32 v42, v42, v43
	v_cvt_pk_bf16_f32 v43, v52, v53
	global_store_dwordx2 v[50:51], v[42:43], off offset:1536
	s_mov_b64 vcc, s[98:99]
	s_cbranch_vccz .Leload_skip_0_u1
	s_waitcnt vmcnt(8)
	v_lshlrev_b32_e32 v78, 16, v80
	v_and_b32_e32 v79, 0xffff0000, v80
	v_lshlrev_b32_e32 v80, 16, v81
	v_and_b32_e32 v81, 0xffff0000, v81
	v_lshlrev_b32_e32 v58, 16, v60
	v_and_b32_e32 v59, 0xffff0000, v60
	v_lshlrev_b32_e32 v60, 16, v61
	v_and_b32_e32 v61, 0xffff0000, v61
	v_lshlrev_b32_e32 v54, 16, v56
	v_and_b32_e32 v55, 0xffff0000, v56
	v_lshlrev_b32_e32 v56, 16, v57
	v_and_b32_e32 v57, 0xffff0000, v57
	v_lshlrev_b32_e32 v46, 16, v48
	v_and_b32_e32 v47, 0xffff0000, v48
	v_lshlrev_b32_e32 v48, 16, v49
	v_and_b32_e32 v49, 0xffff0000, v49

.LBB0_946_u2:
	s_mov_b64 s[98:99], 0
	s_cmp_ge_i32 s23, s17
	s_cbranch_scc1 .LBB0_953_u2
	s_add_i32 s1, s22, s23
	s_add_i32 s0, s21, s23
	s_add_i32 s1, s1, 0x8000
	s_cmp_lt_i32 s23, s16
	s_cselect_b32 s0, s0, s1
	s_cmp_lt_i32 s0, 0x8000
	s_cselect_b64 s[2:3], -1, 0
	s_cmpk_gt_i32 s0, 0x7fff
	s_mov_b64 s[10:11], -1
	s_cbranch_scc0 .LBB0_949_u2
	s_add_i32 s4, s0, 0xffff8000
	s_lshl_b64 s[10:11], s[4:5], 12
	v_lshl_add_u64 v[50:51], v[160:161], 0, s[10:11]
	global_load_dwordx4 v[34:37], v[50:51], off nt
	global_load_dwordx4 v[38:41], v[50:51], off offset:1024 nt
	global_load_dwordx4 v[42:45], v[50:51], off offset:2048 nt
	s_nop 0
	global_load_dwordx4 v[50:53], v[50:51], off offset:3072 nt
	s_mov_b64 s[10:11], 0
.LBB0_949_u2:
	s_andn2_b64 vcc, exec, s[10:11]
	s_cbranch_vccnz .LBB0_951_u2
	s_ashr_i32 s1, s0, 31
	s_lshl_b64 s[10:11], s[0:1], 11
	s_waitcnt vmcnt(3)
	v_lshl_add_u64 v[34:35], v[152:153], 0, s[10:11]
	global_load_dwordx2 v[36:37], v[34:35], off nt
	global_load_dwordx2 v[40:41], v[34:35], off offset:512 nt
	global_load_dwordx2 v[44:45], v[34:35], off offset:1024 nt
	global_load_dwordx2 v[52:53], v[34:35], off offset:1536 nt
	s_mov_b64 s[98:99], -1

; #define GAS __attribute__((address_space(1)))
; DI unsigned pk2(float lo, float hi) { f32x2_t v = {lo, hi}; bf16x2_t b = __builtin_convertvector(v, bf16x2_t); return __builtin_bit_cast(unsigned, b); }
; DI float bflo(unsigned w) { return __uint_as_float(w << 16); }
; DI float bfhi(unsigned w) { return __uint_as_float(w & 0xffff0000u); }
; DI void phase_e(const Ctx& C, int nslab, int has_post, int pl, int ps, float pw, int has_pre, int ql, int qs, int nrows,
;                 const GAS float* xsrc, const GAS float* csrc, GAS float* xdst, GAS float* cdst, bool xs16, bool xd16) {
;     ...
;         if (has_post) {
;             f32x4 y[4]; float ss = 0.f;
; #pragma unroll
;             for (int j = 0; j < 4; ++j) {
;                 if (isx || nslab == 0) { y[j] = (f32x4){bflo(yw[j].x), bfhi(yw[j].x), bflo(yw[j].y), bfhi(yw[j].y)}; }
;                 else { y[j] = (f32x4){0.f, 0.f, 0.f, 0.f};
;                     for (int s = 0; s < nslab; ++s) { const u32x2 w = *(const GAS u32x2*)(YS + ((size_t)s * MC + (row - MX)) * 1024 + 256 * j + 4 * lane); y[j] += (f32x4){bflo(w.x), bfhi(w.x), bflo(w.y), bfhi(w.y)}; } }
;                 ss += (y[j][0] * y[j][0] + y[j][1] * y[j][1]) + (y[j][2] * y[j][2] + y[j][3] * y[j][3]); }
;             const float r = rsqrtf(wave_sum(ss) * (1.0f / 1024.0f) + EPS);
;             if (isx && xd16) { GAS bf16* d16 = (GAS bf16*)xdst + (size_t)row * 1024;
; #pragma unroll
;                 for (int j = 0; j < 4; ++j) { v[j] += pw * gt[j] * ((y[j] * r) * gpo[j]); u32x2 w; w.x = pk2(v[j][0], v[j][1]); w.y = pk2(v[j][2], v[j][3]); __builtin_nontemporal_store(w, (GAS u32x2*)(d16 + 256 * j + 4 * lane));
;                     v[j] = (f32x4){bflo(w.x), bfhi(w.x), bflo(w.y), bfhi(w.y)}; }
;             } else { GAS float* dst = isx ? xdst + (size_t)row * 1024 : cdst + (size_t)(row - MX) * 1024;
; #pragma unroll
;                 for (int j = 0; j < 4; ++j) { v[j] += pw * gt[j] * ((y[j] * r) * gpo[j]); __builtin_nontemporal_store(v[j], (GAS f32x4*)(dst + 256 * j + 4 * lane)); } }
;         }
.LBB0_971_u2:
	v_mul_f32_e32 v130, v175, v175
	v_mul_f32_e32 v131, v139, v139
	v_fmac_f32_e32 v130, v174, v174
	v_fmac_f32_e32 v131, v138, v138
	v_add_f32_e32 v130, v130, v131
	v_mul_f32_e32 v131, v171, v171
	v_mul_f32_e32 v132, v173, v173
	v_fmac_f32_e32 v131, v170, v170
	v_fmac_f32_e32 v132, v172, v172
	v_add_f32_e32 v131, v131, v132
	v_add_f32_e32 v130, v130, v131
	v_mul_f32_e32 v131, v177, v177
	v_mul_f32_e32 v132, v179, v179
	v_fmac_f32_e32 v131, v176, v176
	v_fmac_f32_e32 v132, v178, v178
	v_add_f32_e32 v131, v131, v132
	v_add_f32_e32 v136, v130, v131
	v_pk_mul_f32 v[130:131], v[182:183], v[182:183]
	v_pk_mul_f32 v[132:133], v[180:181], v[180:181]
	s_and_b64 s[0:1], exec, s[0:1]
	v_pk_mov_b32 v[134:135], v[132:133], v[130:131] op_sel:[1,0]
	v_mov_b32_e32 v133, v131
	v_pk_add_f32 v[130:131], v[134:135], v[132:133]
	s_ashr_i32 s11, s10, 31
	v_add_f32_e32 v130, v130, v131
	v_add_f32_e32 v130, v136, v130
	s_nop 1
	v_add_f32_dpp v130, v130, v130 quad_perm:[1,0,3,2] row_mask:0xf bank_mask:0xf
	s_nop 1
	v_add_f32_dpp v130, v130, v130 quad_perm:[2,3,0,1] row_mask:0xf bank_mask:0xf
	s_nop 1
	v_add_f32_dpp v130, v130, v130 row_half_mirror row_mask:0xf bank_mask:0xf
	s_nop 1
	v_add_f32_dpp v130, v130, v130 row_mirror row_mask:0xf bank_mask:0xf
	s_nop 1
	v_add_f32_dpp v130, v130, v130 row_bcast:15 row_mask:0xa bank_mask:0xf
	s_nop 1
	v_add_f32_dpp v130, v130, v130 row_bcast:31 row_mask:0xc bank_mask:0xf
	s_nop 0
	v_readlane_b32 s64, v130, 63
	s_nop 1
	v_mov_b32_e32 v130, s64
	s_waitcnt lgkmcnt(0)
	s_mov_b64 s[12:13], -1
	v_fmamk_f32 v130, v130, 0x3a800000, v192
	v_mul_f32_e32 v131, 0x4b800000, v130
	v_cmp_gt_f32_e32 vcc, s27, v130
	s_nop 1
	v_cndmask_b32_e32 v130, v130, v131, vcc
	v_rsq_f32_e32 v130, v130
	s_nop 0
	v_mul_f32_e32 v131, 0x45800000, v130
	v_cndmask_b32_e32 v184, v130, v131, vcc
	v_mov_b32_e32 v185, v184
	v_pk_mul_f32 v[130:131], v[138:139], v[184:185] op_sel_hi:[1,0]
	v_pk_mul_f32 v[134:135], v[174:175], v[184:185] op_sel_hi:[1,0]
	v_pk_mul_f32 v[130:131], v[4:5], v[130:131]
	v_pk_mul_f32 v[134:135], v[2:3], v[134:135]
	s_waitcnt vmcnt(11)
	v_pk_fma_f32 v[116:117], v[100:101], v[130:131], v[116:117]
	v_pk_fma_f32 v[114:115], v[98:99], v[134:135], v[114:115]
	s_mov_b64 vcc, s[0:1]
	s_cbranch_vccz .LBB0_973_u2
	v_mov_b32_e32 v138, v184
	v_mov_b32_e32 v139, v184
	v_pk_mul_f32 v[130:131], v[172:173], v[138:139]
	v_pk_mul_f32 v[132:133], v[170:171], v[184:185]
	v_pk_mul_f32 v[130:131], v[8:9], v[130:131]
	v_pk_mul_f32 v[134:135], v[6:7], v[132:133]
	s_waitcnt vmcnt(7)
	v_pk_fma_f32 v[132:133], v[104:105], v[130:131], v[120:121]
	v_pk_fma_f32 v[130:131], v[102:103], v[134:135], v[118:119]
	v_pk_mul_f32 v[134:135], v[178:179], v[138:139]
	v_pk_mul_f32 v[136:137], v[176:177], v[184:185]
	v_pk_mul_f32 v[134:135], v[20:21], v[134:135]
	v_pk_mul_f32 v[140:141], v[18:19], v[136:137]
	s_waitcnt vmcnt(6)
	v_pk_fma_f32 v[136:137], v[108:109], v[134:135], v[124:125]
	v_pk_fma_f32 v[134:135], v[106:107], v[140:141], v[122:123]
	v_pk_mul_f32 v[138:139], v[182:183], v[138:139]
	v_pk_mul_f32 v[140:141], v[180:181], v[184:185]
	s_lshl_b64 s[0:1], s[4:5], 12
	v_pk_mul_f32 v[138:139], v[24:25], v[138:139]
	v_pk_mul_f32 v[194:195], v[22:23], v[140:141]
	v_lshl_add_u64 v[174:175], v[160:161], 0, s[0:1]
	s_waitcnt vmcnt(4)
	v_pk_fma_f32 v[140:141], v[112:113], v[138:139], v[128:129]
	v_pk_fma_f32 v[138:139], v[110:111], v[194:195], v[126:127]
	global_store_dwordx4 v[174:175], v[114:117], off nt
	global_store_dwordx4 v[174:175], v[130:133], off offset:1024 nt
	global_store_dwordx4 v[174:175], v[134:137], off offset:2048 nt
	global_store_dwordx4 v[174:175], v[138:141], off offset:3072 nt
	s_lshl_b64 s[2:3], s[10:11], 11
	s_mov_b64 s[12:13], 0
.LBB0_973_u2:
	s_andn2_b64 vcc, exec, s[12:13]
	s_cbranch_vccnz .LBB0_945
	s_lshl_b64 s[2:3], s[10:11], 11
	v_lshl_add_u64 v[138:139], v[152:153], 0, s[2:3]
	v_cvt_pk_bf16_f32 v130, v114, v115
	v_cvt_pk_bf16_f32 v131, v116, v117
	v_mov_b32_e32 v140, v184
	v_mov_b32_e32 v141, v184
	global_store_dwordx2 v[138:139], v[130:131], off nt
	v_lshlrev_b32_e32 v114, 16, v130
	v_and_b32_e32 v115, 0xffff0000, v130
	v_lshlrev_b32_e32 v116, 16, v131
	v_and_b32_e32 v117, 0xffff0000, v131
	v_pk_mul_f32 v[130:131], v[172:173], v[140:141]
	v_pk_mul_f32 v[132:133], v[170:171], v[184:185]
	v_pk_mul_f32 v[130:131], v[8:9], v[130:131]
	v_pk_mul_f32 v[132:133], v[6:7], v[132:133]
	s_waitcnt vmcnt(8)
	v_pk_fma_f32 v[120:121], v[104:105], v[130:131], v[120:121]
	v_pk_fma_f32 v[118:119], v[102:103], v[132:133], v[118:119]
	s_nop 0
	v_cvt_pk_bf16_f32 v118, v118, v119
	v_cvt_pk_bf16_f32 v119, v120, v121
	global_store_dwordx2 v[138:139], v[118:119], off offset:512 nt
	v_lshlrev_b32_e32 v130, 16, v118
	v_and_b32_e32 v131, 0xffff0000, v118
	v_lshlrev_b32_e32 v132, 16, v119
	v_and_b32_e32 v133, 0xffff0000, v119
	v_pk_mul_f32 v[118:119], v[178:179], v[140:141]
	v_pk_mul_f32 v[120:121], v[176:177], v[184:185]
	v_pk_mul_f32 v[118:119], v[20:21], v[118:119]
	v_pk_mul_f32 v[120:121], v[18:19], v[120:121]
	s_waitcnt vmcnt(8)
	v_pk_fma_f32 v[124:125], v[108:109], v[118:119], v[124:125]
	v_pk_fma_f32 v[122:123], v[106:107], v[120:121], v[122:123]
	s_nop 0
	v_cvt_pk_bf16_f32 v122, v122, v123
	v_cvt_pk_bf16_f32 v123, v124, v125
	global_store_dwordx2 v[138:139], v[122:123], off offset:1024 nt
	v_lshlrev_b32_e32 v134, 16, v122
	v_and_b32_e32 v135, 0xffff0000, v122
	v_lshlrev_b32_e32 v136, 16, v123
	v_and_b32_e32 v137, 0xffff0000, v123
	v_pk_mul_f32 v[122:123], v[182:183], v[140:141]
	v_pk_mul_f32 v[124:125], v[180:181], v[184:185]
	v_pk_mul_f32 v[122:123], v[24:25], v[122:123]
	v_pk_mul_f32 v[124:125], v[22:23], v[124:125]
	s_waitcnt vmcnt(7)
	v_pk_fma_f32 v[128:129], v[112:113], v[122:123], v[128:129]
	v_pk_fma_f32 v[126:127], v[110:111], v[124:125], v[126:127]
	s_nop 0
	v_cvt_pk_bf16_f32 v126, v126, v127
	v_cvt_pk_bf16_f32 v127, v128, v129
	global_store_dwordx2 v[138:139], v[126:127], off offset:1536 nt
	v_lshlrev_b32_e32 v138, 16, v126
	v_and_b32_e32 v139, 0xffff0000, v126
	v_lshlrev_b32_e32 v140, 16, v127
	v_and_b32_e32 v141, 0xffff0000, v127
	s_branch .LBB0_945

; #define GAS __attribute__((address_space(1)))
; DI unsigned pk2(float lo, float hi) { f32x2_t v = {lo, hi}; bf16x2_t b = __builtin_convertvector(v, bf16x2_t); return __builtin_bit_cast(unsigned, b); }
; DI void phase_e(const Ctx& C, int nslab, int has_post, int pl, int ps, float pw, int has_pre, int ql, int qs, int nrows,
;                 const GAS float* xsrc, const GAS float* csrc, GAS float* xdst, GAS float* cdst, bool xs16, bool xd16) {
;     ...
;         if (has_pre) {
;             float ss = 0.f;
; #pragma unroll
;             for (int j = 0; j < 4; ++j) ss += (v[j][0] * v[j][0] + v[j][1] * v[j][1]) + (v[j][2] * v[j][2] + v[j][3] * v[j][3]);
;             const float r = rsqrtf(wave_sum(ss) * (1.0f / 1024.0f) + EPS);
; #pragma unroll
;             for (int j = 0; j < 4; ++j) { const f32x4 h = ((v[j] * r) * gpr[j]) * (1.0f + sc[j]) + sh[j];
;                 u32x2 w; w.x = pk2(h[0], h[1]); w.y = pk2(h[2], h[3]); *(GAS u32x2*)(H + (size_t)row * 1024 + 256 * j + 4 * lane) = w; }
.LBB0_1212:
	v_pk_mul_f32 v[122:123], v[116:117], v[116:117]
	v_pk_mul_f32 v[124:125], v[114:115], v[114:115]
	v_pk_mul_f32 v[126:127], v[132:133], v[132:133]
	v_pk_mul_f32 v[128:129], v[130:131], v[130:131]
	v_pk_mov_b32 v[118:119], v[124:125], v[122:123] op_sel:[1,0]
	v_mov_b32_e32 v125, v123
	v_pk_add_f32 v[122:123], v[118:119], v[124:125]
	v_pk_mov_b32 v[124:125], v[128:129], v[126:127] op_sel:[1,0]
	v_mov_b32_e32 v129, v127
	v_pk_add_f32 v[126:127], v[124:125], v[128:129]
	v_pk_add_f32 v[122:123], v[122:123], v[122:123] op_sel_hi:[0,1]
	v_pk_add_f32 v[126:127], v[126:127], v[126:127] op_sel_hi:[0,1]
	v_mul_f32_e32 v126, v134, v134
	v_pk_fma_f32 v[128:129], v[134:135], v[134:135], v[126:127] op_sel_hi:[1,1,0]
	v_mul_f32_e32 v126, v136, v136
	v_pk_fma_f32 v[124:125], v[136:137], v[136:137], v[126:127] op_sel_hi:[1,1,0]
	v_mul_f32_e32 v128, v138, v138
	v_mul_f32_e32 v124, v139, v139
	v_mul_f32_e32 v122, v140, v140
	v_mul_f32_e32 v126, v141, v141
	v_pk_add_f32 v[128:129], v[128:129], v[124:125]
	v_pk_add_f32 v[126:127], v[122:123], v[126:127]
	v_pk_add_f32 v[122:123], v[66:67], 1.0 op_sel_hi:[1,0]
	v_pk_add_f32 v[126:127], v[128:129], v[126:127]
	v_pk_add_f32 v[128:129], v[68:69], 1.0 op_sel_hi:[1,0]
	v_add_f32_e32 v126, v126, v127
	s_nop 1
	v_add_f32_dpp v126, v126, v126 quad_perm:[1,0,3,2] row_mask:0xf bank_mask:0xf
	s_nop 1
	v_add_f32_dpp v126, v126, v126 quad_perm:[2,3,0,1] row_mask:0xf bank_mask:0xf
	s_nop 1
	v_add_f32_dpp v126, v126, v126 row_half_mirror row_mask:0xf bank_mask:0xf
	s_nop 1
	v_add_f32_dpp v126, v126, v126 row_mirror row_mask:0xf bank_mask:0xf
	s_nop 1
	v_add_f32_dpp v126, v126, v126 row_bcast:15 row_mask:0xa bank_mask:0xf
	s_nop 1
	v_add_f32_dpp v126, v126, v126 row_bcast:31 row_mask:0xc bank_mask:0xf
	s_nop 0
	v_readlane_b32 s64, v126, 63
	s_nop 1
	v_mov_b32_e32 v126, s64
	s_waitcnt lgkmcnt(0)
	s_add_i32 s0, s22, 8
	s_add_i32 s1, s22, -8
	s_cmp_lt_i32 s1, s17
	s_mov_b32 s22, s0
	v_mov_b64_e32 v[170:171], v[144:145]
	s_waitcnt vmcnt(3)
	v_mov_b64_e32 v[144:145], v[162:163]
	v_fmamk_f32 v126, v126, 0x3a800000, v196
	v_mul_f32_e32 v127, 0x4b800000, v126
	v_cmp_gt_f32_e32 vcc, s25, v126
	s_nop 1
	v_cndmask_b32_e32 v126, v126, v127, vcc
	v_rsq_f32_e32 v124, v126
	v_lshl_add_u64 v[126:127], v[158:159], 0, s[2:3]
	v_mul_f32_e32 v125, 0x45800000, v124
	v_cndmask_b32_e32 v124, v124, v125, vcc
	v_pk_mul_f32 v[118:119], v[116:117], v[124:125] op_sel_hi:[1,0]
	v_pk_mul_f32 v[120:121], v[114:115], v[124:125] op_sel_hi:[1,0]
	v_pk_mul_f32 v[118:119], v[12:13], v[118:119]
	v_pk_mul_f32 v[120:121], v[10:11], v[120:121]
	v_pk_fma_f32 v[128:129], v[128:129], v[118:119], v[72:73]
	v_pk_fma_f32 v[122:123], v[122:123], v[120:121], v[70:71]
	v_pk_mul_f32 v[114:115], v[132:133], v[124:125] op_sel_hi:[1,0]
	v_pk_mul_f32 v[116:117], v[130:131], v[124:125] op_sel_hi:[1,0]
	v_cvt_pk_bf16_f32 v122, v122, v123
	v_cvt_pk_bf16_f32 v123, v128, v129
	v_pk_mul_f32 v[116:117], v[14:15], v[116:117]
	global_store_dwordx2 v[126:127], v[122:123], off
	v_pk_mul_f32 v[128:129], v[16:17], v[114:115]
	v_pk_add_f32 v[122:123], v[76:77], 1.0 op_sel_hi:[1,0]
	v_pk_add_f32 v[118:119], v[74:75], 1.0 op_sel_hi:[1,0]
	v_pk_fma_f32 v[128:129], v[122:123], v[128:129], v[80:81]
	v_pk_fma_f32 v[122:123], v[118:119], v[116:117], v[78:79]
	v_pk_add_f32 v[118:119], v[84:85], 1.0 op_sel_hi:[1,0]
	v_cvt_pk_bf16_f32 v122, v122, v123
	v_cvt_pk_bf16_f32 v123, v128, v129
	global_store_dwordx2 v[126:127], v[122:123], off offset:512
	v_pk_mul_f32 v[128:129], v[136:137], v[124:125] op_sel_hi:[1,0]
	v_pk_mul_f32 v[122:123], v[134:135], v[124:125] op_sel_hi:[1,0]
	v_pk_mul_f32 v[128:129], v[28:29], v[128:129]
	v_pk_mul_f32 v[122:123], v[26:27], v[122:123]
	v_pk_add_f32 v[120:121], v[82:83], 1.0 op_sel_hi:[1,0]
	s_waitcnt vmcnt(3)
	v_pk_fma_f32 v[128:129], v[118:119], v[128:129], v[92:93]
	v_pk_fma_f32 v[122:123], v[120:121], v[122:123], v[90:91]
	v_pk_add_f32 v[118:119], v[62:63], 1.0 op_sel_hi:[1,0]
	v_cvt_pk_bf16_f32 v122, v122, v123
	v_cvt_pk_bf16_f32 v123, v128, v129
	global_store_dwordx2 v[126:127], v[122:123], off offset:1024
	v_pk_mul_f32 v[128:129], v[140:141], v[124:125] op_sel_hi:[1,0]
	v_pk_mul_f32 v[122:123], v[138:139], v[124:125] op_sel_hi:[1,0]
	v_pk_mul_f32 v[128:129], v[32:33], v[128:129]
	v_pk_mul_f32 v[122:123], v[30:31], v[122:123]
	v_pk_add_f32 v[124:125], v[64:65], 1.0 op_sel_hi:[1,0]
	s_waitcnt vmcnt(3)
	v_pk_fma_f32 v[122:123], v[118:119], v[122:123], v[86:87]
	v_pk_fma_f32 v[128:129], v[124:125], v[128:129], v[88:89]
	v_cvt_pk_bf16_f32 v122, v122, v123
	v_cvt_pk_bf16_f32 v123, v128, v129
	global_store_dwordx2 v[126:127], v[122:123], off offset:1536
	s_mov_b64 vcc, s[98:99]
	s_cbranch_vccz .Leload_skip_1_u2
	s_waitcnt vmcnt(8)
	v_lshlrev_b32_e32 v34, 16, v36
	v_and_b32_e32 v35, 0xffff0000, v36
	v_lshlrev_b32_e32 v36, 16, v37
	v_and_b32_e32 v37, 0xffff0000, v37
	v_lshlrev_b32_e32 v38, 16, v40
	v_and_b32_e32 v39, 0xffff0000, v40
	v_lshlrev_b32_e32 v40, 16, v41
	v_and_b32_e32 v41, 0xffff0000, v41
	v_lshlrev_b32_e32 v42, 16, v44
	v_and_b32_e32 v43, 0xffff0000, v44
	v_lshlrev_b32_e32 v44, 16, v45
	v_and_b32_e32 v45, 0xffff0000, v45
	v_lshlrev_b32_e32 v50, 16, v52
	v_and_b32_e32 v51, 0xffff0000, v52
	v_lshlrev_b32_e32 v52, 16, v53
	v_and_b32_e32 v53, 0xffff0000, v53
.Leload_skip_1_u2:
	v_mov_b64_e32 v[130:131], v[150:151]
	v_mov_b64_e32 v[132:133], v[148:149]
	v_mov_b64_e32 v[134:135], v[146:147]
	v_mov_b64_e32 v[150:151], v[168:169]
	v_mov_b64_e32 v[148:149], v[166:167]
	v_mov_b64_e32 v[146:147], v[164:165]
	s_cbranch_scc0 .LBB0_1242

; #define GAS __attribute__((address_space(1)))
; DI unsigned pk2(float lo, float hi) { f32x2_t v = {lo, hi}; bf16x2_t b = __builtin_convertvector(v, bf16x2_t); return __builtin_bit_cast(unsigned, b); }
; DI float bflo(unsigned w) { return __uint_as_float(w << 16); }
; DI float bfhi(unsigned w) { return __uint_as_float(w & 0xffff0000u); }
; DI void phase_e(const Ctx& C, int nslab, int has_post, int pl, int ps, float pw, int has_pre, int ql, int qs, int nrows,
;                 const GAS float* xsrc, const GAS float* csrc, GAS float* xdst, GAS float* cdst, bool xs16, bool xd16) {
;     ...
;             if (isx && xd16) { GAS bf16* d16 = (GAS bf16*)xdst + (size_t)row * 1024;
; #pragma unroll
;                 for (int j = 0; j < 4; ++j) { v[j] += pw * gt[j] * ((y[j] * r) * gpo[j]); u32x2 w; w.x = pk2(v[j][0], v[j][1]); w.y = pk2(v[j][2], v[j][3]); __builtin_nontemporal_store(w, (GAS u32x2*)(d16 + 256 * j + 4 * lane));
;                     v[j] = (f32x4){bflo(w.x), bfhi(w.x), bflo(w.y), bfhi(w.y)}; }
.LBB0_1240:
	s_andn2_b64 vcc, exec, s[12:13]
	s_cbranch_vccnz .LBB0_1212_u0
	s_lshl_b64 s[2:3], s[10:11], 11
	v_mov_b32_e32 v140, v182
	v_mov_b32_e32 v141, v182
	v_lshl_add_u64 v[138:139], v[152:153], 0, s[2:3]
	v_cvt_pk_bf16_f32 v130, v98, v99
	v_cvt_pk_bf16_f32 v131, v100, v101
	v_pk_mul_f32 v[132:133], v[172:173], v[140:141]
	v_pk_mul_f32 v[134:135], v[170:171], v[182:183]
	global_store_dwordx2 v[138:139], v[130:131], off nt
	v_lshlrev_b32_e32 v98, 16, v130
	v_and_b32_e32 v99, 0xffff0000, v130
	v_lshlrev_b32_e32 v100, 16, v131
	v_and_b32_e32 v101, 0xffff0000, v131
	v_pk_mul_f32 v[130:131], v[104:105], 0.5 op_sel_hi:[1,0]
	v_pk_mul_f32 v[132:133], v[8:9], v[132:133]
	v_pk_mul_f32 v[134:135], v[6:7], v[134:135]
	v_pk_fma_f32 v[60:61], v[130:131], v[132:133], v[60:61]
	v_pk_fma_f32 v[58:59], v[188:189], v[134:135], v[58:59]
	v_pk_mul_f32 v[134:135], v[174:175], v[182:183]
	v_cvt_pk_bf16_f32 v58, v58, v59
	v_cvt_pk_bf16_f32 v59, v60, v61
	v_pk_mul_f32 v[60:61], v[176:177], v[140:141]
	global_store_dwordx2 v[138:139], v[58:59], off offset:512 nt
	v_lshlrev_b32_e32 v130, 16, v58
	v_and_b32_e32 v131, 0xffff0000, v58
	v_lshlrev_b32_e32 v132, 16, v59
	v_and_b32_e32 v133, 0xffff0000, v59
	v_pk_mul_f32 v[58:59], v[108:109], 0.5 op_sel_hi:[1,0]
	v_pk_mul_f32 v[60:61], v[20:21], v[60:61]
	v_pk_mul_f32 v[134:135], v[18:19], v[134:135]
	v_pk_fma_f32 v[56:57], v[58:59], v[60:61], v[56:57]
	v_pk_fma_f32 v[54:55], v[186:187], v[134:135], v[54:55]
	v_pk_mul_f32 v[58:59], v[178:179], v[182:183]
	v_cvt_pk_bf16_f32 v54, v54, v55
	v_cvt_pk_bf16_f32 v55, v56, v57
	v_pk_mul_f32 v[56:57], v[180:181], v[140:141]
	global_store_dwordx2 v[138:139], v[54:55], off offset:1024 nt
	v_lshlrev_b32_e32 v134, 16, v54
	v_and_b32_e32 v135, 0xffff0000, v54
	v_lshlrev_b32_e32 v136, 16, v55
	v_and_b32_e32 v137, 0xffff0000, v55
	v_pk_mul_f32 v[54:55], v[112:113], 0.5 op_sel_hi:[1,0]
	v_pk_mul_f32 v[56:57], v[24:25], v[56:57]
	v_pk_mul_f32 v[58:59], v[22:23], v[58:59]
	v_pk_fma_f32 v[48:49], v[54:55], v[56:57], v[48:49]
	v_pk_fma_f32 v[46:47], v[184:185], v[58:59], v[46:47]
	s_nop 0
	v_cvt_pk_bf16_f32 v46, v46, v47
	v_cvt_pk_bf16_f32 v47, v48, v49
	global_store_dwordx2 v[138:139], v[46:47], off offset:1536 nt
	v_lshlrev_b32_e32 v138, 16, v46
	v_and_b32_e32 v139, 0xffff0000, v46
	v_lshlrev_b32_e32 v140, 16, v47
	v_and_b32_e32 v141, 0xffff0000, v47
	s_branch .LBB0_1212_u0
; #define GAS __attribute__((address_space(1)))
; DI unsigned pk2(float lo, float hi) { f32x2_t v = {lo, hi}; bf16x2_t b = __builtin_convertvector(v, bf16x2_t); return __builtin_bit_cast(unsigned, b); }
; DI void phase_e(const Ctx& C, int nslab, int has_post, int pl, int ps, float pw, int has_pre, int ql, int qs, int nrows,
;                 const GAS float* xsrc, const GAS float* csrc, GAS float* xdst, GAS float* cdst, bool xs16, bool xd16) {
;     ...
;         if (has_pre) {
;             float ss = 0.f;
; #pragma unroll
;             for (int j = 0; j < 4; ++j) ss += (v[j][0] * v[j][0] + v[j][1] * v[j][1]) + (v[j][2] * v[j][2] + v[j][3] * v[j][3]);
;             const float r = rsqrtf(wave_sum(ss) * (1.0f / 1024.0f) + EPS);
; #pragma unroll
;             for (int j = 0; j < 4; ++j) { const f32x4 h = ((v[j] * r) * gpr[j]) * (1.0f + sc[j]) + sh[j];
;                 u32x2 w; w.x = pk2(h[0], h[1]); w.y = pk2(h[2], h[3]); *(GAS u32x2*)(H + (size_t)row * 1024 + 256 * j + 4 * lane) = w; }
.LBB0_1212_u0:
	v_pk_mul_f32 v[54:55], v[100:101], v[100:101]
	v_pk_mul_f32 v[56:57], v[98:99], v[98:99]
	v_pk_mul_f32 v[46:47], v[132:133], v[132:133]
	v_pk_mul_f32 v[48:49], v[130:131], v[130:131]
	v_pk_mov_b32 v[58:59], v[56:57], v[54:55] op_sel:[1,0]
	v_mov_b32_e32 v57, v55
	v_pk_add_f32 v[54:55], v[58:59], v[56:57]
	v_pk_mov_b32 v[56:57], v[48:49], v[46:47] op_sel:[1,0]
	v_mov_b32_e32 v49, v47
	v_pk_add_f32 v[46:47], v[56:57], v[48:49]
	v_pk_add_f32 v[54:55], v[54:55], v[54:55] op_sel_hi:[0,1]
	v_pk_add_f32 v[46:47], v[46:47], v[46:47] op_sel_hi:[0,1]
	v_mul_f32_e32 v46, v134, v134
	v_pk_fma_f32 v[48:49], v[134:135], v[134:135], v[46:47] op_sel_hi:[1,1,0]
	v_mul_f32_e32 v46, v136, v136
	v_pk_fma_f32 v[56:57], v[136:137], v[136:137], v[46:47] op_sel_hi:[1,1,0]
	v_mul_f32_e32 v48, v138, v138
	v_mul_f32_e32 v56, v139, v139
	v_mul_f32_e32 v54, v140, v140
	v_mul_f32_e32 v46, v141, v141
	v_pk_add_f32 v[48:49], v[48:49], v[56:57]
	v_pk_add_f32 v[46:47], v[54:55], v[46:47]
	v_pk_add_f32 v[54:55], v[66:67], 1.0 op_sel_hi:[1,0]
	v_pk_add_f32 v[46:47], v[48:49], v[46:47]
	v_pk_add_f32 v[48:49], v[68:69], 1.0 op_sel_hi:[1,0]
	v_add_f32_e32 v46, v46, v47
	s_nop 1
	v_add_f32_dpp v46, v46, v46 quad_perm:[1,0,3,2] row_mask:0xf bank_mask:0xf
	s_nop 1
	v_add_f32_dpp v46, v46, v46 quad_perm:[2,3,0,1] row_mask:0xf bank_mask:0xf
	s_nop 1
	v_add_f32_dpp v46, v46, v46 row_half_mirror row_mask:0xf bank_mask:0xf
	s_nop 1
	v_add_f32_dpp v46, v46, v46 row_mirror row_mask:0xf bank_mask:0xf
	s_nop 1
	v_add_f32_dpp v46, v46, v46 row_bcast:15 row_mask:0xa bank_mask:0xf
	s_nop 1
	v_add_f32_dpp v46, v46, v46 row_bcast:31 row_mask:0xc bank_mask:0xf
	s_nop 0
	v_readlane_b32 s64, v46, 63
	s_nop 1
	v_mov_b32_e32 v46, s64
	s_waitcnt lgkmcnt(0)
	s_add_i32 s0, s22, 8
	s_add_i32 s1, s22, -8
	s_cmp_lt_i32 s1, s17
	s_mov_b32 s22, s0
	v_mov_b64_e32 v[170:171], v[144:145]
	s_waitcnt vmcnt(3)
	v_mov_b64_e32 v[144:145], v[162:163]
	v_fmamk_f32 v46, v46, 0x3a800000, v196
	v_mul_f32_e32 v47, 0x4b800000, v46
	v_cmp_gt_f32_e32 vcc, s25, v46
	s_nop 1
	v_cndmask_b32_e32 v46, v46, v47, vcc
	v_rsq_f32_e32 v56, v46
	v_lshl_add_u64 v[46:47], v[158:159], 0, s[2:3]
	v_mul_f32_e32 v57, 0x45800000, v56
	v_cndmask_b32_e32 v56, v56, v57, vcc
	v_pk_mul_f32 v[58:59], v[100:101], v[56:57] op_sel_hi:[1,0]
	v_pk_mul_f32 v[60:61], v[98:99], v[56:57] op_sel_hi:[1,0]
	v_pk_mul_f32 v[58:59], v[12:13], v[58:59]
	v_pk_mul_f32 v[60:61], v[10:11], v[60:61]
	v_pk_fma_f32 v[48:49], v[48:49], v[58:59], v[72:73]
	v_pk_fma_f32 v[54:55], v[54:55], v[60:61], v[70:71]
	v_pk_mul_f32 v[98:99], v[132:133], v[56:57] op_sel_hi:[1,0]
	v_pk_mul_f32 v[100:101], v[130:131], v[56:57] op_sel_hi:[1,0]
	v_cvt_pk_bf16_f32 v54, v54, v55
	v_cvt_pk_bf16_f32 v55, v48, v49
	v_pk_mul_f32 v[100:101], v[14:15], v[100:101]
	global_store_dwordx2 v[46:47], v[54:55], off
	v_pk_mul_f32 v[48:49], v[16:17], v[98:99]
	v_pk_add_f32 v[54:55], v[76:77], 1.0 op_sel_hi:[1,0]
	v_pk_add_f32 v[58:59], v[74:75], 1.0 op_sel_hi:[1,0]
	v_pk_fma_f32 v[48:49], v[54:55], v[48:49], v[80:81]
	v_pk_fma_f32 v[54:55], v[58:59], v[100:101], v[78:79]
	v_pk_add_f32 v[58:59], v[84:85], 1.0 op_sel_hi:[1,0]
	v_cvt_pk_bf16_f32 v54, v54, v55
	v_cvt_pk_bf16_f32 v55, v48, v49
	global_store_dwordx2 v[46:47], v[54:55], off offset:512
	v_pk_mul_f32 v[48:49], v[136:137], v[56:57] op_sel_hi:[1,0]
	v_pk_mul_f32 v[54:55], v[134:135], v[56:57] op_sel_hi:[1,0]
	v_pk_mul_f32 v[48:49], v[28:29], v[48:49]
	v_pk_mul_f32 v[54:55], v[26:27], v[54:55]
	v_pk_add_f32 v[60:61], v[82:83], 1.0 op_sel_hi:[1,0]
	s_waitcnt vmcnt(3)
	v_pk_fma_f32 v[48:49], v[58:59], v[48:49], v[92:93]
	v_pk_fma_f32 v[54:55], v[60:61], v[54:55], v[90:91]
	v_pk_add_f32 v[58:59], v[62:63], 1.0 op_sel_hi:[1,0]
	v_cvt_pk_bf16_f32 v54, v54, v55
	v_cvt_pk_bf16_f32 v55, v48, v49
	global_store_dwordx2 v[46:47], v[54:55], off offset:1024
	v_pk_mul_f32 v[48:49], v[140:141], v[56:57] op_sel_hi:[1,0]
	v_pk_mul_f32 v[54:55], v[138:139], v[56:57] op_sel_hi:[1,0]
	v_pk_mul_f32 v[48:49], v[32:33], v[48:49]
	v_pk_mul_f32 v[54:55], v[30:31], v[54:55]
	v_pk_add_f32 v[56:57], v[64:65], 1.0 op_sel_hi:[1,0]
	s_waitcnt vmcnt(3)
	v_pk_fma_f32 v[54:55], v[58:59], v[54:55], v[86:87]
	v_pk_fma_f32 v[48:49], v[56:57], v[48:49], v[88:89]
	v_cvt_pk_bf16_f32 v54, v54, v55
	v_cvt_pk_bf16_f32 v55, v48, v49
	global_store_dwordx2 v[46:47], v[54:55], off offset:1536
	s_mov_b64 vcc, s[98:99]
	s_cbranch_vccz .Leload_skip_1
	s_waitcnt vmcnt(8)
	v_lshlrev_b32_e32 v114, 16, v116
	v_and_b32_e32 v115, 0xffff0000, v116
	v_lshlrev_b32_e32 v116, 16, v117
	v_and_b32_e32 v117, 0xffff0000, v117
	v_lshlrev_b32_e32 v118, 16, v120
	v_and_b32_e32 v119, 0xffff0000, v120
	v_lshlrev_b32_e32 v120, 16, v121
	v_and_b32_e32 v121, 0xffff0000, v121
	v_lshlrev_b32_e32 v122, 16, v124
	v_and_b32_e32 v123, 0xffff0000, v124
	v_lshlrev_b32_e32 v124, 16, v125
	v_and_b32_e32 v125, 0xffff0000, v125
	v_lshlrev_b32_e32 v126, 16, v128
	v_and_b32_e32 v127, 0xffff0000, v128
	v_lshlrev_b32_e32 v128, 16, v129
	v_and_b32_e32 v129, 0xffff0000, v129

.LBB0_1213_u1:
	s_mov_b64 s[98:99], 0
	s_cmp_ge_i32 s22, s17
	s_cbranch_scc1 .LBB0_1220_u1
	s_add_i32 s1, s21, s22
	s_add_i32 s0, s20, s22
	s_add_i32 s1, s1, 0x8000
	s_cmp_lt_i32 s22, s16
	s_cselect_b32 s0, s0, s1
	s_cmp_lt_i32 s0, 0x8000
	s_cselect_b64 s[2:3], -1, 0
	s_cmpk_gt_i32 s0, 0x7fff
	s_mov_b64 s[10:11], -1
	s_cbranch_scc0 .LBB0_1216_u1
	s_add_i32 s4, s0, 0xffff8000
	s_lshl_b64 s[10:11], s[4:5], 12
	v_lshl_add_u64 v[46:47], v[160:161], 0, s[10:11]
	global_load_dwordx4 v[98:101], v[46:47], off nt
	global_load_dwordx4 v[58:61], v[46:47], off offset:1024 nt
	global_load_dwordx4 v[54:57], v[46:47], off offset:2048 nt
	s_nop 0
	global_load_dwordx4 v[46:49], v[46:47], off offset:3072 nt
	s_mov_b64 s[10:11], 0
.LBB0_1216_u1:
	s_andn2_b64 vcc, exec, s[10:11]
	s_cbranch_vccnz .LBB0_1218_u1
	s_ashr_i32 s1, s0, 31
	s_lshl_b64 s[10:11], s[0:1], 11
	s_waitcnt vmcnt(3)
	v_lshl_add_u64 v[98:99], v[152:153], 0, s[10:11]
	global_load_dwordx2 v[100:101], v[98:99], off nt
	global_load_dwordx2 v[60:61], v[98:99], off offset:512 nt
	global_load_dwordx2 v[56:57], v[98:99], off offset:1024 nt
	global_load_dwordx2 v[48:49], v[98:99], off offset:1536 nt
	s_mov_b64 s[98:99], -1

; #define GAS __attribute__((address_space(1)))
; DI unsigned pk2(float lo, float hi) { f32x2_t v = {lo, hi}; bf16x2_t b = __builtin_convertvector(v, bf16x2_t); return __builtin_bit_cast(unsigned, b); }
; DI float bflo(unsigned w) { return __uint_as_float(w << 16); }
; DI float bfhi(unsigned w) { return __uint_as_float(w & 0xffff0000u); }
; DI void phase_e(const Ctx& C, int nslab, int has_post, int pl, int ps, float pw, int has_pre, int ql, int qs, int nrows,
;                 const GAS float* xsrc, const GAS float* csrc, GAS float* xdst, GAS float* cdst, bool xs16, bool xd16) {
;     ...
;         if (has_post) {
;             f32x4 y[4]; float ss = 0.f;
; #pragma unroll
;             for (int j = 0; j < 4; ++j) {
;                 if (isx || nslab == 0) { y[j] = (f32x4){bflo(yw[j].x), bfhi(yw[j].x), bflo(yw[j].y), bfhi(yw[j].y)}; }
;                 else { y[j] = (f32x4){0.f, 0.f, 0.f, 0.f};
;                     for (int s = 0; s < nslab; ++s) { const u32x2 w = *(const GAS u32x2*)(YS + ((size_t)s * MC + (row - MX)) * 1024 + 256 * j + 4 * lane); y[j] += (f32x4){bflo(w.x), bfhi(w.x), bflo(w.y), bfhi(w.y)}; } }
;                 ss += (y[j][0] * y[j][0] + y[j][1] * y[j][1]) + (y[j][2] * y[j][2] + y[j][3] * y[j][3]); }
;             const float r = rsqrtf(wave_sum(ss) * (1.0f / 1024.0f) + EPS);
;             if (isx && xd16) { GAS bf16* d16 = (GAS bf16*)xdst + (size_t)row * 1024;
; #pragma unroll
;                 for (int j = 0; j < 4; ++j) { v[j] += pw * gt[j] * ((y[j] * r) * gpo[j]); u32x2 w; w.x = pk2(v[j][0], v[j][1]); w.y = pk2(v[j][2], v[j][3]); __builtin_nontemporal_store(w, (GAS u32x2*)(d16 + 256 * j + 4 * lane));
;                     v[j] = (f32x4){bflo(w.x), bfhi(w.x), bflo(w.y), bfhi(w.y)}; }
;             } else { GAS float* dst = isx ? xdst + (size_t)row * 1024 : cdst + (size_t)(row - MX) * 1024;
; #pragma unroll
;                 for (int j = 0; j < 4; ++j) { v[j] += pw * gt[j] * ((y[j] * r) * gpo[j]); __builtin_nontemporal_store(v[j], (GAS f32x4*)(dst + 256 * j + 4 * lane)); } }
;         }
.LBB0_1238_u1:
	v_mul_f32_e32 v130, v141, v141
	v_mul_f32_e32 v131, v139, v139
	v_fmac_f32_e32 v130, v140, v140
	v_fmac_f32_e32 v131, v138, v138
	v_add_f32_e32 v130, v130, v131
	v_mul_f32_e32 v131, v171, v171
	v_mul_f32_e32 v132, v173, v173
	v_fmac_f32_e32 v131, v170, v170
	v_fmac_f32_e32 v132, v172, v172
	v_add_f32_e32 v131, v131, v132
	v_add_f32_e32 v130, v130, v131
	v_mul_f32_e32 v131, v175, v175
	v_mul_f32_e32 v132, v177, v177
	v_fmac_f32_e32 v131, v174, v174
	v_fmac_f32_e32 v132, v176, v176
	v_add_f32_e32 v131, v131, v132
	v_add_f32_e32 v136, v130, v131
	v_pk_mul_f32 v[130:131], v[180:181], v[180:181]
	v_pk_mul_f32 v[132:133], v[178:179], v[178:179]
	s_and_b64 s[0:1], exec, s[0:1]
	v_pk_mov_b32 v[134:135], v[132:133], v[130:131] op_sel:[1,0]
	v_mov_b32_e32 v133, v131
	v_pk_add_f32 v[130:131], v[134:135], v[132:133]
	s_ashr_i32 s11, s10, 31
	v_add_f32_e32 v130, v130, v131
	v_add_f32_e32 v130, v136, v130
	s_nop 1
	v_add_f32_dpp v130, v130, v130 quad_perm:[1,0,3,2] row_mask:0xf bank_mask:0xf
	s_nop 1
	v_add_f32_dpp v130, v130, v130 quad_perm:[2,3,0,1] row_mask:0xf bank_mask:0xf
	s_nop 1
	v_add_f32_dpp v130, v130, v130 row_half_mirror row_mask:0xf bank_mask:0xf
	s_nop 1
	v_add_f32_dpp v130, v130, v130 row_mirror row_mask:0xf bank_mask:0xf
	s_nop 1
	v_add_f32_dpp v130, v130, v130 row_bcast:15 row_mask:0xa bank_mask:0xf
	s_nop 1
	v_add_f32_dpp v130, v130, v130 row_bcast:31 row_mask:0xc bank_mask:0xf
	s_nop 0
	v_readlane_b32 s64, v130, 63
	s_nop 1
	v_mov_b32_e32 v132, s64
	s_waitcnt lgkmcnt(0)
	s_mov_b64 s[12:13], -1
	s_waitcnt vmcnt(7)
	v_pk_mul_f32 v[188:189], v[102:103], 0.5 op_sel_hi:[1,0]
	s_waitcnt vmcnt(6)
	v_pk_mul_f32 v[186:187], v[106:107], 0.5 op_sel_hi:[1,0]
	s_waitcnt vmcnt(4)
	v_pk_mul_f32 v[184:185], v[110:111], 0.5 op_sel_hi:[1,0]
	v_pk_mul_f32 v[130:131], v[96:97], 0.5 op_sel_hi:[1,0]
	v_fmamk_f32 v132, v132, 0x3a800000, v196
	v_mul_f32_e32 v133, 0x4b800000, v132
	v_cmp_gt_f32_e32 vcc, s25, v132
	s_nop 1
	v_cndmask_b32_e32 v132, v132, v133, vcc
	v_rsq_f32_e32 v134, v132
	v_pk_mul_f32 v[132:133], v[94:95], 0.5 op_sel_hi:[1,0]
	v_mul_f32_e32 v135, 0x45800000, v134
	v_cndmask_b32_e32 v182, v134, v135, vcc
	v_mov_b32_e32 v183, v182
	v_pk_mul_f32 v[134:135], v[138:139], v[182:183] op_sel_hi:[1,0]
	v_pk_mul_f32 v[136:137], v[140:141], v[182:183] op_sel_hi:[1,0]
	v_pk_mul_f32 v[134:135], v[4:5], v[134:135]
	v_pk_mul_f32 v[136:137], v[2:3], v[136:137]
	v_pk_fma_f32 v[36:37], v[130:131], v[134:135], v[36:37]
	v_pk_fma_f32 v[34:35], v[132:133], v[136:137], v[34:35]
	s_mov_b64 vcc, s[0:1]
	s_cbranch_vccz .LBB0_1240_u1
	v_mov_b32_e32 v138, v182
	v_mov_b32_e32 v139, v182
	v_pk_mul_f32 v[132:133], v[172:173], v[138:139]
	v_pk_mul_f32 v[134:135], v[170:171], v[182:183]
	v_pk_mul_f32 v[130:131], v[104:105], 0.5 op_sel_hi:[1,0]
	v_pk_mul_f32 v[132:133], v[8:9], v[132:133]
	v_pk_mul_f32 v[134:135], v[6:7], v[134:135]
	v_pk_mul_f32 v[136:137], v[176:177], v[138:139]
	v_pk_mul_f32 v[140:141], v[174:175], v[182:183]
	v_pk_fma_f32 v[132:133], v[130:131], v[132:133], v[40:41]
	v_pk_fma_f32 v[130:131], v[188:189], v[134:135], v[38:39]
	v_pk_mul_f32 v[134:135], v[108:109], 0.5 op_sel_hi:[1,0]
	v_pk_mul_f32 v[136:137], v[20:21], v[136:137]
	v_pk_mul_f32 v[140:141], v[18:19], v[140:141]
	v_pk_mul_f32 v[138:139], v[180:181], v[138:139]
	v_pk_mul_f32 v[200:201], v[178:179], v[182:183]
	s_lshl_b64 s[0:1], s[4:5], 12
	v_pk_fma_f32 v[136:137], v[134:135], v[136:137], v[44:45]
	v_pk_fma_f32 v[134:135], v[186:187], v[140:141], v[42:43]
	v_pk_mul_f32 v[140:141], v[112:113], 0.5 op_sel_hi:[1,0]
	v_pk_mul_f32 v[138:139], v[24:25], v[138:139]
	v_pk_mul_f32 v[200:201], v[22:23], v[200:201]
	v_lshl_add_u64 v[198:199], v[160:161], 0, s[0:1]
	v_pk_fma_f32 v[140:141], v[140:141], v[138:139], v[52:53]
	v_pk_fma_f32 v[138:139], v[184:185], v[200:201], v[50:51]
	global_store_dwordx4 v[198:199], v[34:37], off nt
	global_store_dwordx4 v[198:199], v[130:133], off offset:1024 nt
	global_store_dwordx4 v[198:199], v[134:137], off offset:2048 nt
	global_store_dwordx4 v[198:199], v[138:141], off offset:3072 nt
	s_lshl_b64 s[2:3], s[10:11], 11
	s_mov_b64 s[12:13], 0
.LBB0_1240_u1:
	s_andn2_b64 vcc, exec, s[12:13]
	s_cbranch_vccnz .LBB0_1212_u1
	s_lshl_b64 s[2:3], s[10:11], 11
	v_mov_b32_e32 v140, v182
	v_mov_b32_e32 v141, v182
	v_lshl_add_u64 v[138:139], v[152:153], 0, s[2:3]
	v_cvt_pk_bf16_f32 v130, v34, v35
	v_cvt_pk_bf16_f32 v131, v36, v37
	v_pk_mul_f32 v[132:133], v[172:173], v[140:141]
	v_pk_mul_f32 v[134:135], v[170:171], v[182:183]
	global_store_dwordx2 v[138:139], v[130:131], off nt
	v_lshlrev_b32_e32 v34, 16, v130
	v_and_b32_e32 v35, 0xffff0000, v130
	v_lshlrev_b32_e32 v36, 16, v131
	v_and_b32_e32 v37, 0xffff0000, v131
	v_pk_mul_f32 v[130:131], v[104:105], 0.5 op_sel_hi:[1,0]
	v_pk_mul_f32 v[132:133], v[8:9], v[132:133]
	v_pk_mul_f32 v[134:135], v[6:7], v[134:135]
	v_pk_fma_f32 v[40:41], v[130:131], v[132:133], v[40:41]
	v_pk_fma_f32 v[38:39], v[188:189], v[134:135], v[38:39]
	v_pk_mul_f32 v[134:135], v[174:175], v[182:183]
	v_cvt_pk_bf16_f32 v38, v38, v39
	v_cvt_pk_bf16_f32 v39, v40, v41
	v_pk_mul_f32 v[40:41], v[176:177], v[140:141]
	global_store_dwordx2 v[138:139], v[38:39], off offset:512 nt
	v_lshlrev_b32_e32 v130, 16, v38
	v_and_b32_e32 v131, 0xffff0000, v38
	v_lshlrev_b32_e32 v132, 16, v39
	v_and_b32_e32 v133, 0xffff0000, v39
	v_pk_mul_f32 v[38:39], v[108:109], 0.5 op_sel_hi:[1,0]
	v_pk_mul_f32 v[40:41], v[20:21], v[40:41]
	v_pk_mul_f32 v[134:135], v[18:19], v[134:135]
	v_pk_fma_f32 v[44:45], v[38:39], v[40:41], v[44:45]
	v_pk_fma_f32 v[42:43], v[186:187], v[134:135], v[42:43]
	v_pk_mul_f32 v[38:39], v[178:179], v[182:183]
	v_cvt_pk_bf16_f32 v42, v42, v43
	v_cvt_pk_bf16_f32 v43, v44, v45
	v_pk_mul_f32 v[44:45], v[180:181], v[140:141]
	global_store_dwordx2 v[138:139], v[42:43], off offset:1024 nt
	v_lshlrev_b32_e32 v134, 16, v42
	v_and_b32_e32 v135, 0xffff0000, v42
	v_lshlrev_b32_e32 v136, 16, v43
	v_and_b32_e32 v137, 0xffff0000, v43
	v_pk_mul_f32 v[42:43], v[112:113], 0.5 op_sel_hi:[1,0]
	v_pk_mul_f32 v[44:45], v[24:25], v[44:45]
	v_pk_mul_f32 v[38:39], v[22:23], v[38:39]
	v_pk_fma_f32 v[52:53], v[42:43], v[44:45], v[52:53]
	v_pk_fma_f32 v[50:51], v[184:185], v[38:39], v[50:51]
	s_nop 0
	v_cvt_pk_bf16_f32 v50, v50, v51
	v_cvt_pk_bf16_f32 v51, v52, v53
	global_store_dwordx2 v[138:139], v[50:51], off offset:1536 nt
	v_lshlrev_b32_e32 v138, 16, v50
	v_and_b32_e32 v139, 0xffff0000, v50
	v_lshlrev_b32_e32 v140, 16, v51
	v_and_b32_e32 v141, 0xffff0000, v51
	s_branch .LBB0_1212_u1
; #define GAS __attribute__((address_space(1)))
; DI unsigned pk2(float lo, float hi) { f32x2_t v = {lo, hi}; bf16x2_t b = __builtin_convertvector(v, bf16x2_t); return __builtin_bit_cast(unsigned, b); }
; DI void phase_e(const Ctx& C, int nslab, int has_post, int pl, int ps, float pw, int has_pre, int ql, int qs, int nrows,
;                 const GAS float* xsrc, const GAS float* csrc, GAS float* xdst, GAS float* cdst, bool xs16, bool xd16) {
;     ...
;         if (has_pre) {
;             float ss = 0.f;
; #pragma unroll
;             for (int j = 0; j < 4; ++j) ss += (v[j][0] * v[j][0] + v[j][1] * v[j][1]) + (v[j][2] * v[j][2] + v[j][3] * v[j][3]);
;             const float r = rsqrtf(wave_sum(ss) * (1.0f / 1024.0f) + EPS);
; #pragma unroll
;             for (int j = 0; j < 4; ++j) { const f32x4 h = ((v[j] * r) * gpr[j]) * (1.0f + sc[j]) + sh[j];
;                 u32x2 w; w.x = pk2(h[0], h[1]); w.y = pk2(h[2], h[3]); *(GAS u32x2*)(H + (size_t)row * 1024 + 256 * j + 4 * lane) = w; }
.LBB0_1212_u1:
	v_pk_mul_f32 v[42:43], v[36:37], v[36:37]
	v_pk_mul_f32 v[44:45], v[34:35], v[34:35]
	v_pk_mul_f32 v[50:51], v[132:133], v[132:133]
	v_pk_mul_f32 v[52:53], v[130:131], v[130:131]
	v_pk_mov_b32 v[38:39], v[44:45], v[42:43] op_sel:[1,0]
	v_mov_b32_e32 v45, v43
	v_pk_add_f32 v[42:43], v[38:39], v[44:45]
	v_pk_mov_b32 v[44:45], v[52:53], v[50:51] op_sel:[1,0]
	v_mov_b32_e32 v53, v51
	v_pk_add_f32 v[50:51], v[44:45], v[52:53]
	v_pk_add_f32 v[42:43], v[42:43], v[42:43] op_sel_hi:[0,1]
	v_pk_add_f32 v[50:51], v[50:51], v[50:51] op_sel_hi:[0,1]
	v_mul_f32_e32 v50, v134, v134
	v_pk_fma_f32 v[52:53], v[134:135], v[134:135], v[50:51] op_sel_hi:[1,1,0]
	v_mul_f32_e32 v50, v136, v136
	v_pk_fma_f32 v[44:45], v[136:137], v[136:137], v[50:51] op_sel_hi:[1,1,0]
	v_mul_f32_e32 v52, v138, v138
	v_mul_f32_e32 v44, v139, v139
	v_mul_f32_e32 v42, v140, v140
	v_mul_f32_e32 v50, v141, v141
	v_pk_add_f32 v[52:53], v[52:53], v[44:45]
	v_pk_add_f32 v[50:51], v[42:43], v[50:51]
	v_pk_add_f32 v[42:43], v[66:67], 1.0 op_sel_hi:[1,0]
	v_pk_add_f32 v[50:51], v[52:53], v[50:51]
	v_pk_add_f32 v[52:53], v[68:69], 1.0 op_sel_hi:[1,0]
	v_add_f32_e32 v50, v50, v51
	s_nop 1
	v_add_f32_dpp v50, v50, v50 quad_perm:[1,0,3,2] row_mask:0xf bank_mask:0xf
	s_nop 1
	v_add_f32_dpp v50, v50, v50 quad_perm:[2,3,0,1] row_mask:0xf bank_mask:0xf
	s_nop 1
	v_add_f32_dpp v50, v50, v50 row_half_mirror row_mask:0xf bank_mask:0xf
	s_nop 1
	v_add_f32_dpp v50, v50, v50 row_mirror row_mask:0xf bank_mask:0xf
	s_nop 1
	v_add_f32_dpp v50, v50, v50 row_bcast:15 row_mask:0xa bank_mask:0xf
	s_nop 1
	v_add_f32_dpp v50, v50, v50 row_bcast:31 row_mask:0xc bank_mask:0xf
	s_nop 0
	v_readlane_b32 s64, v50, 63
	s_nop 1
	v_mov_b32_e32 v50, s64
	s_waitcnt lgkmcnt(0)
	s_add_i32 s0, s22, 8
	s_add_i32 s1, s22, -8
	s_cmp_lt_i32 s1, s17
	s_mov_b32 s22, s0
	v_mov_b64_e32 v[170:171], v[144:145]
	s_waitcnt vmcnt(3)
	v_mov_b64_e32 v[144:145], v[162:163]
	v_fmamk_f32 v50, v50, 0x3a800000, v196
	v_mul_f32_e32 v51, 0x4b800000, v50
	v_cmp_gt_f32_e32 vcc, s25, v50
	s_nop 1
	v_cndmask_b32_e32 v50, v50, v51, vcc
	v_rsq_f32_e32 v44, v50
	v_lshl_add_u64 v[50:51], v[158:159], 0, s[2:3]
	v_mul_f32_e32 v45, 0x45800000, v44
	v_cndmask_b32_e32 v44, v44, v45, vcc
	v_pk_mul_f32 v[38:39], v[36:37], v[44:45] op_sel_hi:[1,0]
	v_pk_mul_f32 v[40:41], v[34:35], v[44:45] op_sel_hi:[1,0]
	v_pk_mul_f32 v[38:39], v[12:13], v[38:39]
	v_pk_mul_f32 v[40:41], v[10:11], v[40:41]
	v_pk_fma_f32 v[52:53], v[52:53], v[38:39], v[72:73]
	v_pk_fma_f32 v[42:43], v[42:43], v[40:41], v[70:71]
	v_pk_mul_f32 v[34:35], v[132:133], v[44:45] op_sel_hi:[1,0]
	v_pk_mul_f32 v[36:37], v[130:131], v[44:45] op_sel_hi:[1,0]
	v_cvt_pk_bf16_f32 v42, v42, v43
	v_cvt_pk_bf16_f32 v43, v52, v53
	v_pk_mul_f32 v[36:37], v[14:15], v[36:37]
	global_store_dwordx2 v[50:51], v[42:43], off
	v_pk_mul_f32 v[52:53], v[16:17], v[34:35]
	v_pk_add_f32 v[42:43], v[76:77], 1.0 op_sel_hi:[1,0]
	v_pk_add_f32 v[38:39], v[74:75], 1.0 op_sel_hi:[1,0]
	v_pk_fma_f32 v[52:53], v[42:43], v[52:53], v[80:81]
	v_pk_fma_f32 v[42:43], v[38:39], v[36:37], v[78:79]
	v_pk_add_f32 v[38:39], v[84:85], 1.0 op_sel_hi:[1,0]
	v_cvt_pk_bf16_f32 v42, v42, v43
	v_cvt_pk_bf16_f32 v43, v52, v53
	global_store_dwordx2 v[50:51], v[42:43], off offset:512
	v_pk_mul_f32 v[52:53], v[136:137], v[44:45] op_sel_hi:[1,0]
	v_pk_mul_f32 v[42:43], v[134:135], v[44:45] op_sel_hi:[1,0]
	v_pk_mul_f32 v[52:53], v[28:29], v[52:53]
	v_pk_mul_f32 v[42:43], v[26:27], v[42:43]
	v_pk_add_f32 v[40:41], v[82:83], 1.0 op_sel_hi:[1,0]
	s_waitcnt vmcnt(3)
	v_pk_fma_f32 v[52:53], v[38:39], v[52:53], v[92:93]
	v_pk_fma_f32 v[42:43], v[40:41], v[42:43], v[90:91]
	v_pk_add_f32 v[38:39], v[62:63], 1.0 op_sel_hi:[1,0]
	v_cvt_pk_bf16_f32 v42, v42, v43
	v_cvt_pk_bf16_f32 v43, v52, v53
	global_store_dwordx2 v[50:51], v[42:43], off offset:1024
	v_pk_mul_f32 v[52:53], v[140:141], v[44:45] op_sel_hi:[1,0]
	v_pk_mul_f32 v[42:43], v[138:139], v[44:45] op_sel_hi:[1,0]
	v_pk_mul_f32 v[52:53], v[32:33], v[52:53]
	v_pk_mul_f32 v[42:43], v[30:31], v[42:43]
	v_pk_add_f32 v[44:45], v[64:65], 1.0 op_sel_hi:[1,0]
	s_waitcnt vmcnt(3)
	v_pk_fma_f32 v[42:43], v[38:39], v[42:43], v[86:87]
	v_pk_fma_f32 v[52:53], v[44:45], v[52:53], v[88:89]
	v_cvt_pk_bf16_f32 v42, v42, v43
	v_cvt_pk_bf16_f32 v43, v52, v53
	global_store_dwordx2 v[50:51], v[42:43], off offset:1536
	s_mov_b64 vcc, s[98:99]
	s_cbranch_vccz .Leload_skip_1_u1
	s_waitcnt vmcnt(8)
	v_lshlrev_b32_e32 v98, 16, v100
	v_and_b32_e32 v99, 0xffff0000, v100
	v_lshlrev_b32_e32 v100, 16, v101
	v_and_b32_e32 v101, 0xffff0000, v101
	v_lshlrev_b32_e32 v58, 16, v60
	v_and_b32_e32 v59, 0xffff0000, v60
	v_lshlrev_b32_e32 v60, 16, v61
	v_and_b32_e32 v61, 0xffff0000, v61
	v_lshlrev_b32_e32 v54, 16, v56
	v_and_b32_e32 v55, 0xffff0000, v56
	v_lshlrev_b32_e32 v56, 16, v57
	v_and_b32_e32 v57, 0xffff0000, v57
	v_lshlrev_b32_e32 v46, 16, v48
	v_and_b32_e32 v47, 0xffff0000, v48
	v_lshlrev_b32_e32 v48, 16, v49
	v_and_b32_e32 v49, 0xffff0000, v49

.LBB0_1213_u2:
	s_mov_b64 s[98:99], 0
	s_cmp_ge_i32 s22, s17
	s_cbranch_scc1 .LBB0_1220_u2
	s_add_i32 s1, s21, s22
	s_add_i32 s0, s20, s22
	s_add_i32 s1, s1, 0x8000
	s_cmp_lt_i32 s22, s16
	s_cselect_b32 s0, s0, s1
	s_cmp_lt_i32 s0, 0x8000
	s_cselect_b64 s[2:3], -1, 0
	s_cmpk_gt_i32 s0, 0x7fff
	s_mov_b64 s[10:11], -1
	s_cbranch_scc0 .LBB0_1216_u2
	s_add_i32 s4, s0, 0xffff8000
	s_lshl_b64 s[10:11], s[4:5], 12
	v_lshl_add_u64 v[50:51], v[160:161], 0, s[10:11]
	global_load_dwordx4 v[34:37], v[50:51], off nt
	global_load_dwordx4 v[38:41], v[50:51], off offset:1024 nt
	global_load_dwordx4 v[42:45], v[50:51], off offset:2048 nt
	s_nop 0
	global_load_dwordx4 v[50:53], v[50:51], off offset:3072 nt
	s_mov_b64 s[10:11], 0

; #define GAS __attribute__((address_space(1)))
; DI unsigned pk2(float lo, float hi) { f32x2_t v = {lo, hi}; bf16x2_t b = __builtin_convertvector(v, bf16x2_t); return __builtin_bit_cast(unsigned, b); }
; DI float bflo(unsigned w) { return __uint_as_float(w << 16); }
; DI float bfhi(unsigned w) { return __uint_as_float(w & 0xffff0000u); }
; DI void phase_e(const Ctx& C, int nslab, int has_post, int pl, int ps, float pw, int has_pre, int ql, int qs, int nrows,
;                 const GAS float* xsrc, const GAS float* csrc, GAS float* xdst, GAS float* cdst, bool xs16, bool xd16) {
;     ...
;         if (has_post) {
;             f32x4 y[4]; float ss = 0.f;
; #pragma unroll
;             for (int j = 0; j < 4; ++j) {
;                 if (isx || nslab == 0) { y[j] = (f32x4){bflo(yw[j].x), bfhi(yw[j].x), bflo(yw[j].y), bfhi(yw[j].y)}; }
;                 else { y[j] = (f32x4){0.f, 0.f, 0.f, 0.f};
;                     for (int s = 0; s < nslab; ++s) { const u32x2 w = *(const GAS u32x2*)(YS + ((size_t)s * MC + (row - MX)) * 1024 + 256 * j + 4 * lane); y[j] += (f32x4){bflo(w.x), bfhi(w.x), bflo(w.y), bfhi(w.y)}; } }
;                 ss += (y[j][0] * y[j][0] + y[j][1] * y[j][1]) + (y[j][2] * y[j][2] + y[j][3] * y[j][3]); }
;             const float r = rsqrtf(wave_sum(ss) * (1.0f / 1024.0f) + EPS);
;             if (isx && xd16) { GAS bf16* d16 = (GAS bf16*)xdst + (size_t)row * 1024;
; #pragma unroll
;                 for (int j = 0; j < 4; ++j) { v[j] += pw * gt[j] * ((y[j] * r) * gpo[j]); u32x2 w; w.x = pk2(v[j][0], v[j][1]); w.y = pk2(v[j][2], v[j][3]); __builtin_nontemporal_store(w, (GAS u32x2*)(d16 + 256 * j + 4 * lane));
;                     v[j] = (f32x4){bflo(w.x), bfhi(w.x), bflo(w.y), bfhi(w.y)}; }
;             } else { GAS float* dst = isx ? xdst + (size_t)row * 1024 : cdst + (size_t)(row - MX) * 1024;
; #pragma unroll
;                 for (int j = 0; j < 4; ++j) { v[j] += pw * gt[j] * ((y[j] * r) * gpo[j]); __builtin_nontemporal_store(v[j], (GAS f32x4*)(dst + 256 * j + 4 * lane)); } }
;         }
.LBB0_1238_u2:
	v_mul_f32_e32 v130, v141, v141
	v_mul_f32_e32 v131, v139, v139
	v_fmac_f32_e32 v130, v140, v140
	v_fmac_f32_e32 v131, v138, v138
	v_add_f32_e32 v130, v130, v131
	v_mul_f32_e32 v131, v171, v171
	v_mul_f32_e32 v132, v173, v173
	v_fmac_f32_e32 v131, v170, v170
	v_fmac_f32_e32 v132, v172, v172
	v_add_f32_e32 v131, v131, v132
	v_add_f32_e32 v130, v130, v131
	v_mul_f32_e32 v131, v175, v175
	v_mul_f32_e32 v132, v177, v177
	v_fmac_f32_e32 v131, v174, v174
	v_fmac_f32_e32 v132, v176, v176
	v_add_f32_e32 v131, v131, v132
	v_add_f32_e32 v136, v130, v131
	v_pk_mul_f32 v[130:131], v[180:181], v[180:181]
	v_pk_mul_f32 v[132:133], v[178:179], v[178:179]
	s_and_b64 s[0:1], exec, s[0:1]
	v_pk_mov_b32 v[134:135], v[132:133], v[130:131] op_sel:[1,0]
	v_mov_b32_e32 v133, v131
	v_pk_add_f32 v[130:131], v[134:135], v[132:133]
	s_ashr_i32 s11, s10, 31
	v_add_f32_e32 v130, v130, v131
	v_add_f32_e32 v130, v136, v130
	s_nop 1
	v_add_f32_dpp v130, v130, v130 quad_perm:[1,0,3,2] row_mask:0xf bank_mask:0xf
	s_nop 1
	v_add_f32_dpp v130, v130, v130 quad_perm:[2,3,0,1] row_mask:0xf bank_mask:0xf
	s_nop 1
	v_add_f32_dpp v130, v130, v130 row_half_mirror row_mask:0xf bank_mask:0xf
	s_nop 1
	v_add_f32_dpp v130, v130, v130 row_mirror row_mask:0xf bank_mask:0xf
	s_nop 1
	v_add_f32_dpp v130, v130, v130 row_bcast:15 row_mask:0xa bank_mask:0xf
	s_nop 1
	v_add_f32_dpp v130, v130, v130 row_bcast:31 row_mask:0xc bank_mask:0xf
	s_nop 0
	v_readlane_b32 s64, v130, 63
	s_nop 1
	v_mov_b32_e32 v132, s64
	s_waitcnt lgkmcnt(0)
	s_mov_b64 s[12:13], -1
	s_waitcnt vmcnt(7)
	v_pk_mul_f32 v[188:189], v[102:103], 0.5 op_sel_hi:[1,0]
	s_waitcnt vmcnt(6)
	v_pk_mul_f32 v[186:187], v[106:107], 0.5 op_sel_hi:[1,0]
	s_waitcnt vmcnt(4)
	v_pk_mul_f32 v[184:185], v[110:111], 0.5 op_sel_hi:[1,0]
	v_pk_mul_f32 v[130:131], v[96:97], 0.5 op_sel_hi:[1,0]
	v_fmamk_f32 v132, v132, 0x3a800000, v196
	v_mul_f32_e32 v133, 0x4b800000, v132
	v_cmp_gt_f32_e32 vcc, s25, v132
	s_nop 1
	v_cndmask_b32_e32 v132, v132, v133, vcc
	v_rsq_f32_e32 v134, v132
	v_pk_mul_f32 v[132:133], v[94:95], 0.5 op_sel_hi:[1,0]
	v_mul_f32_e32 v135, 0x45800000, v134
	v_cndmask_b32_e32 v182, v134, v135, vcc
	v_mov_b32_e32 v183, v182
	v_pk_mul_f32 v[134:135], v[138:139], v[182:183] op_sel_hi:[1,0]
	v_pk_mul_f32 v[136:137], v[140:141], v[182:183] op_sel_hi:[1,0]
	v_pk_mul_f32 v[134:135], v[4:5], v[134:135]
	v_pk_mul_f32 v[136:137], v[2:3], v[136:137]
	v_pk_fma_f32 v[116:117], v[130:131], v[134:135], v[116:117]
	v_pk_fma_f32 v[114:115], v[132:133], v[136:137], v[114:115]
	s_mov_b64 vcc, s[0:1]
	s_cbranch_vccz .LBB0_1240_u2
	v_mov_b32_e32 v138, v182
	v_mov_b32_e32 v139, v182
	v_pk_mul_f32 v[132:133], v[172:173], v[138:139]
	v_pk_mul_f32 v[134:135], v[170:171], v[182:183]
	v_pk_mul_f32 v[130:131], v[104:105], 0.5 op_sel_hi:[1,0]
	v_pk_mul_f32 v[132:133], v[8:9], v[132:133]
	v_pk_mul_f32 v[134:135], v[6:7], v[134:135]
	v_pk_mul_f32 v[136:137], v[176:177], v[138:139]
	v_pk_mul_f32 v[140:141], v[174:175], v[182:183]
	v_pk_fma_f32 v[132:133], v[130:131], v[132:133], v[120:121]
	v_pk_fma_f32 v[130:131], v[188:189], v[134:135], v[118:119]
	v_pk_mul_f32 v[134:135], v[108:109], 0.5 op_sel_hi:[1,0]
	v_pk_mul_f32 v[136:137], v[20:21], v[136:137]
	v_pk_mul_f32 v[140:141], v[18:19], v[140:141]
	v_pk_mul_f32 v[138:139], v[180:181], v[138:139]
	v_pk_mul_f32 v[200:201], v[178:179], v[182:183]
	s_lshl_b64 s[0:1], s[4:5], 12
	v_pk_fma_f32 v[136:137], v[134:135], v[136:137], v[124:125]
	v_pk_fma_f32 v[134:135], v[186:187], v[140:141], v[122:123]
	v_pk_mul_f32 v[140:141], v[112:113], 0.5 op_sel_hi:[1,0]
	v_pk_mul_f32 v[138:139], v[24:25], v[138:139]
	v_pk_mul_f32 v[200:201], v[22:23], v[200:201]
	v_lshl_add_u64 v[198:199], v[160:161], 0, s[0:1]
	v_pk_fma_f32 v[140:141], v[140:141], v[138:139], v[128:129]
	v_pk_fma_f32 v[138:139], v[184:185], v[200:201], v[126:127]
	global_store_dwordx4 v[198:199], v[114:117], off nt
	global_store_dwordx4 v[198:199], v[130:133], off offset:1024 nt
	global_store_dwordx4 v[198:199], v[134:137], off offset:2048 nt
	global_store_dwordx4 v[198:199], v[138:141], off offset:3072 nt
	s_lshl_b64 s[2:3], s[10:11], 11
	s_mov_b64 s[12:13], 0
.LBB0_1240_u2:
	s_andn2_b64 vcc, exec, s[12:13]
	s_cbranch_vccnz .LBB0_1212
	s_lshl_b64 s[2:3], s[10:11], 11
	v_mov_b32_e32 v140, v182
	v_mov_b32_e32 v141, v182
	v_lshl_add_u64 v[138:139], v[152:153], 0, s[2:3]
	v_cvt_pk_bf16_f32 v130, v114, v115
	v_cvt_pk_bf16_f32 v131, v116, v117
	v_pk_mul_f32 v[132:133], v[172:173], v[140:141]
	v_pk_mul_f32 v[134:135], v[170:171], v[182:183]
	global_store_dwordx2 v[138:139], v[130:131], off nt
	v_lshlrev_b32_e32 v114, 16, v130
	v_and_b32_e32 v115, 0xffff0000, v130
	v_lshlrev_b32_e32 v116, 16, v131
	v_and_b32_e32 v117, 0xffff0000, v131
	v_pk_mul_f32 v[130:131], v[104:105], 0.5 op_sel_hi:[1,0]
	v_pk_mul_f32 v[132:133], v[8:9], v[132:133]
	v_pk_mul_f32 v[134:135], v[6:7], v[134:135]
	v_pk_fma_f32 v[120:121], v[130:131], v[132:133], v[120:121]
	v_pk_fma_f32 v[118:119], v[188:189], v[134:135], v[118:119]
	v_pk_mul_f32 v[134:135], v[174:175], v[182:183]
	v_cvt_pk_bf16_f32 v118, v118, v119
	v_cvt_pk_bf16_f32 v119, v120, v121
	v_pk_mul_f32 v[120:121], v[176:177], v[140:141]
	global_store_dwordx2 v[138:139], v[118:119], off offset:512 nt
	v_lshlrev_b32_e32 v130, 16, v118
	v_and_b32_e32 v131, 0xffff0000, v118
	v_lshlrev_b32_e32 v132, 16, v119
	v_and_b32_e32 v133, 0xffff0000, v119
	v_pk_mul_f32 v[118:119], v[108:109], 0.5 op_sel_hi:[1,0]
	v_pk_mul_f32 v[120:121], v[20:21], v[120:121]
	v_pk_mul_f32 v[134:135], v[18:19], v[134:135]
	v_pk_fma_f32 v[124:125], v[118:119], v[120:121], v[124:125]
	v_pk_fma_f32 v[122:123], v[186:187], v[134:135], v[122:123]
	v_pk_mul_f32 v[118:119], v[178:179], v[182:183]
	v_cvt_pk_bf16_f32 v122, v122, v123
	v_cvt_pk_bf16_f32 v123, v124, v125
	v_pk_mul_f32 v[124:125], v[180:181], v[140:141]
	global_store_dwordx2 v[138:139], v[122:123], off offset:1024 nt
	v_lshlrev_b32_e32 v134, 16, v122
	v_and_b32_e32 v135, 0xffff0000, v122
	v_lshlrev_b32_e32 v136, 16, v123
	v_and_b32_e32 v137, 0xffff0000, v123
	v_pk_mul_f32 v[122:123], v[112:113], 0.5 op_sel_hi:[1,0]
	v_pk_mul_f32 v[124:125], v[24:25], v[124:125]
	v_pk_mul_f32 v[118:119], v[22:23], v[118:119]
	v_pk_fma_f32 v[128:129], v[122:123], v[124:125], v[128:129]
	v_pk_fma_f32 v[126:127], v[184:185], v[118:119], v[126:127]
	s_nop 0
	v_cvt_pk_bf16_f32 v126, v126, v127
	v_cvt_pk_bf16_f32 v127, v128, v129
	global_store_dwordx2 v[138:139], v[126:127], off offset:1536 nt
	v_lshlrev_b32_e32 v138, 16, v126
	v_and_b32_e32 v139, 0xffff0000, v126
	v_lshlrev_b32_e32 v140, 16, v127
	v_and_b32_e32 v141, 0xffff0000, v127
	s_branch .LBB0_1212

; #define GAS __attribute__((address_space(1)))
; DI unsigned pk2(float lo, float hi) { f32x2_t v = {lo, hi}; bf16x2_t b = __builtin_convertvector(v, bf16x2_t); return __builtin_bit_cast(unsigned, b); }
; DI void phase_e(const Ctx& C, int nslab, int has_post, int pl, int ps, float pw, int has_pre, int ql, int qs, int nrows,
;                 const GAS float* xsrc, const GAS float* csrc, GAS float* xdst, GAS float* cdst, bool xs16, bool xd16) {
;     ...
;         if (has_pre) {
;             float ss = 0.f;
; #pragma unroll
;             for (int j = 0; j < 4; ++j) ss += (v[j][0] * v[j][0] + v[j][1] * v[j][1]) + (v[j][2] * v[j][2] + v[j][3] * v[j][3]);
;             const float r = rsqrtf(wave_sum(ss) * (1.0f / 1024.0f) + EPS);
; #pragma unroll
;             for (int j = 0; j < 4; ++j) { const f32x4 h = ((v[j] * r) * gpr[j]) * (1.0f + sc[j]) + sh[j];
;                 u32x2 w; w.x = pk2(h[0], h[1]); w.y = pk2(h[2], h[3]); *(GAS u32x2*)(H + (size_t)row * 1024 + 256 * j + 4 * lane) = w; }
;         }
.LBB0_1480:
	v_pk_mul_f32 v[122:123], v[116:117], v[116:117]
	v_pk_mul_f32 v[124:125], v[114:115], v[114:115]
	v_pk_mul_f32 v[126:127], v[132:133], v[132:133]
	v_pk_mul_f32 v[128:129], v[130:131], v[130:131]
	v_pk_mov_b32 v[118:119], v[124:125], v[122:123] op_sel:[1,0]
	v_mov_b32_e32 v125, v123
	v_pk_add_f32 v[122:123], v[118:119], v[124:125]
	v_pk_mov_b32 v[124:125], v[128:129], v[126:127] op_sel:[1,0]
	v_mov_b32_e32 v129, v127
	v_pk_add_f32 v[126:127], v[124:125], v[128:129]
	v_pk_add_f32 v[122:123], v[122:123], v[122:123] op_sel_hi:[0,1]
	v_pk_add_f32 v[126:127], v[126:127], v[126:127] op_sel_hi:[0,1]
	v_mul_f32_e32 v126, v134, v134
	v_pk_fma_f32 v[128:129], v[134:135], v[134:135], v[126:127] op_sel_hi:[1,1,0]
	v_mul_f32_e32 v126, v136, v136
	v_pk_fma_f32 v[124:125], v[136:137], v[136:137], v[126:127] op_sel_hi:[1,1,0]
	v_mul_f32_e32 v128, v138, v138
	v_mul_f32_e32 v124, v139, v139
	v_mul_f32_e32 v122, v140, v140
	v_mul_f32_e32 v126, v141, v141
	v_pk_add_f32 v[128:129], v[128:129], v[124:125]
	v_pk_add_f32 v[126:127], v[122:123], v[126:127]
	v_pk_add_f32 v[122:123], v[66:67], 1.0 op_sel_hi:[1,0]
	v_pk_add_f32 v[126:127], v[128:129], v[126:127]
	v_pk_add_f32 v[128:129], v[68:69], 1.0 op_sel_hi:[1,0]
	v_add_f32_e32 v126, v126, v127
	s_nop 1
	v_add_f32_dpp v126, v126, v126 quad_perm:[1,0,3,2] row_mask:0xf bank_mask:0xf
	s_nop 1
	v_add_f32_dpp v126, v126, v126 quad_perm:[2,3,0,1] row_mask:0xf bank_mask:0xf
	s_nop 1
	v_add_f32_dpp v126, v126, v126 row_half_mirror row_mask:0xf bank_mask:0xf
	s_nop 1
	v_add_f32_dpp v126, v126, v126 row_mirror row_mask:0xf bank_mask:0xf
	s_nop 1
	v_add_f32_dpp v126, v126, v126 row_bcast:15 row_mask:0xa bank_mask:0xf
	s_nop 1
	v_add_f32_dpp v126, v126, v126 row_bcast:31 row_mask:0xc bank_mask:0xf
	s_nop 0
	v_readlane_b32 s64, v126, 63
	s_nop 1
	v_mov_b32_e32 v126, s64
	s_waitcnt lgkmcnt(0)
	s_add_i32 s0, s23, 8
	s_add_i32 s1, s23, -8
	s_cmp_lt_i32 s1, s17
	s_mov_b32 s23, s0
	v_mov_b64_e32 v[170:171], v[144:145]
	s_waitcnt vmcnt(3)
	v_mov_b64_e32 v[144:145], v[162:163]
	v_fmamk_f32 v126, v126, 0x3a800000, v196
	v_mul_f32_e32 v127, 0x4b800000, v126
	v_cmp_gt_f32_e32 vcc, s27, v126
	s_nop 1
	v_cndmask_b32_e32 v126, v126, v127, vcc
	v_rsq_f32_e32 v124, v126
	v_lshl_add_u64 v[126:127], v[158:159], 0, s[2:3]
	v_mul_f32_e32 v125, 0x45800000, v124
	v_cndmask_b32_e32 v124, v124, v125, vcc
	v_pk_mul_f32 v[118:119], v[116:117], v[124:125] op_sel_hi:[1,0]
	v_pk_mul_f32 v[120:121], v[114:115], v[124:125] op_sel_hi:[1,0]
	v_pk_mul_f32 v[118:119], v[12:13], v[118:119]
	v_pk_mul_f32 v[120:121], v[10:11], v[120:121]
	v_pk_fma_f32 v[128:129], v[128:129], v[118:119], v[72:73]
	v_pk_fma_f32 v[122:123], v[122:123], v[120:121], v[70:71]
	v_pk_mul_f32 v[114:115], v[132:133], v[124:125] op_sel_hi:[1,0]
	v_pk_mul_f32 v[116:117], v[130:131], v[124:125] op_sel_hi:[1,0]
	v_cvt_pk_bf16_f32 v122, v122, v123
	v_cvt_pk_bf16_f32 v123, v128, v129
	v_pk_mul_f32 v[116:117], v[14:15], v[116:117]
	global_store_dwordx2 v[126:127], v[122:123], off
	v_pk_mul_f32 v[128:129], v[16:17], v[114:115]
	v_pk_add_f32 v[122:123], v[76:77], 1.0 op_sel_hi:[1,0]
	v_pk_add_f32 v[118:119], v[74:75], 1.0 op_sel_hi:[1,0]
	v_pk_fma_f32 v[128:129], v[122:123], v[128:129], v[80:81]
	v_pk_fma_f32 v[122:123], v[118:119], v[116:117], v[78:79]
	v_pk_add_f32 v[118:119], v[84:85], 1.0 op_sel_hi:[1,0]
	v_cvt_pk_bf16_f32 v122, v122, v123
	v_cvt_pk_bf16_f32 v123, v128, v129
	global_store_dwordx2 v[126:127], v[122:123], off offset:512
	v_pk_mul_f32 v[128:129], v[136:137], v[124:125] op_sel_hi:[1,0]
	v_pk_mul_f32 v[122:123], v[134:135], v[124:125] op_sel_hi:[1,0]
	v_pk_mul_f32 v[128:129], v[28:29], v[128:129]
	v_pk_mul_f32 v[122:123], v[26:27], v[122:123]
	v_pk_add_f32 v[120:121], v[82:83], 1.0 op_sel_hi:[1,0]
	s_waitcnt vmcnt(3)
	v_pk_fma_f32 v[128:129], v[118:119], v[128:129], v[92:93]
	v_pk_fma_f32 v[122:123], v[120:121], v[122:123], v[90:91]
	v_pk_add_f32 v[118:119], v[62:63], 1.0 op_sel_hi:[1,0]
	v_cvt_pk_bf16_f32 v122, v122, v123
	v_cvt_pk_bf16_f32 v123, v128, v129
	global_store_dwordx2 v[126:127], v[122:123], off offset:1024
	v_pk_mul_f32 v[128:129], v[140:141], v[124:125] op_sel_hi:[1,0]
	v_pk_mul_f32 v[122:123], v[138:139], v[124:125] op_sel_hi:[1,0]
	v_pk_mul_f32 v[128:129], v[32:33], v[128:129]
	v_pk_mul_f32 v[122:123], v[30:31], v[122:123]
	v_pk_add_f32 v[124:125], v[64:65], 1.0 op_sel_hi:[1,0]
	s_waitcnt vmcnt(3)
	v_pk_fma_f32 v[122:123], v[118:119], v[122:123], v[86:87]
	v_pk_fma_f32 v[128:129], v[124:125], v[128:129], v[88:89]
	v_cvt_pk_bf16_f32 v122, v122, v123
	v_cvt_pk_bf16_f32 v123, v128, v129
	global_store_dwordx2 v[126:127], v[122:123], off offset:1536
	s_mov_b64 vcc, s[98:99]
	s_cbranch_vccz .Leload_skip_2_u2
	s_waitcnt vmcnt(8)
	v_lshlrev_b32_e32 v34, 16, v36
	v_and_b32_e32 v35, 0xffff0000, v36
	v_lshlrev_b32_e32 v36, 16, v37
	v_and_b32_e32 v37, 0xffff0000, v37
	v_lshlrev_b32_e32 v38, 16, v40
	v_and_b32_e32 v39, 0xffff0000, v40
	v_lshlrev_b32_e32 v40, 16, v41
	v_and_b32_e32 v41, 0xffff0000, v41
	v_lshlrev_b32_e32 v42, 16, v44
	v_and_b32_e32 v43, 0xffff0000, v44
	v_lshlrev_b32_e32 v44, 16, v45
	v_and_b32_e32 v45, 0xffff0000, v45
	v_lshlrev_b32_e32 v50, 16, v52
	v_and_b32_e32 v51, 0xffff0000, v52
	v_lshlrev_b32_e32 v52, 16, v53
	v_and_b32_e32 v53, 0xffff0000, v53

; #define GAS __attribute__((address_space(1)))
; DI unsigned pk2(float lo, float hi) { f32x2_t v = {lo, hi}; bf16x2_t b = __builtin_convertvector(v, bf16x2_t); return __builtin_bit_cast(unsigned, b); }
; DI float bflo(unsigned w) { return __uint_as_float(w << 16); }
; DI float bfhi(unsigned w) { return __uint_as_float(w & 0xffff0000u); }
; DI void phase_e(const Ctx& C, int nslab, int has_post, int pl, int ps, float pw, int has_pre, int ql, int qs, int nrows,
;                 const GAS float* xsrc, const GAS float* csrc, GAS float* xdst, GAS float* cdst, bool xs16, bool xd16) {
;     ...
;             if (isx && xd16) { GAS bf16* d16 = (GAS bf16*)xdst + (size_t)row * 1024;
; #pragma unroll
;                 for (int j = 0; j < 4; ++j) { v[j] += pw * gt[j] * ((y[j] * r) * gpo[j]); u32x2 w; w.x = pk2(v[j][0], v[j][1]); w.y = pk2(v[j][2], v[j][3]); __builtin_nontemporal_store(w, (GAS u32x2*)(d16 + 256 * j + 4 * lane));
;                     v[j] = (f32x4){bflo(w.x), bfhi(w.x), bflo(w.y), bfhi(w.y)}; }
.LBB0_1508:
	s_andn2_b64 vcc, exec, s[12:13]
	s_cbranch_vccnz .LBB0_1480_u0
	s_lshl_b64 s[2:3], s[10:11], 11
	v_mov_b32_e32 v140, v182
	v_mov_b32_e32 v141, v182
	v_lshl_add_u64 v[138:139], v[152:153], 0, s[2:3]
	v_cvt_pk_bf16_f32 v130, v98, v99
	v_cvt_pk_bf16_f32 v131, v100, v101
	v_pk_mul_f32 v[132:133], v[172:173], v[140:141]
	v_pk_mul_f32 v[134:135], v[170:171], v[182:183]
	global_store_dwordx2 v[138:139], v[130:131], off nt
	v_lshlrev_b32_e32 v98, 16, v130
	v_and_b32_e32 v99, 0xffff0000, v130
	v_lshlrev_b32_e32 v100, 16, v131
	v_and_b32_e32 v101, 0xffff0000, v131
	v_pk_mul_f32 v[130:131], v[104:105], 0.5 op_sel_hi:[1,0]
	v_pk_mul_f32 v[132:133], v[8:9], v[132:133]
	v_pk_mul_f32 v[134:135], v[6:7], v[134:135]
	v_pk_fma_f32 v[60:61], v[130:131], v[132:133], v[60:61]
	v_pk_fma_f32 v[58:59], v[188:189], v[134:135], v[58:59]
	v_pk_mul_f32 v[134:135], v[174:175], v[182:183]
	v_cvt_pk_bf16_f32 v58, v58, v59
	v_cvt_pk_bf16_f32 v59, v60, v61
	v_pk_mul_f32 v[60:61], v[176:177], v[140:141]
	global_store_dwordx2 v[138:139], v[58:59], off offset:512 nt
	v_lshlrev_b32_e32 v130, 16, v58
	v_and_b32_e32 v131, 0xffff0000, v58
	v_lshlrev_b32_e32 v132, 16, v59
	v_and_b32_e32 v133, 0xffff0000, v59
	v_pk_mul_f32 v[58:59], v[108:109], 0.5 op_sel_hi:[1,0]
	v_pk_mul_f32 v[60:61], v[20:21], v[60:61]
	v_pk_mul_f32 v[134:135], v[18:19], v[134:135]
	v_pk_fma_f32 v[56:57], v[58:59], v[60:61], v[56:57]
	v_pk_fma_f32 v[54:55], v[186:187], v[134:135], v[54:55]
	v_pk_mul_f32 v[58:59], v[178:179], v[182:183]
	v_cvt_pk_bf16_f32 v54, v54, v55
	v_cvt_pk_bf16_f32 v55, v56, v57
	v_pk_mul_f32 v[56:57], v[180:181], v[140:141]
	global_store_dwordx2 v[138:139], v[54:55], off offset:1024 nt
	v_lshlrev_b32_e32 v134, 16, v54
	v_and_b32_e32 v135, 0xffff0000, v54
	v_lshlrev_b32_e32 v136, 16, v55
	v_and_b32_e32 v137, 0xffff0000, v55
	v_pk_mul_f32 v[54:55], v[112:113], 0.5 op_sel_hi:[1,0]
	v_pk_mul_f32 v[56:57], v[24:25], v[56:57]
	v_pk_mul_f32 v[58:59], v[22:23], v[58:59]
	v_pk_fma_f32 v[48:49], v[54:55], v[56:57], v[48:49]
	v_pk_fma_f32 v[46:47], v[184:185], v[58:59], v[46:47]
	s_nop 0
	v_cvt_pk_bf16_f32 v46, v46, v47
	v_cvt_pk_bf16_f32 v47, v48, v49
	global_store_dwordx2 v[138:139], v[46:47], off offset:1536 nt
	v_lshlrev_b32_e32 v138, 16, v46
	v_and_b32_e32 v139, 0xffff0000, v46
	v_lshlrev_b32_e32 v140, 16, v47
	v_and_b32_e32 v141, 0xffff0000, v47
	s_branch .LBB0_1480_u0
; #define GAS __attribute__((address_space(1)))
; DI unsigned pk2(float lo, float hi) { f32x2_t v = {lo, hi}; bf16x2_t b = __builtin_convertvector(v, bf16x2_t); return __builtin_bit_cast(unsigned, b); }
; DI void phase_e(const Ctx& C, int nslab, int has_post, int pl, int ps, float pw, int has_pre, int ql, int qs, int nrows,
;                 const GAS float* xsrc, const GAS float* csrc, GAS float* xdst, GAS float* cdst, bool xs16, bool xd16) {
;     ...
;         if (has_pre) {
;             float ss = 0.f;
; #pragma unroll
;             for (int j = 0; j < 4; ++j) ss += (v[j][0] * v[j][0] + v[j][1] * v[j][1]) + (v[j][2] * v[j][2] + v[j][3] * v[j][3]);
;             const float r = rsqrtf(wave_sum(ss) * (1.0f / 1024.0f) + EPS);
; #pragma unroll
;             for (int j = 0; j < 4; ++j) { const f32x4 h = ((v[j] * r) * gpr[j]) * (1.0f + sc[j]) + sh[j];
;                 u32x2 w; w.x = pk2(h[0], h[1]); w.y = pk2(h[2], h[3]); *(GAS u32x2*)(H + (size_t)row * 1024 + 256 * j + 4 * lane) = w; }
;         }
.LBB0_1480_u0:
	v_pk_mul_f32 v[54:55], v[100:101], v[100:101]
	v_pk_mul_f32 v[56:57], v[98:99], v[98:99]
	v_pk_mul_f32 v[46:47], v[132:133], v[132:133]
	v_pk_mul_f32 v[48:49], v[130:131], v[130:131]
	v_pk_mov_b32 v[58:59], v[56:57], v[54:55] op_sel:[1,0]
	v_mov_b32_e32 v57, v55
	v_pk_add_f32 v[54:55], v[58:59], v[56:57]
	v_pk_mov_b32 v[56:57], v[48:49], v[46:47] op_sel:[1,0]
	v_mov_b32_e32 v49, v47
	v_pk_add_f32 v[46:47], v[56:57], v[48:49]
	v_pk_add_f32 v[54:55], v[54:55], v[54:55] op_sel_hi:[0,1]
	v_pk_add_f32 v[46:47], v[46:47], v[46:47] op_sel_hi:[0,1]
	v_mul_f32_e32 v46, v134, v134
	v_pk_fma_f32 v[48:49], v[134:135], v[134:135], v[46:47] op_sel_hi:[1,1,0]
	v_mul_f32_e32 v46, v136, v136
	v_pk_fma_f32 v[56:57], v[136:137], v[136:137], v[46:47] op_sel_hi:[1,1,0]
	v_mul_f32_e32 v48, v138, v138
	v_mul_f32_e32 v56, v139, v139
	v_mul_f32_e32 v54, v140, v140
	v_mul_f32_e32 v46, v141, v141
	v_pk_add_f32 v[48:49], v[48:49], v[56:57]
	v_pk_add_f32 v[46:47], v[54:55], v[46:47]
	v_pk_add_f32 v[54:55], v[66:67], 1.0 op_sel_hi:[1,0]
	v_pk_add_f32 v[46:47], v[48:49], v[46:47]
	v_pk_add_f32 v[48:49], v[68:69], 1.0 op_sel_hi:[1,0]
	v_add_f32_e32 v46, v46, v47
	s_nop 1
	v_add_f32_dpp v46, v46, v46 quad_perm:[1,0,3,2] row_mask:0xf bank_mask:0xf
	s_nop 1
	v_add_f32_dpp v46, v46, v46 quad_perm:[2,3,0,1] row_mask:0xf bank_mask:0xf
	s_nop 1
	v_add_f32_dpp v46, v46, v46 row_half_mirror row_mask:0xf bank_mask:0xf
	s_nop 1
	v_add_f32_dpp v46, v46, v46 row_mirror row_mask:0xf bank_mask:0xf
	s_nop 1
	v_add_f32_dpp v46, v46, v46 row_bcast:15 row_mask:0xa bank_mask:0xf
	s_nop 1
	v_add_f32_dpp v46, v46, v46 row_bcast:31 row_mask:0xc bank_mask:0xf
	s_nop 0
	v_readlane_b32 s64, v46, 63
	s_nop 1
	v_mov_b32_e32 v46, s64
	s_waitcnt lgkmcnt(0)
	s_add_i32 s0, s23, 8
	s_add_i32 s1, s23, -8
	s_cmp_lt_i32 s1, s17
	s_mov_b32 s23, s0
	v_mov_b64_e32 v[170:171], v[144:145]
	s_waitcnt vmcnt(3)
	v_mov_b64_e32 v[144:145], v[162:163]
	v_fmamk_f32 v46, v46, 0x3a800000, v196
	v_mul_f32_e32 v47, 0x4b800000, v46
	v_cmp_gt_f32_e32 vcc, s27, v46
	s_nop 1
	v_cndmask_b32_e32 v46, v46, v47, vcc
	v_rsq_f32_e32 v56, v46
	v_lshl_add_u64 v[46:47], v[158:159], 0, s[2:3]
	v_mul_f32_e32 v57, 0x45800000, v56
	v_cndmask_b32_e32 v56, v56, v57, vcc
	v_pk_mul_f32 v[58:59], v[100:101], v[56:57] op_sel_hi:[1,0]
	v_pk_mul_f32 v[60:61], v[98:99], v[56:57] op_sel_hi:[1,0]
	v_pk_mul_f32 v[58:59], v[12:13], v[58:59]
	v_pk_mul_f32 v[60:61], v[10:11], v[60:61]
	v_pk_fma_f32 v[48:49], v[48:49], v[58:59], v[72:73]
	v_pk_fma_f32 v[54:55], v[54:55], v[60:61], v[70:71]
	v_pk_mul_f32 v[98:99], v[132:133], v[56:57] op_sel_hi:[1,0]
	v_pk_mul_f32 v[100:101], v[130:131], v[56:57] op_sel_hi:[1,0]
	v_cvt_pk_bf16_f32 v54, v54, v55
	v_cvt_pk_bf16_f32 v55, v48, v49
	v_pk_mul_f32 v[100:101], v[14:15], v[100:101]
	global_store_dwordx2 v[46:47], v[54:55], off
	v_pk_mul_f32 v[48:49], v[16:17], v[98:99]
	v_pk_add_f32 v[54:55], v[76:77], 1.0 op_sel_hi:[1,0]
	v_pk_add_f32 v[58:59], v[74:75], 1.0 op_sel_hi:[1,0]
	v_pk_fma_f32 v[48:49], v[54:55], v[48:49], v[80:81]
	v_pk_fma_f32 v[54:55], v[58:59], v[100:101], v[78:79]
	v_pk_add_f32 v[58:59], v[84:85], 1.0 op_sel_hi:[1,0]
	v_cvt_pk_bf16_f32 v54, v54, v55
	v_cvt_pk_bf16_f32 v55, v48, v49
	global_store_dwordx2 v[46:47], v[54:55], off offset:512
	v_pk_mul_f32 v[48:49], v[136:137], v[56:57] op_sel_hi:[1,0]
	v_pk_mul_f32 v[54:55], v[134:135], v[56:57] op_sel_hi:[1,0]
	v_pk_mul_f32 v[48:49], v[28:29], v[48:49]
	v_pk_mul_f32 v[54:55], v[26:27], v[54:55]
	v_pk_add_f32 v[60:61], v[82:83], 1.0 op_sel_hi:[1,0]
	s_waitcnt vmcnt(3)
	v_pk_fma_f32 v[48:49], v[58:59], v[48:49], v[92:93]
	v_pk_fma_f32 v[54:55], v[60:61], v[54:55], v[90:91]
	v_pk_add_f32 v[58:59], v[62:63], 1.0 op_sel_hi:[1,0]
	v_cvt_pk_bf16_f32 v54, v54, v55
	v_cvt_pk_bf16_f32 v55, v48, v49
	global_store_dwordx2 v[46:47], v[54:55], off offset:1024
	v_pk_mul_f32 v[48:49], v[140:141], v[56:57] op_sel_hi:[1,0]
	v_pk_mul_f32 v[54:55], v[138:139], v[56:57] op_sel_hi:[1,0]
	v_pk_mul_f32 v[48:49], v[32:33], v[48:49]
	v_pk_mul_f32 v[54:55], v[30:31], v[54:55]
	v_pk_add_f32 v[56:57], v[64:65], 1.0 op_sel_hi:[1,0]
	s_waitcnt vmcnt(3)
	v_pk_fma_f32 v[54:55], v[58:59], v[54:55], v[86:87]
	v_pk_fma_f32 v[48:49], v[56:57], v[48:49], v[88:89]
	v_cvt_pk_bf16_f32 v54, v54, v55
	v_cvt_pk_bf16_f32 v55, v48, v49
	global_store_dwordx2 v[46:47], v[54:55], off offset:1536
	s_mov_b64 vcc, s[98:99]
	s_cbranch_vccz .Leload_skip_2
	s_waitcnt vmcnt(8)
	v_lshlrev_b32_e32 v114, 16, v116
	v_and_b32_e32 v115, 0xffff0000, v116
	v_lshlrev_b32_e32 v116, 16, v117
	v_and_b32_e32 v117, 0xffff0000, v117
	v_lshlrev_b32_e32 v118, 16, v120
	v_and_b32_e32 v119, 0xffff0000, v120
	v_lshlrev_b32_e32 v120, 16, v121
	v_and_b32_e32 v121, 0xffff0000, v121
	v_lshlrev_b32_e32 v122, 16, v124
	v_and_b32_e32 v123, 0xffff0000, v124
	v_lshlrev_b32_e32 v124, 16, v125
	v_and_b32_e32 v125, 0xffff0000, v125
	v_lshlrev_b32_e32 v126, 16, v128
	v_and_b32_e32 v127, 0xffff0000, v128
	v_lshlrev_b32_e32 v128, 16, v129
	v_and_b32_e32 v129, 0xffff0000, v129

.LBB0_1481_u1:
	s_mov_b64 s[98:99], 0
	s_cmp_ge_i32 s23, s17
	s_cbranch_scc1 .LBB0_1488_u1
	s_add_i32 s1, s22, s23
	s_add_i32 s0, s21, s23
	s_add_i32 s1, s1, 0x8000
	s_cmp_lt_i32 s23, s16
	s_cselect_b32 s0, s0, s1
	s_cmp_lt_i32 s0, 0x8000
	s_cselect_b64 s[2:3], -1, 0
	s_cmpk_gt_i32 s0, 0x7fff
	s_mov_b64 s[10:11], -1
	s_cbranch_scc0 .LBB0_1484_u1
	s_add_i32 s4, s0, 0xffff8000
	s_lshl_b64 s[10:11], s[4:5], 12
	v_lshl_add_u64 v[46:47], v[160:161], 0, s[10:11]
	global_load_dwordx4 v[98:101], v[46:47], off nt
	global_load_dwordx4 v[58:61], v[46:47], off offset:1024 nt
	global_load_dwordx4 v[54:57], v[46:47], off offset:2048 nt
	s_nop 0
	global_load_dwordx4 v[46:49], v[46:47], off offset:3072 nt
	s_mov_b64 s[10:11], 0

; #define GAS __attribute__((address_space(1)))
; DI unsigned pk2(float lo, float hi) { f32x2_t v = {lo, hi}; bf16x2_t b = __builtin_convertvector(v, bf16x2_t); return __builtin_bit_cast(unsigned, b); }
; DI float bflo(unsigned w) { return __uint_as_float(w << 16); }
; DI float bfhi(unsigned w) { return __uint_as_float(w & 0xffff0000u); }
; DI void phase_e(const Ctx& C, int nslab, int has_post, int pl, int ps, float pw, int has_pre, int ql, int qs, int nrows,
;                 const GAS float* xsrc, const GAS float* csrc, GAS float* xdst, GAS float* cdst, bool xs16, bool xd16) {
;     ...
;         if (has_post) {
;             f32x4 y[4]; float ss = 0.f;
; #pragma unroll
;             for (int j = 0; j < 4; ++j) {
;                 if (isx || nslab == 0) { y[j] = (f32x4){bflo(yw[j].x), bfhi(yw[j].x), bflo(yw[j].y), bfhi(yw[j].y)}; }
;                 else { y[j] = (f32x4){0.f, 0.f, 0.f, 0.f};
;                     for (int s = 0; s < nslab; ++s) { const u32x2 w = *(const GAS u32x2*)(YS + ((size_t)s * MC + (row - MX)) * 1024 + 256 * j + 4 * lane); y[j] += (f32x4){bflo(w.x), bfhi(w.x), bflo(w.y), bfhi(w.y)}; } }
;                 ss += (y[j][0] * y[j][0] + y[j][1] * y[j][1]) + (y[j][2] * y[j][2] + y[j][3] * y[j][3]); }
;             const float r = rsqrtf(wave_sum(ss) * (1.0f / 1024.0f) + EPS);
;             if (isx && xd16) { GAS bf16* d16 = (GAS bf16*)xdst + (size_t)row * 1024;
; #pragma unroll
;                 for (int j = 0; j < 4; ++j) { v[j] += pw * gt[j] * ((y[j] * r) * gpo[j]); u32x2 w; w.x = pk2(v[j][0], v[j][1]); w.y = pk2(v[j][2], v[j][3]); __builtin_nontemporal_store(w, (GAS u32x2*)(d16 + 256 * j + 4 * lane));
;                     v[j] = (f32x4){bflo(w.x), bfhi(w.x), bflo(w.y), bfhi(w.y)}; }
;             } else { GAS float* dst = isx ? xdst + (size_t)row * 1024 : cdst + (size_t)(row - MX) * 1024;
; #pragma unroll
;                 for (int j = 0; j < 4; ++j) { v[j] += pw * gt[j] * ((y[j] * r) * gpo[j]); __builtin_nontemporal_store(v[j], (GAS f32x4*)(dst + 256 * j + 4 * lane)); } }
.LBB0_1506_u1:
	v_mul_f32_e32 v130, v141, v141
	v_mul_f32_e32 v131, v139, v139
	v_fmac_f32_e32 v130, v140, v140
	v_fmac_f32_e32 v131, v138, v138
	v_add_f32_e32 v130, v130, v131
	v_mul_f32_e32 v131, v171, v171
	v_mul_f32_e32 v132, v173, v173
	v_fmac_f32_e32 v131, v170, v170
	v_fmac_f32_e32 v132, v172, v172
	v_add_f32_e32 v131, v131, v132
	v_add_f32_e32 v130, v130, v131
	v_mul_f32_e32 v131, v175, v175
	v_mul_f32_e32 v132, v177, v177
	v_fmac_f32_e32 v131, v174, v174
	v_fmac_f32_e32 v132, v176, v176
	v_add_f32_e32 v131, v131, v132
	v_add_f32_e32 v136, v130, v131
	v_pk_mul_f32 v[130:131], v[180:181], v[180:181]
	v_pk_mul_f32 v[132:133], v[178:179], v[178:179]
	s_and_b64 s[0:1], exec, s[0:1]
	v_pk_mov_b32 v[134:135], v[132:133], v[130:131] op_sel:[1,0]
	v_mov_b32_e32 v133, v131
	v_pk_add_f32 v[130:131], v[134:135], v[132:133]
	s_ashr_i32 s11, s10, 31
	v_add_f32_e32 v130, v130, v131
	v_add_f32_e32 v130, v136, v130
	s_nop 1
	v_add_f32_dpp v130, v130, v130 quad_perm:[1,0,3,2] row_mask:0xf bank_mask:0xf
	s_nop 1
	v_add_f32_dpp v130, v130, v130 quad_perm:[2,3,0,1] row_mask:0xf bank_mask:0xf
	s_nop 1
	v_add_f32_dpp v130, v130, v130 row_half_mirror row_mask:0xf bank_mask:0xf
	s_nop 1
	v_add_f32_dpp v130, v130, v130 row_mirror row_mask:0xf bank_mask:0xf
	s_nop 1
	v_add_f32_dpp v130, v130, v130 row_bcast:15 row_mask:0xa bank_mask:0xf
	s_nop 1
	v_add_f32_dpp v130, v130, v130 row_bcast:31 row_mask:0xc bank_mask:0xf
	s_nop 0
	v_readlane_b32 s64, v130, 63
	s_nop 1
	v_mov_b32_e32 v132, s64
	s_waitcnt lgkmcnt(0)
	s_mov_b64 s[12:13], -1
	s_waitcnt vmcnt(7)
	v_pk_mul_f32 v[188:189], v[102:103], 0.5 op_sel_hi:[1,0]
	s_waitcnt vmcnt(6)
	v_pk_mul_f32 v[186:187], v[106:107], 0.5 op_sel_hi:[1,0]
	s_waitcnt vmcnt(4)
	v_pk_mul_f32 v[184:185], v[110:111], 0.5 op_sel_hi:[1,0]
	v_pk_mul_f32 v[130:131], v[96:97], 0.5 op_sel_hi:[1,0]
	v_fmamk_f32 v132, v132, 0x3a800000, v196
	v_mul_f32_e32 v133, 0x4b800000, v132
	v_cmp_gt_f32_e32 vcc, s27, v132
	s_nop 1
	v_cndmask_b32_e32 v132, v132, v133, vcc
	v_rsq_f32_e32 v134, v132
	v_pk_mul_f32 v[132:133], v[94:95], 0.5 op_sel_hi:[1,0]
	v_mul_f32_e32 v135, 0x45800000, v134
	v_cndmask_b32_e32 v182, v134, v135, vcc
	v_mov_b32_e32 v183, v182
	v_pk_mul_f32 v[134:135], v[138:139], v[182:183] op_sel_hi:[1,0]
	v_pk_mul_f32 v[136:137], v[140:141], v[182:183] op_sel_hi:[1,0]
	v_pk_mul_f32 v[134:135], v[4:5], v[134:135]
	v_pk_mul_f32 v[136:137], v[2:3], v[136:137]
	v_pk_fma_f32 v[36:37], v[130:131], v[134:135], v[36:37]
	v_pk_fma_f32 v[34:35], v[132:133], v[136:137], v[34:35]
	s_mov_b64 vcc, s[0:1]
	s_cbranch_vccz .LBB0_1508_u1
	v_mov_b32_e32 v138, v182
	v_mov_b32_e32 v139, v182
	v_pk_mul_f32 v[132:133], v[172:173], v[138:139]
	v_pk_mul_f32 v[134:135], v[170:171], v[182:183]
	v_pk_mul_f32 v[130:131], v[104:105], 0.5 op_sel_hi:[1,0]
	v_pk_mul_f32 v[132:133], v[8:9], v[132:133]
	v_pk_mul_f32 v[134:135], v[6:7], v[134:135]
	v_pk_mul_f32 v[136:137], v[176:177], v[138:139]
	v_pk_mul_f32 v[140:141], v[174:175], v[182:183]
	v_pk_fma_f32 v[132:133], v[130:131], v[132:133], v[40:41]
	v_pk_fma_f32 v[130:131], v[188:189], v[134:135], v[38:39]
	v_pk_mul_f32 v[134:135], v[108:109], 0.5 op_sel_hi:[1,0]
	v_pk_mul_f32 v[136:137], v[20:21], v[136:137]
	v_pk_mul_f32 v[140:141], v[18:19], v[140:141]
	v_pk_mul_f32 v[138:139], v[180:181], v[138:139]
	v_pk_mul_f32 v[200:201], v[178:179], v[182:183]
	s_lshl_b64 s[0:1], s[4:5], 12
	v_pk_fma_f32 v[136:137], v[134:135], v[136:137], v[44:45]
	v_pk_fma_f32 v[134:135], v[186:187], v[140:141], v[42:43]
	v_pk_mul_f32 v[140:141], v[112:113], 0.5 op_sel_hi:[1,0]
	v_pk_mul_f32 v[138:139], v[24:25], v[138:139]
	v_pk_mul_f32 v[200:201], v[22:23], v[200:201]
	v_lshl_add_u64 v[198:199], v[160:161], 0, s[0:1]
	v_pk_fma_f32 v[140:141], v[140:141], v[138:139], v[52:53]
	v_pk_fma_f32 v[138:139], v[184:185], v[200:201], v[50:51]
	global_store_dwordx4 v[198:199], v[34:37], off nt
	global_store_dwordx4 v[198:199], v[130:133], off offset:1024 nt
	global_store_dwordx4 v[198:199], v[134:137], off offset:2048 nt
	global_store_dwordx4 v[198:199], v[138:141], off offset:3072 nt
	s_lshl_b64 s[2:3], s[10:11], 11
	s_mov_b64 s[12:13], 0

; #define GAS __attribute__((address_space(1)))
; DI unsigned pk2(float lo, float hi) { f32x2_t v = {lo, hi}; bf16x2_t b = __builtin_convertvector(v, bf16x2_t); return __builtin_bit_cast(unsigned, b); }
; DI void phase_e(const Ctx& C, int nslab, int has_post, int pl, int ps, float pw, int has_pre, int ql, int qs, int nrows,
;                 const GAS float* xsrc, const GAS float* csrc, GAS float* xdst, GAS float* cdst, bool xs16, bool xd16) {
;     ...
;         if (has_pre) {
;             float ss = 0.f;
; #pragma unroll
;             for (int j = 0; j < 4; ++j) ss += (v[j][0] * v[j][0] + v[j][1] * v[j][1]) + (v[j][2] * v[j][2] + v[j][3] * v[j][3]);
;             const float r = rsqrtf(wave_sum(ss) * (1.0f / 1024.0f) + EPS);
; #pragma unroll
;             for (int j = 0; j < 4; ++j) { const f32x4 h = ((v[j] * r) * gpr[j]) * (1.0f + sc[j]) + sh[j];
;                 u32x2 w; w.x = pk2(h[0], h[1]); w.y = pk2(h[2], h[3]); *(GAS u32x2*)(H + (size_t)row * 1024 + 256 * j + 4 * lane) = w; }
;         }
.LBB0_1480_u1:
	v_pk_mul_f32 v[42:43], v[36:37], v[36:37]
	v_pk_mul_f32 v[44:45], v[34:35], v[34:35]
	v_pk_mul_f32 v[50:51], v[132:133], v[132:133]
	v_pk_mul_f32 v[52:53], v[130:131], v[130:131]
	v_pk_mov_b32 v[38:39], v[44:45], v[42:43] op_sel:[1,0]
	v_mov_b32_e32 v45, v43
	v_pk_add_f32 v[42:43], v[38:39], v[44:45]
	v_pk_mov_b32 v[44:45], v[52:53], v[50:51] op_sel:[1,0]
	v_mov_b32_e32 v53, v51
	v_pk_add_f32 v[50:51], v[44:45], v[52:53]
	v_pk_add_f32 v[42:43], v[42:43], v[42:43] op_sel_hi:[0,1]
	v_pk_add_f32 v[50:51], v[50:51], v[50:51] op_sel_hi:[0,1]
	v_mul_f32_e32 v50, v134, v134
	v_pk_fma_f32 v[52:53], v[134:135], v[134:135], v[50:51] op_sel_hi:[1,1,0]
	v_mul_f32_e32 v50, v136, v136
	v_pk_fma_f32 v[44:45], v[136:137], v[136:137], v[50:51] op_sel_hi:[1,1,0]
	v_mul_f32_e32 v52, v138, v138
	v_mul_f32_e32 v44, v139, v139
	v_mul_f32_e32 v42, v140, v140
	v_mul_f32_e32 v50, v141, v141
	v_pk_add_f32 v[52:53], v[52:53], v[44:45]
	v_pk_add_f32 v[50:51], v[42:43], v[50:51]
	v_pk_add_f32 v[42:43], v[66:67], 1.0 op_sel_hi:[1,0]
	v_pk_add_f32 v[50:51], v[52:53], v[50:51]
	v_pk_add_f32 v[52:53], v[68:69], 1.0 op_sel_hi:[1,0]
	v_add_f32_e32 v50, v50, v51
	s_nop 1
	v_add_f32_dpp v50, v50, v50 quad_perm:[1,0,3,2] row_mask:0xf bank_mask:0xf
	s_nop 1
	v_add_f32_dpp v50, v50, v50 quad_perm:[2,3,0,1] row_mask:0xf bank_mask:0xf
	s_nop 1
	v_add_f32_dpp v50, v50, v50 row_half_mirror row_mask:0xf bank_mask:0xf
	s_nop 1
	v_add_f32_dpp v50, v50, v50 row_mirror row_mask:0xf bank_mask:0xf
	s_nop 1
	v_add_f32_dpp v50, v50, v50 row_bcast:15 row_mask:0xa bank_mask:0xf
	s_nop 1
	v_add_f32_dpp v50, v50, v50 row_bcast:31 row_mask:0xc bank_mask:0xf
	s_nop 0
	v_readlane_b32 s64, v50, 63
	s_nop 1
	v_mov_b32_e32 v50, s64
	s_waitcnt lgkmcnt(0)
	s_add_i32 s0, s23, 8
	s_add_i32 s1, s23, -8
	s_cmp_lt_i32 s1, s17
	s_mov_b32 s23, s0
	v_mov_b64_e32 v[170:171], v[144:145]
	s_waitcnt vmcnt(3)
	v_mov_b64_e32 v[144:145], v[162:163]
	v_fmamk_f32 v50, v50, 0x3a800000, v196
	v_mul_f32_e32 v51, 0x4b800000, v50
	v_cmp_gt_f32_e32 vcc, s27, v50
	s_nop 1
	v_cndmask_b32_e32 v50, v50, v51, vcc
	v_rsq_f32_e32 v44, v50
	v_lshl_add_u64 v[50:51], v[158:159], 0, s[2:3]
	v_mul_f32_e32 v45, 0x45800000, v44
	v_cndmask_b32_e32 v44, v44, v45, vcc
	v_pk_mul_f32 v[38:39], v[36:37], v[44:45] op_sel_hi:[1,0]
	v_pk_mul_f32 v[40:41], v[34:35], v[44:45] op_sel_hi:[1,0]
	v_pk_mul_f32 v[38:39], v[12:13], v[38:39]
	v_pk_mul_f32 v[40:41], v[10:11], v[40:41]
	v_pk_fma_f32 v[52:53], v[52:53], v[38:39], v[72:73]
	v_pk_fma_f32 v[42:43], v[42:43], v[40:41], v[70:71]
	v_pk_mul_f32 v[34:35], v[132:133], v[44:45] op_sel_hi:[1,0]
	v_pk_mul_f32 v[36:37], v[130:131], v[44:45] op_sel_hi:[1,0]
	v_cvt_pk_bf16_f32 v42, v42, v43
	v_cvt_pk_bf16_f32 v43, v52, v53
	v_pk_mul_f32 v[36:37], v[14:15], v[36:37]
	global_store_dwordx2 v[50:51], v[42:43], off
	v_pk_mul_f32 v[52:53], v[16:17], v[34:35]
	v_pk_add_f32 v[42:43], v[76:77], 1.0 op_sel_hi:[1,0]
	v_pk_add_f32 v[38:39], v[74:75], 1.0 op_sel_hi:[1,0]
	v_pk_fma_f32 v[52:53], v[42:43], v[52:53], v[80:81]
	v_pk_fma_f32 v[42:43], v[38:39], v[36:37], v[78:79]
	v_pk_add_f32 v[38:39], v[84:85], 1.0 op_sel_hi:[1,0]
	v_cvt_pk_bf16_f32 v42, v42, v43
	v_cvt_pk_bf16_f32 v43, v52, v53
	global_store_dwordx2 v[50:51], v[42:43], off offset:512
	v_pk_mul_f32 v[52:53], v[136:137], v[44:45] op_sel_hi:[1,0]
	v_pk_mul_f32 v[42:43], v[134:135], v[44:45] op_sel_hi:[1,0]
	v_pk_mul_f32 v[52:53], v[28:29], v[52:53]
	v_pk_mul_f32 v[42:43], v[26:27], v[42:43]
	v_pk_add_f32 v[40:41], v[82:83], 1.0 op_sel_hi:[1,0]
	s_waitcnt vmcnt(3)
	v_pk_fma_f32 v[52:53], v[38:39], v[52:53], v[92:93]
	v_pk_fma_f32 v[42:43], v[40:41], v[42:43], v[90:91]
	v_pk_add_f32 v[38:39], v[62:63], 1.0 op_sel_hi:[1,0]
	v_cvt_pk_bf16_f32 v42, v42, v43
	v_cvt_pk_bf16_f32 v43, v52, v53
	global_store_dwordx2 v[50:51], v[42:43], off offset:1024
	v_pk_mul_f32 v[52:53], v[140:141], v[44:45] op_sel_hi:[1,0]
	v_pk_mul_f32 v[42:43], v[138:139], v[44:45] op_sel_hi:[1,0]
	v_pk_mul_f32 v[52:53], v[32:33], v[52:53]
	v_pk_mul_f32 v[42:43], v[30:31], v[42:43]
	v_pk_add_f32 v[44:45], v[64:65], 1.0 op_sel_hi:[1,0]
	s_waitcnt vmcnt(3)
	v_pk_fma_f32 v[42:43], v[38:39], v[42:43], v[86:87]
	v_pk_fma_f32 v[52:53], v[44:45], v[52:53], v[88:89]
	v_cvt_pk_bf16_f32 v42, v42, v43
	v_cvt_pk_bf16_f32 v43, v52, v53
	global_store_dwordx2 v[50:51], v[42:43], off offset:1536
	s_mov_b64 vcc, s[98:99]
	s_cbranch_vccz .Leload_skip_2_u1
	s_waitcnt vmcnt(8)
	v_lshlrev_b32_e32 v98, 16, v100
	v_and_b32_e32 v99, 0xffff0000, v100
	v_lshlrev_b32_e32 v100, 16, v101
	v_and_b32_e32 v101, 0xffff0000, v101
	v_lshlrev_b32_e32 v58, 16, v60
	v_and_b32_e32 v59, 0xffff0000, v60
	v_lshlrev_b32_e32 v60, 16, v61
	v_and_b32_e32 v61, 0xffff0000, v61
	v_lshlrev_b32_e32 v54, 16, v56
	v_and_b32_e32 v55, 0xffff0000, v56
	v_lshlrev_b32_e32 v56, 16, v57
	v_and_b32_e32 v57, 0xffff0000, v57
	v_lshlrev_b32_e32 v46, 16, v48
	v_and_b32_e32 v47, 0xffff0000, v48
	v_lshlrev_b32_e32 v48, 16, v49
	v_and_b32_e32 v49, 0xffff0000, v49

; #define GAS __attribute__((address_space(1)))
; DI unsigned pk2(float lo, float hi) { f32x2_t v = {lo, hi}; bf16x2_t b = __builtin_convertvector(v, bf16x2_t); return __builtin_bit_cast(unsigned, b); }
; DI float bflo(unsigned w) { return __uint_as_float(w << 16); }
; DI float bfhi(unsigned w) { return __uint_as_float(w & 0xffff0000u); }
; DI void phase_e(const Ctx& C, int nslab, int has_post, int pl, int ps, float pw, int has_pre, int ql, int qs, int nrows,
;                 const GAS float* xsrc, const GAS float* csrc, GAS float* xdst, GAS float* cdst, bool xs16, bool xd16) {
;     ...
;         if (has_post) {
;             f32x4 y[4]; float ss = 0.f;
; #pragma unroll
;             for (int j = 0; j < 4; ++j) {
;                 if (isx || nslab == 0) { y[j] = (f32x4){bflo(yw[j].x), bfhi(yw[j].x), bflo(yw[j].y), bfhi(yw[j].y)}; }
;                 else { y[j] = (f32x4){0.f, 0.f, 0.f, 0.f};
;                     for (int s = 0; s < nslab; ++s) { const u32x2 w = *(const GAS u32x2*)(YS + ((size_t)s * MC + (row - MX)) * 1024 + 256 * j + 4 * lane); y[j] += (f32x4){bflo(w.x), bfhi(w.x), bflo(w.y), bfhi(w.y)}; } }
;                 ss += (y[j][0] * y[j][0] + y[j][1] * y[j][1]) + (y[j][2] * y[j][2] + y[j][3] * y[j][3]); }
;             const float r = rsqrtf(wave_sum(ss) * (1.0f / 1024.0f) + EPS);
;             if (isx && xd16) { GAS bf16* d16 = (GAS bf16*)xdst + (size_t)row * 1024;
; #pragma unroll
;                 for (int j = 0; j < 4; ++j) { v[j] += pw * gt[j] * ((y[j] * r) * gpo[j]); u32x2 w; w.x = pk2(v[j][0], v[j][1]); w.y = pk2(v[j][2], v[j][3]); __builtin_nontemporal_store(w, (GAS u32x2*)(d16 + 256 * j + 4 * lane));
;                     v[j] = (f32x4){bflo(w.x), bfhi(w.x), bflo(w.y), bfhi(w.y)}; }
;             } else { GAS float* dst = isx ? xdst + (size_t)row * 1024 : cdst + (size_t)(row - MX) * 1024;
; #pragma unroll
;                 for (int j = 0; j < 4; ++j) { v[j] += pw * gt[j] * ((y[j] * r) * gpo[j]); __builtin_nontemporal_store(v[j], (GAS f32x4*)(dst + 256 * j + 4 * lane)); } }
.LBB0_1506_u2:
	v_mul_f32_e32 v130, v141, v141
	v_mul_f32_e32 v131, v139, v139
	v_fmac_f32_e32 v130, v140, v140
	v_fmac_f32_e32 v131, v138, v138
	v_add_f32_e32 v130, v130, v131
	v_mul_f32_e32 v131, v171, v171
	v_mul_f32_e32 v132, v173, v173
	v_fmac_f32_e32 v131, v170, v170
	v_fmac_f32_e32 v132, v172, v172
	v_add_f32_e32 v131, v131, v132
	v_add_f32_e32 v130, v130, v131
	v_mul_f32_e32 v131, v175, v175
	v_mul_f32_e32 v132, v177, v177
	v_fmac_f32_e32 v131, v174, v174
	v_fmac_f32_e32 v132, v176, v176
	v_add_f32_e32 v131, v131, v132
	v_add_f32_e32 v136, v130, v131
	v_pk_mul_f32 v[130:131], v[180:181], v[180:181]
	v_pk_mul_f32 v[132:133], v[178:179], v[178:179]
	s_and_b64 s[0:1], exec, s[0:1]
	v_pk_mov_b32 v[134:135], v[132:133], v[130:131] op_sel:[1,0]
	v_mov_b32_e32 v133, v131
	v_pk_add_f32 v[130:131], v[134:135], v[132:133]
	s_ashr_i32 s11, s10, 31
	v_add_f32_e32 v130, v130, v131
	v_add_f32_e32 v130, v136, v130
	s_nop 1
	v_add_f32_dpp v130, v130, v130 quad_perm:[1,0,3,2] row_mask:0xf bank_mask:0xf
	s_nop 1
	v_add_f32_dpp v130, v130, v130 quad_perm:[2,3,0,1] row_mask:0xf bank_mask:0xf
	s_nop 1
	v_add_f32_dpp v130, v130, v130 row_half_mirror row_mask:0xf bank_mask:0xf
	s_nop 1
	v_add_f32_dpp v130, v130, v130 row_mirror row_mask:0xf bank_mask:0xf
	s_nop 1
	v_add_f32_dpp v130, v130, v130 row_bcast:15 row_mask:0xa bank_mask:0xf
	s_nop 1
	v_add_f32_dpp v130, v130, v130 row_bcast:31 row_mask:0xc bank_mask:0xf
	s_nop 0
	v_readlane_b32 s64, v130, 63
	s_nop 1
	v_mov_b32_e32 v132, s64
	s_waitcnt lgkmcnt(0)
	s_mov_b64 s[12:13], -1
	s_waitcnt vmcnt(7)
	v_pk_mul_f32 v[188:189], v[102:103], 0.5 op_sel_hi:[1,0]
	s_waitcnt vmcnt(6)
	v_pk_mul_f32 v[186:187], v[106:107], 0.5 op_sel_hi:[1,0]
	s_waitcnt vmcnt(4)
	v_pk_mul_f32 v[184:185], v[110:111], 0.5 op_sel_hi:[1,0]
	v_pk_mul_f32 v[130:131], v[96:97], 0.5 op_sel_hi:[1,0]
	v_fmamk_f32 v132, v132, 0x3a800000, v196
	v_mul_f32_e32 v133, 0x4b800000, v132
	v_cmp_gt_f32_e32 vcc, s27, v132
	s_nop 1
	v_cndmask_b32_e32 v132, v132, v133, vcc
	v_rsq_f32_e32 v134, v132
	v_pk_mul_f32 v[132:133], v[94:95], 0.5 op_sel_hi:[1,0]
	v_mul_f32_e32 v135, 0x45800000, v134
	v_cndmask_b32_e32 v182, v134, v135, vcc
	v_mov_b32_e32 v183, v182
	v_pk_mul_f32 v[134:135], v[138:139], v[182:183] op_sel_hi:[1,0]
	v_pk_mul_f32 v[136:137], v[140:141], v[182:183] op_sel_hi:[1,0]
	v_pk_mul_f32 v[134:135], v[4:5], v[134:135]
	v_pk_mul_f32 v[136:137], v[2:3], v[136:137]
	v_pk_fma_f32 v[116:117], v[130:131], v[134:135], v[116:117]
	v_pk_fma_f32 v[114:115], v[132:133], v[136:137], v[114:115]
	s_mov_b64 vcc, s[0:1]
	s_cbranch_vccz .LBB0_1508_u2
	v_mov_b32_e32 v138, v182
	v_mov_b32_e32 v139, v182
	v_pk_mul_f32 v[132:133], v[172:173], v[138:139]
	v_pk_mul_f32 v[134:135], v[170:171], v[182:183]
	v_pk_mul_f32 v[130:131], v[104:105], 0.5 op_sel_hi:[1,0]
	v_pk_mul_f32 v[132:133], v[8:9], v[132:133]
	v_pk_mul_f32 v[134:135], v[6:7], v[134:135]
	v_pk_mul_f32 v[136:137], v[176:177], v[138:139]
	v_pk_mul_f32 v[140:141], v[174:175], v[182:183]
	v_pk_fma_f32 v[132:133], v[130:131], v[132:133], v[120:121]
	v_pk_fma_f32 v[130:131], v[188:189], v[134:135], v[118:119]
	v_pk_mul_f32 v[134:135], v[108:109], 0.5 op_sel_hi:[1,0]
	v_pk_mul_f32 v[136:137], v[20:21], v[136:137]
	v_pk_mul_f32 v[140:141], v[18:19], v[140:141]
	v_pk_mul_f32 v[138:139], v[180:181], v[138:139]
	v_pk_mul_f32 v[200:201], v[178:179], v[182:183]
	s_lshl_b64 s[0:1], s[4:5], 12
	v_pk_fma_f32 v[136:137], v[134:135], v[136:137], v[124:125]
	v_pk_fma_f32 v[134:135], v[186:187], v[140:141], v[122:123]
	v_pk_mul_f32 v[140:141], v[112:113], 0.5 op_sel_hi:[1,0]
	v_pk_mul_f32 v[138:139], v[24:25], v[138:139]
	v_pk_mul_f32 v[200:201], v[22:23], v[200:201]
	v_lshl_add_u64 v[198:199], v[160:161], 0, s[0:1]
	v_pk_fma_f32 v[140:141], v[140:141], v[138:139], v[128:129]
	v_pk_fma_f32 v[138:139], v[184:185], v[200:201], v[126:127]
	global_store_dwordx4 v[198:199], v[114:117], off nt
	global_store_dwordx4 v[198:199], v[130:133], off offset:1024 nt
	global_store_dwordx4 v[198:199], v[134:137], off offset:2048 nt
	global_store_dwordx4 v[198:199], v[138:141], off offset:3072 nt
	s_lshl_b64 s[2:3], s[10:11], 11
	s_mov_b64 s[12:13], 0

; #define GAS __attribute__((address_space(1)))
; DI unsigned pk2(float lo, float hi) { f32x2_t v = {lo, hi}; bf16x2_t b = __builtin_convertvector(v, bf16x2_t); return __builtin_bit_cast(unsigned, b); }
; DI void phase_e(const Ctx& C, int nslab, int has_post, int pl, int ps, float pw, int has_pre, int ql, int qs, int nrows,
;                 const GAS float* xsrc, const GAS float* csrc, GAS float* xdst, GAS float* cdst, bool xs16, bool xd16) {
;     ...
;         f32x4 v[4]; u32x2 yw[4];
; #pragma unroll
;         for (int j = 0; j < 4; ++j) { v[j] = vN[j]; yw[j] = yN[j]; vN[j] = vM[j]; yN[j] = yM[j]; }
;         if (i + 16 < total) E_LOAD(i + 16, vM, yM);
;     ...
;         if (has_pre) {
;             float ss = 0.f;
; #pragma unroll
;             for (int j = 0; j < 4; ++j) ss += (v[j][0] * v[j][0] + v[j][1] * v[j][1]) + (v[j][2] * v[j][2] + v[j][3] * v[j][3]);
;             const float r = rsqrtf(wave_sum(ss) * (1.0f / 1024.0f) + EPS);
; #pragma unroll
;             for (int j = 0; j < 4; ++j) { const f32x4 h = ((v[j] * r) * gpr[j]) * (1.0f + sc[j]) + sh[j];
;                 u32x2 w; w.x = pk2(h[0], h[1]); w.y = pk2(h[2], h[3]); *(GAS u32x2*)(H + (size_t)row * 1024 + 256 * j + 4 * lane) = w; }
;         }
.LBB0_2209:
	v_pk_mul_f32 v[122:123], v[132:133], v[132:133]
	v_pk_mul_f32 v[124:125], v[130:131], v[130:131]
	v_pk_mul_f32 v[126:127], v[136:137], v[136:137]
	v_pk_mul_f32 v[128:129], v[134:135], v[134:135]
	v_pk_mov_b32 v[118:119], v[124:125], v[122:123] op_sel:[1,0]
	v_mov_b32_e32 v125, v123
	v_pk_add_f32 v[122:123], v[118:119], v[124:125]
	v_pk_mov_b32 v[124:125], v[128:129], v[126:127] op_sel:[1,0]
	v_mov_b32_e32 v129, v127
	v_pk_add_f32 v[126:127], v[124:125], v[128:129]
	v_pk_add_f32 v[122:123], v[122:123], v[122:123] op_sel_hi:[0,1]
	v_pk_add_f32 v[126:127], v[126:127], v[126:127] op_sel_hi:[0,1]
	v_mul_f32_e32 v126, v138, v138
	v_pk_fma_f32 v[128:129], v[138:139], v[138:139], v[126:127] op_sel_hi:[1,1,0]
	v_mul_f32_e32 v126, v140, v140
	v_pk_fma_f32 v[124:125], v[140:141], v[140:141], v[126:127] op_sel_hi:[1,1,0]
	v_mul_f32_e32 v128, v142, v142
	v_mul_f32_e32 v124, v143, v143
	v_mul_f32_e32 v122, v144, v144
	v_mul_f32_e32 v126, v145, v145
	v_pk_add_f32 v[128:129], v[128:129], v[124:125]
	v_pk_add_f32 v[126:127], v[122:123], v[126:127]
	s_waitcnt vmcnt(10)
	v_pk_add_f32 v[122:123], v[70:71], 1.0 op_sel_hi:[1,0]
	v_pk_add_f32 v[126:127], v[128:129], v[126:127]
	v_pk_add_f32 v[128:129], v[72:73], 1.0 op_sel_hi:[1,0]
	v_add_f32_e32 v126, v126, v127
	s_nop 1
	v_add_f32_dpp v126, v126, v126 quad_perm:[1,0,3,2] row_mask:0xf bank_mask:0xf
	s_nop 1
	v_add_f32_dpp v126, v126, v126 quad_perm:[2,3,0,1] row_mask:0xf bank_mask:0xf
	s_nop 1
	v_add_f32_dpp v126, v126, v126 row_half_mirror row_mask:0xf bank_mask:0xf
	s_nop 1
	v_add_f32_dpp v126, v126, v126 row_mirror row_mask:0xf bank_mask:0xf
	s_nop 1
	v_add_f32_dpp v126, v126, v126 row_bcast:15 row_mask:0xa bank_mask:0xf
	s_nop 1
	v_add_f32_dpp v126, v126, v126 row_bcast:31 row_mask:0xc bank_mask:0xf
	s_nop 0
	v_readlane_b32 s64, v126, 63
	s_nop 1
	v_mov_b32_e32 v126, s64
	s_waitcnt lgkmcnt(0)
	s_add_i32 s16, s16, 8
	s_cmp_lt_i32 s16, s17
	v_fmamk_f32 v126, v126, 0x3a800000, v197
	v_mul_f32_e32 v127, 0x4b800000, v126
	v_cmp_gt_f32_e32 vcc, s22, v126
	s_nop 1
	v_cndmask_b32_e32 v126, v126, v127, vcc
	v_rsq_f32_e32 v124, v126
	v_lshl_add_u64 v[126:127], v[162:163], 0, s[8:9]
	v_mul_f32_e32 v125, 0x45800000, v124
	v_cndmask_b32_e32 v124, v124, v125, vcc
	v_pk_mul_f32 v[118:119], v[132:133], v[124:125] op_sel_hi:[1,0]
	v_pk_mul_f32 v[120:121], v[130:131], v[124:125] op_sel_hi:[1,0]
	v_pk_mul_f32 v[118:119], v[12:13], v[118:119]
	v_pk_mul_f32 v[120:121], v[10:11], v[120:121]
	s_waitcnt vmcnt(9)
	v_pk_fma_f32 v[128:129], v[128:129], v[118:119], v[76:77]
	v_pk_fma_f32 v[122:123], v[122:123], v[120:121], v[74:75]
	v_pk_mul_f32 v[114:115], v[136:137], v[124:125] op_sel_hi:[1,0]
	v_pk_mul_f32 v[116:117], v[134:135], v[124:125] op_sel_hi:[1,0]
	v_cvt_pk_bf16_f32 v122, v122, v123
	v_cvt_pk_bf16_f32 v123, v128, v129
	v_pk_mul_f32 v[116:117], v[14:15], v[116:117]
	global_store_dwordx2 v[126:127], v[122:123], off
	v_pk_mul_f32 v[128:129], v[16:17], v[114:115]
	s_waitcnt vmcnt(6)
	v_pk_add_f32 v[122:123], v[80:81], 1.0 op_sel_hi:[1,0]
	v_pk_add_f32 v[118:119], v[78:79], 1.0 op_sel_hi:[1,0]
	v_pk_fma_f32 v[128:129], v[122:123], v[128:129], v[84:85]
	v_pk_fma_f32 v[122:123], v[118:119], v[116:117], v[82:83]
	s_waitcnt vmcnt(4)
	v_pk_add_f32 v[118:119], v[88:89], 1.0 op_sel_hi:[1,0]
	v_cvt_pk_bf16_f32 v122, v122, v123
	v_cvt_pk_bf16_f32 v123, v128, v129
	global_store_dwordx2 v[126:127], v[122:123], off offset:512
	v_pk_mul_f32 v[128:129], v[140:141], v[124:125] op_sel_hi:[1,0]
	v_pk_mul_f32 v[122:123], v[138:139], v[124:125] op_sel_hi:[1,0]
	v_pk_mul_f32 v[128:129], v[28:29], v[128:129]
	v_pk_mul_f32 v[122:123], v[26:27], v[122:123]
	v_pk_add_f32 v[120:121], v[86:87], 1.0 op_sel_hi:[1,0]
	s_waitcnt vmcnt(3)
	v_pk_fma_f32 v[128:129], v[118:119], v[128:129], v[96:97]
	v_pk_fma_f32 v[122:123], v[120:121], v[122:123], v[94:95]
	v_pk_add_f32 v[118:119], v[66:67], 1.0 op_sel_hi:[1,0]
	v_cvt_pk_bf16_f32 v122, v122, v123
	v_cvt_pk_bf16_f32 v123, v128, v129
	global_store_dwordx2 v[126:127], v[122:123], off offset:1024
	v_pk_mul_f32 v[128:129], v[144:145], v[124:125] op_sel_hi:[1,0]
	v_pk_mul_f32 v[122:123], v[142:143], v[124:125] op_sel_hi:[1,0]
	v_pk_mul_f32 v[128:129], v[32:33], v[128:129]
	v_pk_mul_f32 v[122:123], v[30:31], v[122:123]
	v_pk_add_f32 v[124:125], v[68:69], 1.0 op_sel_hi:[1,0]
	s_waitcnt vmcnt(3)
	v_pk_fma_f32 v[122:123], v[118:119], v[122:123], v[90:91]
	v_pk_fma_f32 v[128:129], v[124:125], v[128:129], v[92:93]
	v_cvt_pk_bf16_f32 v122, v122, v123
	v_cvt_pk_bf16_f32 v123, v128, v129
	global_store_dwordx2 v[126:127], v[122:123], off offset:1536
	s_mov_b64 vcc, s[98:99]
	s_cbranch_vccz .Leload_skip_3_u2
	s_waitcnt vmcnt(8)
	v_lshlrev_b32_e32 v34, 16, v36
	v_and_b32_e32 v35, 0xffff0000, v36
	v_lshlrev_b32_e32 v36, 16, v37
	v_and_b32_e32 v37, 0xffff0000, v37
	v_lshlrev_b32_e32 v38, 16, v40
	v_and_b32_e32 v39, 0xffff0000, v40
	v_lshlrev_b32_e32 v40, 16, v41
	v_and_b32_e32 v41, 0xffff0000, v41
	v_lshlrev_b32_e32 v42, 16, v44
	v_and_b32_e32 v43, 0xffff0000, v44
	v_lshlrev_b32_e32 v44, 16, v45
	v_and_b32_e32 v45, 0xffff0000, v45
	v_lshlrev_b32_e32 v46, 16, v48
	v_and_b32_e32 v47, 0xffff0000, v48
	v_lshlrev_b32_e32 v48, 16, v49
	v_and_b32_e32 v49, 0xffff0000, v49
.Leload_skip_3_u2:
	v_mov_b64_e32 v[130:131], v[154:155]
	v_mov_b64_e32 v[132:133], v[152:153]
	v_mov_b64_e32 v[134:135], v[150:151]
	v_mov_b64_e32 v[136:137], v[148:149]
	v_mov_b64_e32 v[154:155], v[172:173]
	v_mov_b64_e32 v[152:153], v[170:171]
	v_mov_b64_e32 v[150:151], v[168:169]
	v_mov_b64_e32 v[148:149], v[166:167]
	s_cbranch_scc0 .LBB0_2222

; #define GAS __attribute__((address_space(1)))
; DI unsigned pk2(float lo, float hi) { f32x2_t v = {lo, hi}; bf16x2_t b = __builtin_convertvector(v, bf16x2_t); return __builtin_bit_cast(unsigned, b); }
; DI float bflo(unsigned w) { return __uint_as_float(w << 16); }
; DI float bfhi(unsigned w) { return __uint_as_float(w & 0xffff0000u); }
; DI void phase_e(const Ctx& C, int nslab, int has_post, int pl, int ps, float pw, int has_pre, int ql, int qs, int nrows,
;                 const GAS float* xsrc, const GAS float* csrc, GAS float* xdst, GAS float* cdst, bool xs16, bool xd16) {
;     ...
;             if (isx && xd16) { GAS bf16* d16 = (GAS bf16*)xdst + (size_t)row * 1024;
; #pragma unroll
;                 for (int j = 0; j < 4; ++j) { v[j] += pw * gt[j] * ((y[j] * r) * gpo[j]); u32x2 w; w.x = pk2(v[j][0], v[j][1]); w.y = pk2(v[j][2], v[j][3]); __builtin_nontemporal_store(w, (GAS u32x2*)(d16 + 256 * j + 4 * lane));
;                     v[j] = (f32x4){bflo(w.x), bfhi(w.x), bflo(w.y), bfhi(w.y)}; }
.LBB0_2220:
	s_andn2_b64 vcc, exec, s[10:11]
	s_cbranch_vccnz .LBB0_2209_u0
	v_mov_b32_e32 v130, v187
	v_mov_b32_e32 v131, v189
	v_mov_b32_e32 v187, v188
	v_pk_mul_f32 v[130:131], v[130:131], v[190:191] op_sel_hi:[1,0]
	v_pk_mul_f32 v[132:133], v[186:187], v[190:191] op_sel_hi:[1,0]
	v_pk_mul_f32 v[130:131], v[4:5], v[130:131]
	v_pk_mul_f32 v[132:133], v[2:3], v[132:133]
	s_lshl_b64 s[8:9], s[6:7], 11
	s_waitcnt vmcnt(11)
	v_pk_fma_f32 v[64:65], v[100:101], v[130:131], v[64:65]
	v_pk_fma_f32 v[62:63], v[98:99], v[132:133], v[62:63]
	v_lshl_add_u64 v[142:143], v[160:161], 0, s[8:9]
	v_cvt_pk_bf16_f32 v62, v62, v63
	v_cvt_pk_bf16_f32 v63, v64, v65
	global_store_dwordx2 v[142:143], v[62:63], off nt
	v_lshlrev_b32_e32 v130, 16, v62
	v_and_b32_e32 v131, 0xffff0000, v62
	v_lshlrev_b32_e32 v132, 16, v63
	v_and_b32_e32 v133, 0xffff0000, v63
	v_mov_b32_e32 v62, v183
	v_mov_b32_e32 v63, v185
	v_mov_b32_e32 v183, v184
	v_pk_mul_f32 v[62:63], v[62:63], v[190:191] op_sel_hi:[1,0]
	v_pk_mul_f32 v[64:65], v[182:183], v[190:191] op_sel_hi:[1,0]
	v_pk_mul_f32 v[62:63], v[8:9], v[62:63]
	v_pk_mul_f32 v[64:65], v[6:7], v[64:65]
	s_waitcnt vmcnt(8)
	v_pk_fma_f32 v[60:61], v[104:105], v[62:63], v[60:61]
	v_pk_fma_f32 v[58:59], v[102:103], v[64:65], v[58:59]
	s_nop 0
	v_cvt_pk_bf16_f32 v58, v58, v59
	v_cvt_pk_bf16_f32 v59, v60, v61
	global_store_dwordx2 v[142:143], v[58:59], off offset:512 nt
	v_lshlrev_b32_e32 v134, 16, v58
	v_and_b32_e32 v135, 0xffff0000, v58
	v_lshlrev_b32_e32 v136, 16, v59
	v_and_b32_e32 v137, 0xffff0000, v59
	v_pk_mul_f32 v[58:59], v[178:179], v[190:191] op_sel_hi:[1,0]
	v_pk_mul_f32 v[60:61], v[180:181], v[190:191] op_sel_hi:[1,0]
	v_pk_mul_f32 v[58:59], v[18:19], v[58:59]
	v_pk_mul_f32 v[60:61], v[20:21], v[60:61]
	s_waitcnt vmcnt(8)
	v_pk_fma_f32 v[54:55], v[106:107], v[58:59], v[54:55]
	v_pk_fma_f32 v[56:57], v[108:109], v[60:61], v[56:57]
	v_cvt_pk_bf16_f32 v54, v54, v55
	v_cvt_pk_bf16_f32 v55, v56, v57
	global_store_dwordx2 v[142:143], v[54:55], off offset:1024 nt
	v_lshlrev_b32_e32 v138, 16, v54
	v_and_b32_e32 v139, 0xffff0000, v54
	v_lshlrev_b32_e32 v140, 16, v55
	v_and_b32_e32 v141, 0xffff0000, v55
	v_pk_mul_f32 v[54:55], v[176:177], v[190:191] op_sel_hi:[1,0]
	v_pk_mul_f32 v[56:57], v[174:175], v[190:191] op_sel_hi:[1,0]
	v_pk_mul_f32 v[54:55], v[24:25], v[54:55]
	v_pk_mul_f32 v[56:57], v[22:23], v[56:57]
	s_waitcnt vmcnt(7)
	v_pk_fma_f32 v[52:53], v[112:113], v[54:55], v[52:53]
	v_pk_fma_f32 v[50:51], v[110:111], v[56:57], v[50:51]
	s_nop 0
	v_cvt_pk_bf16_f32 v50, v50, v51
	v_cvt_pk_bf16_f32 v51, v52, v53
	global_store_dwordx2 v[142:143], v[50:51], off offset:1536 nt
	v_lshlrev_b32_e32 v142, 16, v50
	v_and_b32_e32 v143, 0xffff0000, v50
	v_lshlrev_b32_e32 v144, 16, v51
	v_and_b32_e32 v145, 0xffff0000, v51
	s_branch .LBB0_2209_u0
; #define GAS __attribute__((address_space(1)))
; DI unsigned pk2(float lo, float hi) { f32x2_t v = {lo, hi}; bf16x2_t b = __builtin_convertvector(v, bf16x2_t); return __builtin_bit_cast(unsigned, b); }
; DI void phase_e(const Ctx& C, int nslab, int has_post, int pl, int ps, float pw, int has_pre, int ql, int qs, int nrows,
;                 const GAS float* xsrc, const GAS float* csrc, GAS float* xdst, GAS float* cdst, bool xs16, bool xd16) {
;     ...
;         if (has_pre) {
;             float ss = 0.f;
; #pragma unroll
;             for (int j = 0; j < 4; ++j) ss += (v[j][0] * v[j][0] + v[j][1] * v[j][1]) + (v[j][2] * v[j][2] + v[j][3] * v[j][3]);
;             const float r = rsqrtf(wave_sum(ss) * (1.0f / 1024.0f) + EPS);
; #pragma unroll
;             for (int j = 0; j < 4; ++j) { const f32x4 h = ((v[j] * r) * gpr[j]) * (1.0f + sc[j]) + sh[j];
;                 u32x2 w; w.x = pk2(h[0], h[1]); w.y = pk2(h[2], h[3]); *(GAS u32x2*)(H + (size_t)row * 1024 + 256 * j + 4 * lane) = w; }
;         }
.LBB0_2209_u0:
	v_pk_mul_f32 v[54:55], v[132:133], v[132:133]
	v_pk_mul_f32 v[56:57], v[130:131], v[130:131]
	v_pk_mul_f32 v[50:51], v[136:137], v[136:137]
	v_pk_mul_f32 v[52:53], v[134:135], v[134:135]
	v_pk_mov_b32 v[58:59], v[56:57], v[54:55] op_sel:[1,0]
	v_mov_b32_e32 v57, v55
	v_pk_add_f32 v[54:55], v[58:59], v[56:57]
	v_pk_mov_b32 v[56:57], v[52:53], v[50:51] op_sel:[1,0]
	v_mov_b32_e32 v53, v51
	v_pk_add_f32 v[50:51], v[56:57], v[52:53]
	v_pk_add_f32 v[54:55], v[54:55], v[54:55] op_sel_hi:[0,1]
	v_pk_add_f32 v[50:51], v[50:51], v[50:51] op_sel_hi:[0,1]
	v_mul_f32_e32 v50, v138, v138
	v_pk_fma_f32 v[52:53], v[138:139], v[138:139], v[50:51] op_sel_hi:[1,1,0]
	v_mul_f32_e32 v50, v140, v140
	v_pk_fma_f32 v[56:57], v[140:141], v[140:141], v[50:51] op_sel_hi:[1,1,0]
	v_mul_f32_e32 v52, v142, v142
	v_mul_f32_e32 v56, v143, v143
	v_mul_f32_e32 v54, v144, v144
	v_mul_f32_e32 v50, v145, v145
	v_pk_add_f32 v[52:53], v[52:53], v[56:57]
	v_pk_add_f32 v[50:51], v[54:55], v[50:51]
	s_waitcnt vmcnt(10)
	v_pk_add_f32 v[54:55], v[70:71], 1.0 op_sel_hi:[1,0]
	v_pk_add_f32 v[50:51], v[52:53], v[50:51]
	v_pk_add_f32 v[52:53], v[72:73], 1.0 op_sel_hi:[1,0]
	v_add_f32_e32 v50, v50, v51
	s_nop 1
	v_add_f32_dpp v50, v50, v50 quad_perm:[1,0,3,2] row_mask:0xf bank_mask:0xf
	s_nop 1
	v_add_f32_dpp v50, v50, v50 quad_perm:[2,3,0,1] row_mask:0xf bank_mask:0xf
	s_nop 1
	v_add_f32_dpp v50, v50, v50 row_half_mirror row_mask:0xf bank_mask:0xf
	s_nop 1
	v_add_f32_dpp v50, v50, v50 row_mirror row_mask:0xf bank_mask:0xf
	s_nop 1
	v_add_f32_dpp v50, v50, v50 row_bcast:15 row_mask:0xa bank_mask:0xf
	s_nop 1
	v_add_f32_dpp v50, v50, v50 row_bcast:31 row_mask:0xc bank_mask:0xf
	s_nop 0
	v_readlane_b32 s64, v50, 63
	s_nop 1
	v_mov_b32_e32 v50, s64
	s_waitcnt lgkmcnt(0)
	s_add_i32 s16, s16, 8
	s_cmp_lt_i32 s16, s17
	v_fmamk_f32 v50, v50, 0x3a800000, v197
	v_mul_f32_e32 v51, 0x4b800000, v50
	v_cmp_gt_f32_e32 vcc, s22, v50
	s_nop 1
	v_cndmask_b32_e32 v50, v50, v51, vcc
	v_rsq_f32_e32 v56, v50
	v_lshl_add_u64 v[50:51], v[162:163], 0, s[8:9]
	v_mul_f32_e32 v57, 0x45800000, v56
	v_cndmask_b32_e32 v56, v56, v57, vcc
	v_pk_mul_f32 v[58:59], v[132:133], v[56:57] op_sel_hi:[1,0]
	v_pk_mul_f32 v[60:61], v[130:131], v[56:57] op_sel_hi:[1,0]
	v_pk_mul_f32 v[58:59], v[12:13], v[58:59]
	v_pk_mul_f32 v[60:61], v[10:11], v[60:61]
	s_waitcnt vmcnt(9)
	v_pk_fma_f32 v[52:53], v[52:53], v[58:59], v[76:77]
	v_pk_fma_f32 v[54:55], v[54:55], v[60:61], v[74:75]
	v_pk_mul_f32 v[62:63], v[136:137], v[56:57] op_sel_hi:[1,0]
	v_pk_mul_f32 v[64:65], v[134:135], v[56:57] op_sel_hi:[1,0]
	v_cvt_pk_bf16_f32 v54, v54, v55
	v_cvt_pk_bf16_f32 v55, v52, v53
	v_pk_mul_f32 v[64:65], v[14:15], v[64:65]
	global_store_dwordx2 v[50:51], v[54:55], off
	v_pk_mul_f32 v[52:53], v[16:17], v[62:63]
	s_waitcnt vmcnt(6)
	v_pk_add_f32 v[54:55], v[80:81], 1.0 op_sel_hi:[1,0]
	v_pk_add_f32 v[58:59], v[78:79], 1.0 op_sel_hi:[1,0]
	v_pk_fma_f32 v[52:53], v[54:55], v[52:53], v[84:85]
	v_pk_fma_f32 v[54:55], v[58:59], v[64:65], v[82:83]
	s_waitcnt vmcnt(4)
	v_pk_add_f32 v[58:59], v[88:89], 1.0 op_sel_hi:[1,0]
	v_cvt_pk_bf16_f32 v54, v54, v55
	v_cvt_pk_bf16_f32 v55, v52, v53
	global_store_dwordx2 v[50:51], v[54:55], off offset:512
	v_pk_mul_f32 v[52:53], v[140:141], v[56:57] op_sel_hi:[1,0]
	v_pk_mul_f32 v[54:55], v[138:139], v[56:57] op_sel_hi:[1,0]
	v_pk_mul_f32 v[52:53], v[28:29], v[52:53]
	v_pk_mul_f32 v[54:55], v[26:27], v[54:55]
	v_pk_add_f32 v[60:61], v[86:87], 1.0 op_sel_hi:[1,0]
	s_waitcnt vmcnt(3)
	v_pk_fma_f32 v[52:53], v[58:59], v[52:53], v[96:97]
	v_pk_fma_f32 v[54:55], v[60:61], v[54:55], v[94:95]
	v_pk_add_f32 v[58:59], v[66:67], 1.0 op_sel_hi:[1,0]
	v_cvt_pk_bf16_f32 v54, v54, v55
	v_cvt_pk_bf16_f32 v55, v52, v53
	global_store_dwordx2 v[50:51], v[54:55], off offset:1024
	v_pk_mul_f32 v[52:53], v[144:145], v[56:57] op_sel_hi:[1,0]
	v_pk_mul_f32 v[54:55], v[142:143], v[56:57] op_sel_hi:[1,0]
	v_pk_mul_f32 v[52:53], v[32:33], v[52:53]
	v_pk_mul_f32 v[54:55], v[30:31], v[54:55]
	v_pk_add_f32 v[56:57], v[68:69], 1.0 op_sel_hi:[1,0]
	s_waitcnt vmcnt(3)
	v_pk_fma_f32 v[54:55], v[58:59], v[54:55], v[90:91]
	v_pk_fma_f32 v[52:53], v[56:57], v[52:53], v[92:93]
	v_cvt_pk_bf16_f32 v54, v54, v55
	v_cvt_pk_bf16_f32 v55, v52, v53
	global_store_dwordx2 v[50:51], v[54:55], off offset:1536
	s_mov_b64 vcc, s[98:99]
	s_cbranch_vccz .Leload_skip_3
	s_waitcnt vmcnt(8)
	v_lshlrev_b32_e32 v114, 16, v116
	v_and_b32_e32 v115, 0xffff0000, v116
	v_lshlrev_b32_e32 v116, 16, v117
	v_and_b32_e32 v117, 0xffff0000, v117
	v_lshlrev_b32_e32 v118, 16, v120
	v_and_b32_e32 v119, 0xffff0000, v120
	v_lshlrev_b32_e32 v120, 16, v121
	v_and_b32_e32 v121, 0xffff0000, v121
	v_lshlrev_b32_e32 v122, 16, v124
	v_and_b32_e32 v123, 0xffff0000, v124
	v_lshlrev_b32_e32 v124, 16, v125
	v_and_b32_e32 v125, 0xffff0000, v125
	v_lshlrev_b32_e32 v126, 16, v128
	v_and_b32_e32 v127, 0xffff0000, v128
	v_lshlrev_b32_e32 v128, 16, v129
	v_and_b32_e32 v129, 0xffff0000, v129

.LBB0_2210_u1:
	s_mov_b64 s[98:99], 0
	s_add_i32 s6, s18, s16
	s_add_i32 s0, s16, 16
	s_cmp_ge_i32 s0, s17
	s_cbranch_scc1 .LBB0_2216_u1
	s_add_i32 s10, s6, 16
	s_cmpk_gt_i32 s10, 0x7fff
	s_mov_b64 s[12:13], -1
	s_cbranch_scc0 .LBB0_2213_u1
	s_add_i32 s0, s6, 0xffff8010
	s_lshl_b64 s[8:9], s[0:1], 12
	v_lshl_add_u64 v[50:51], v[164:165], 0, s[8:9]
	global_load_dwordx4 v[62:65], v[50:51], off nt
	global_load_dwordx4 v[58:61], v[50:51], off offset:1024 nt
	global_load_dwordx4 v[54:57], v[50:51], off offset:2048 nt
	s_nop 0
	global_load_dwordx4 v[50:53], v[50:51], off offset:3072 nt
	s_mov_b32 s11, s1
	s_lshl_b64 s[8:9], s[10:11], 11
	s_mov_b64 s[12:13], 0
.LBB0_2213_u1:
	s_andn2_b64 vcc, exec, s[12:13]
	s_cbranch_vccnz .LBB0_2215_u1
	s_ashr_i32 s11, s10, 31
	s_lshl_b64 s[8:9], s[10:11], 11
	s_waitcnt vmcnt(3)
	v_lshl_add_u64 v[62:63], v[156:157], 0, s[8:9]
	global_load_dwordx2 v[64:65], v[62:63], off nt
	global_load_dwordx2 v[60:61], v[62:63], off offset:512 nt
	global_load_dwordx2 v[56:57], v[62:63], off offset:1024 nt
	global_load_dwordx2 v[52:53], v[62:63], off offset:1536 nt
	s_mov_b64 s[98:99], -1

; #define GAS __attribute__((address_space(1)))
; DI unsigned pk2(float lo, float hi) { f32x2_t v = {lo, hi}; bf16x2_t b = __builtin_convertvector(v, bf16x2_t); return __builtin_bit_cast(unsigned, b); }
; DI float bflo(unsigned w) { return __uint_as_float(w << 16); }
; DI float bfhi(unsigned w) { return __uint_as_float(w & 0xffff0000u); }
; DI void phase_e(const Ctx& C, int nslab, int has_post, int pl, int ps, float pw, int has_pre, int ql, int qs, int nrows,
;                 const GAS float* xsrc, const GAS float* csrc, GAS float* xdst, GAS float* cdst, bool xs16, bool xd16) {
;     ...
;         if (has_post) {
;             f32x4 y[4]; float ss = 0.f;
; #pragma unroll
;             for (int j = 0; j < 4; ++j) {
;                 if (isx || nslab == 0) { y[j] = (f32x4){bflo(yw[j].x), bfhi(yw[j].x), bflo(yw[j].y), bfhi(yw[j].y)}; }
;                 else { y[j] = (f32x4){0.f, 0.f, 0.f, 0.f};
;                     for (int s = 0; s < nslab; ++s) { const u32x2 w = *(const GAS u32x2*)(YS + ((size_t)s * MC + (row - MX)) * 1024 + 256 * j + 4 * lane); y[j] += (f32x4){bflo(w.x), bfhi(w.x), bflo(w.y), bfhi(w.y)}; } }
;                 ss += (y[j][0] * y[j][0] + y[j][1] * y[j][1]) + (y[j][2] * y[j][2] + y[j][3] * y[j][3]); }
;             const float r = rsqrtf(wave_sum(ss) * (1.0f / 1024.0f) + EPS);
;             if (isx && xd16) { GAS bf16* d16 = (GAS bf16*)xdst + (size_t)row * 1024;
; #pragma unroll
;                 for (int j = 0; j < 4; ++j) { v[j] += pw * gt[j] * ((y[j] * r) * gpo[j]); u32x2 w; w.x = pk2(v[j][0], v[j][1]); w.y = pk2(v[j][2], v[j][3]); __builtin_nontemporal_store(w, (GAS u32x2*)(d16 + 256 * j + 4 * lane));
;                     v[j] = (f32x4){bflo(w.x), bfhi(w.x), bflo(w.y), bfhi(w.y)}; }
;             } else { GAS float* dst = isx ? xdst + (size_t)row * 1024 : cdst + (size_t)(row - MX) * 1024;
; #pragma unroll
;                 for (int j = 0; j < 4; ++j) { v[j] += pw * gt[j] * ((y[j] * r) * gpo[j]); __builtin_nontemporal_store(v[j], (GAS f32x4*)(dst + 256 * j + 4 * lane)); } }
.LBB0_2218_u1:
	v_and_b32_e32 v189, 0xffff0000, v137
	v_and_b32_e32 v188, 0xffff0000, v136
	v_and_b32_e32 v185, 0xffff0000, v135
	v_and_b32_e32 v184, 0xffff0000, v134
	v_lshlrev_b32_e32 v187, 16, v137
	v_lshlrev_b32_e32 v186, 16, v136
	v_pk_mul_f32 v[136:137], v[188:189], v[188:189]
	v_lshlrev_b32_e32 v183, 16, v135
	v_lshlrev_b32_e32 v182, 16, v134
	v_pk_mul_f32 v[134:135], v[184:185], v[184:185]
	v_lshlrev_b32_e32 v178, 16, v132
	v_and_b32_e32 v179, 0xffff0000, v132
	v_lshlrev_b32_e32 v180, 16, v133
	v_lshlrev_b32_e32 v174, 16, v130
	v_pk_fma_f32 v[136:137], v[186:187], v[186:187], v[136:137]
	v_pk_fma_f32 v[134:135], v[182:183], v[182:183], v[134:135]
	v_mul_f32_e32 v139, v178, v178
	v_mul_f32_e32 v141, v179, v179
	v_and_b32_e32 v181, 0xffff0000, v133
	v_mul_f32_e32 v132, v180, v180
	v_mov_b32_e32 v138, v174
	v_mov_b32_e32 v140, v174
	v_pk_add_f32 v[136:137], v[136:137], v[136:137] op_sel_hi:[0,1]
	v_pk_add_f32 v[134:135], v[134:135], v[134:135] op_sel_hi:[0,1]
	v_pk_fma_f32 v[132:133], v[180:181], v[180:181], v[132:133] op_sel_hi:[1,1,0]
	v_and_b32_e32 v175, 0xffff0000, v130
	v_lshlrev_b32_e32 v176, 16, v131
	v_and_b32_e32 v177, 0xffff0000, v131
	v_pk_add_f32 v[138:139], v[138:139], v[140:141]
	v_mul_f32_e32 v132, v175, v175
	v_mul_f32_e32 v134, v176, v176
	v_mul_f32_e32 v136, v177, v177
	v_mul_f32_e32 v130, v174, v174
	v_mov_b32_e32 v131, v139
	v_pk_add_f32 v[130:131], v[130:131], v[132:133]
	v_pk_add_f32 v[132:133], v[134:135], v[136:137]
	s_ashr_i32 s7, s6, 31
	v_pk_add_f32 v[130:131], v[130:131], v[132:133]
	s_cmpk_gt_i32 s6, 0x7fff
	v_add_f32_e32 v130, v130, v131
	s_nop 1
	v_add_f32_dpp v130, v130, v130 quad_perm:[1,0,3,2] row_mask:0xf bank_mask:0xf
	s_nop 1
	v_add_f32_dpp v130, v130, v130 quad_perm:[2,3,0,1] row_mask:0xf bank_mask:0xf
	s_nop 1
	v_add_f32_dpp v130, v130, v130 row_half_mirror row_mask:0xf bank_mask:0xf
	s_nop 1
	v_add_f32_dpp v130, v130, v130 row_mirror row_mask:0xf bank_mask:0xf
	s_nop 1
	v_add_f32_dpp v130, v130, v130 row_bcast:15 row_mask:0xa bank_mask:0xf
	s_nop 1
	v_add_f32_dpp v130, v130, v130 row_bcast:31 row_mask:0xc bank_mask:0xf
	s_nop 0
	v_readlane_b32 s64, v130, 63
	s_nop 1
	v_mov_b32_e32 v130, s64
	s_waitcnt lgkmcnt(0)
	s_mov_b64 s[10:11], -1
	v_fmamk_f32 v130, v130, 0x3a800000, v197
	v_mul_f32_e32 v131, 0x4b800000, v130
	v_cmp_gt_f32_e32 vcc, s22, v130
	s_nop 1
	v_cndmask_b32_e32 v130, v130, v131, vcc
	v_rsq_f32_e32 v130, v130
	s_nop 0
	v_mul_f32_e32 v131, 0x45800000, v130
	v_cndmask_b32_e32 v190, v130, v131, vcc
	s_cbranch_scc0 .LBB0_2220_u1
	v_mov_b32_e32 v130, v187
	v_mov_b32_e32 v131, v189
	v_mov_b32_e32 v132, v186
	v_mov_b32_e32 v133, v188
	v_pk_mul_f32 v[130:131], v[130:131], v[190:191] op_sel_hi:[1,0]
	v_pk_mul_f32 v[132:133], v[132:133], v[190:191] op_sel_hi:[1,0]
	v_pk_mul_f32 v[130:131], v[4:5], v[130:131]
	v_pk_mul_f32 v[134:135], v[2:3], v[132:133]
	s_waitcnt vmcnt(11)
	v_pk_fma_f32 v[132:133], v[100:101], v[130:131], v[36:37]
	v_pk_fma_f32 v[130:131], v[98:99], v[134:135], v[34:35]
	v_mov_b32_e32 v134, v183
	v_mov_b32_e32 v135, v185
	v_mov_b32_e32 v136, v182
	v_mov_b32_e32 v137, v184
	v_pk_mul_f32 v[134:135], v[134:135], v[190:191] op_sel_hi:[1,0]
	v_pk_mul_f32 v[136:137], v[136:137], v[190:191] op_sel_hi:[1,0]
	v_pk_mul_f32 v[134:135], v[8:9], v[134:135]
	v_pk_mul_f32 v[138:139], v[6:7], v[136:137]
	s_add_i32 s0, s6, 0xffff8000
	s_waitcnt vmcnt(7)
	v_pk_fma_f32 v[136:137], v[104:105], v[134:135], v[40:41]
	v_pk_fma_f32 v[134:135], v[102:103], v[138:139], v[38:39]
	v_pk_mul_f32 v[138:139], v[178:179], v[190:191] op_sel_hi:[1,0]
	v_pk_mul_f32 v[140:141], v[180:181], v[190:191] op_sel_hi:[1,0]
	v_pk_mul_f32 v[142:143], v[176:177], v[190:191] op_sel_hi:[1,0]
	v_pk_mul_f32 v[144:145], v[174:175], v[190:191] op_sel_hi:[1,0]
	s_lshl_b64 s[8:9], s[0:1], 12
	v_pk_mul_f32 v[138:139], v[18:19], v[138:139]
	v_pk_mul_f32 v[140:141], v[20:21], v[140:141]
	v_pk_mul_f32 v[200:201], v[22:23], v[144:145]
	v_pk_mul_f32 v[142:143], v[24:25], v[142:143]
	v_lshl_add_u64 v[198:199], v[164:165], 0, s[8:9]
	s_waitcnt vmcnt(6)
	v_pk_fma_f32 v[140:141], v[108:109], v[140:141], v[44:45]
	v_pk_fma_f32 v[138:139], v[106:107], v[138:139], v[42:43]
	s_waitcnt vmcnt(4)
	v_pk_fma_f32 v[144:145], v[112:113], v[142:143], v[48:49]
	v_pk_fma_f32 v[142:143], v[110:111], v[200:201], v[46:47]
	global_store_dwordx4 v[198:199], v[130:133], off nt
	global_store_dwordx4 v[198:199], v[134:137], off offset:1024 nt
	global_store_dwordx4 v[198:199], v[138:141], off offset:2048 nt
	global_store_dwordx4 v[198:199], v[142:145], off offset:3072 nt
	s_lshl_b64 s[8:9], s[6:7], 11
	s_mov_b64 s[10:11], 0
; #define GAS __attribute__((address_space(1)))
; DI unsigned pk2(float lo, float hi) { f32x2_t v = {lo, hi}; bf16x2_t b = __builtin_convertvector(v, bf16x2_t); return __builtin_bit_cast(unsigned, b); }
; DI float bflo(unsigned w) { return __uint_as_float(w << 16); }
; DI float bfhi(unsigned w) { return __uint_as_float(w & 0xffff0000u); }
; DI void phase_e(const Ctx& C, int nslab, int has_post, int pl, int ps, float pw, int has_pre, int ql, int qs, int nrows,
;                 const GAS float* xsrc, const GAS float* csrc, GAS float* xdst, GAS float* cdst, bool xs16, bool xd16) {
;     ...
;             if (isx && xd16) { GAS bf16* d16 = (GAS bf16*)xdst + (size_t)row * 1024;
; #pragma unroll
;                 for (int j = 0; j < 4; ++j) { v[j] += pw * gt[j] * ((y[j] * r) * gpo[j]); u32x2 w; w.x = pk2(v[j][0], v[j][1]); w.y = pk2(v[j][2], v[j][3]); __builtin_nontemporal_store(w, (GAS u32x2*)(d16 + 256 * j + 4 * lane));
;                     v[j] = (f32x4){bflo(w.x), bfhi(w.x), bflo(w.y), bfhi(w.y)}; }
.LBB0_2220_u1:
	s_andn2_b64 vcc, exec, s[10:11]
	s_cbranch_vccnz .LBB0_2209_u1
	v_mov_b32_e32 v130, v187
	v_mov_b32_e32 v131, v189
	v_mov_b32_e32 v187, v188
	v_pk_mul_f32 v[130:131], v[130:131], v[190:191] op_sel_hi:[1,0]
	v_pk_mul_f32 v[132:133], v[186:187], v[190:191] op_sel_hi:[1,0]
	v_pk_mul_f32 v[130:131], v[4:5], v[130:131]
	v_pk_mul_f32 v[132:133], v[2:3], v[132:133]
	s_lshl_b64 s[8:9], s[6:7], 11
	s_waitcnt vmcnt(11)
	v_pk_fma_f32 v[36:37], v[100:101], v[130:131], v[36:37]
	v_pk_fma_f32 v[34:35], v[98:99], v[132:133], v[34:35]
	v_lshl_add_u64 v[142:143], v[160:161], 0, s[8:9]
	v_cvt_pk_bf16_f32 v34, v34, v35
	v_cvt_pk_bf16_f32 v35, v36, v37
	global_store_dwordx2 v[142:143], v[34:35], off nt
	v_lshlrev_b32_e32 v130, 16, v34
	v_and_b32_e32 v131, 0xffff0000, v34
	v_lshlrev_b32_e32 v132, 16, v35
	v_and_b32_e32 v133, 0xffff0000, v35
	v_mov_b32_e32 v34, v183
	v_mov_b32_e32 v35, v185
	v_mov_b32_e32 v183, v184
	v_pk_mul_f32 v[34:35], v[34:35], v[190:191] op_sel_hi:[1,0]
	v_pk_mul_f32 v[36:37], v[182:183], v[190:191] op_sel_hi:[1,0]
	v_pk_mul_f32 v[34:35], v[8:9], v[34:35]
	v_pk_mul_f32 v[36:37], v[6:7], v[36:37]
	s_waitcnt vmcnt(8)
	v_pk_fma_f32 v[40:41], v[104:105], v[34:35], v[40:41]
	v_pk_fma_f32 v[38:39], v[102:103], v[36:37], v[38:39]
	s_nop 0
	v_cvt_pk_bf16_f32 v38, v38, v39
	v_cvt_pk_bf16_f32 v39, v40, v41
	global_store_dwordx2 v[142:143], v[38:39], off offset:512 nt
	v_lshlrev_b32_e32 v134, 16, v38
	v_and_b32_e32 v135, 0xffff0000, v38
	v_lshlrev_b32_e32 v136, 16, v39
	v_and_b32_e32 v137, 0xffff0000, v39
	v_pk_mul_f32 v[38:39], v[178:179], v[190:191] op_sel_hi:[1,0]
	v_pk_mul_f32 v[40:41], v[180:181], v[190:191] op_sel_hi:[1,0]
	v_pk_mul_f32 v[38:39], v[18:19], v[38:39]
	v_pk_mul_f32 v[40:41], v[20:21], v[40:41]
	s_waitcnt vmcnt(8)
	v_pk_fma_f32 v[42:43], v[106:107], v[38:39], v[42:43]
	v_pk_fma_f32 v[44:45], v[108:109], v[40:41], v[44:45]
	v_cvt_pk_bf16_f32 v42, v42, v43
	v_cvt_pk_bf16_f32 v43, v44, v45
	global_store_dwordx2 v[142:143], v[42:43], off offset:1024 nt
	v_lshlrev_b32_e32 v138, 16, v42
	v_and_b32_e32 v139, 0xffff0000, v42
	v_lshlrev_b32_e32 v140, 16, v43
	v_and_b32_e32 v141, 0xffff0000, v43
	v_pk_mul_f32 v[42:43], v[176:177], v[190:191] op_sel_hi:[1,0]
	v_pk_mul_f32 v[44:45], v[174:175], v[190:191] op_sel_hi:[1,0]
	v_pk_mul_f32 v[42:43], v[24:25], v[42:43]
	v_pk_mul_f32 v[44:45], v[22:23], v[44:45]
	s_waitcnt vmcnt(7)
	v_pk_fma_f32 v[48:49], v[112:113], v[42:43], v[48:49]
	v_pk_fma_f32 v[46:47], v[110:111], v[44:45], v[46:47]
	s_nop 0
	v_cvt_pk_bf16_f32 v46, v46, v47
	v_cvt_pk_bf16_f32 v47, v48, v49
	global_store_dwordx2 v[142:143], v[46:47], off offset:1536 nt
	v_lshlrev_b32_e32 v142, 16, v46
	v_and_b32_e32 v143, 0xffff0000, v46
	v_lshlrev_b32_e32 v144, 16, v47
	v_and_b32_e32 v145, 0xffff0000, v47
	s_branch .LBB0_2209_u1
; #define GAS __attribute__((address_space(1)))
; DI unsigned pk2(float lo, float hi) { f32x2_t v = {lo, hi}; bf16x2_t b = __builtin_convertvector(v, bf16x2_t); return __builtin_bit_cast(unsigned, b); }
; DI void phase_e(const Ctx& C, int nslab, int has_post, int pl, int ps, float pw, int has_pre, int ql, int qs, int nrows,
;                 const GAS float* xsrc, const GAS float* csrc, GAS float* xdst, GAS float* cdst, bool xs16, bool xd16) {
;     ...
;         if (has_pre) {
;             float ss = 0.f;
; #pragma unroll
;             for (int j = 0; j < 4; ++j) ss += (v[j][0] * v[j][0] + v[j][1] * v[j][1]) + (v[j][2] * v[j][2] + v[j][3] * v[j][3]);
;             const float r = rsqrtf(wave_sum(ss) * (1.0f / 1024.0f) + EPS);
; #pragma unroll
;             for (int j = 0; j < 4; ++j) { const f32x4 h = ((v[j] * r) * gpr[j]) * (1.0f + sc[j]) + sh[j];
;                 u32x2 w; w.x = pk2(h[0], h[1]); w.y = pk2(h[2], h[3]); *(GAS u32x2*)(H + (size_t)row * 1024 + 256 * j + 4 * lane) = w; }
;         }
.LBB0_2209_u1:
	v_pk_mul_f32 v[42:43], v[132:133], v[132:133]
	v_pk_mul_f32 v[44:45], v[130:131], v[130:131]
	v_pk_mul_f32 v[46:47], v[136:137], v[136:137]
	v_pk_mul_f32 v[48:49], v[134:135], v[134:135]
	v_pk_mov_b32 v[38:39], v[44:45], v[42:43] op_sel:[1,0]
	v_mov_b32_e32 v45, v43
	v_pk_add_f32 v[42:43], v[38:39], v[44:45]
	v_pk_mov_b32 v[44:45], v[48:49], v[46:47] op_sel:[1,0]
	v_mov_b32_e32 v49, v47
	v_pk_add_f32 v[46:47], v[44:45], v[48:49]
	v_pk_add_f32 v[42:43], v[42:43], v[42:43] op_sel_hi:[0,1]
	v_pk_add_f32 v[46:47], v[46:47], v[46:47] op_sel_hi:[0,1]
	v_mul_f32_e32 v46, v138, v138
	v_pk_fma_f32 v[48:49], v[138:139], v[138:139], v[46:47] op_sel_hi:[1,1,0]
	v_mul_f32_e32 v46, v140, v140
	v_pk_fma_f32 v[44:45], v[140:141], v[140:141], v[46:47] op_sel_hi:[1,1,0]
	v_mul_f32_e32 v48, v142, v142
	v_mul_f32_e32 v44, v143, v143
	v_mul_f32_e32 v42, v144, v144
	v_mul_f32_e32 v46, v145, v145
	v_pk_add_f32 v[48:49], v[48:49], v[44:45]
	v_pk_add_f32 v[46:47], v[42:43], v[46:47]
	s_waitcnt vmcnt(10)
	v_pk_add_f32 v[42:43], v[70:71], 1.0 op_sel_hi:[1,0]
	v_pk_add_f32 v[46:47], v[48:49], v[46:47]
	v_pk_add_f32 v[48:49], v[72:73], 1.0 op_sel_hi:[1,0]
	v_add_f32_e32 v46, v46, v47
	s_nop 1
	v_add_f32_dpp v46, v46, v46 quad_perm:[1,0,3,2] row_mask:0xf bank_mask:0xf
	s_nop 1
	v_add_f32_dpp v46, v46, v46 quad_perm:[2,3,0,1] row_mask:0xf bank_mask:0xf
	s_nop 1
	v_add_f32_dpp v46, v46, v46 row_half_mirror row_mask:0xf bank_mask:0xf
	s_nop 1
	v_add_f32_dpp v46, v46, v46 row_mirror row_mask:0xf bank_mask:0xf
	s_nop 1
	v_add_f32_dpp v46, v46, v46 row_bcast:15 row_mask:0xa bank_mask:0xf
	s_nop 1
	v_add_f32_dpp v46, v46, v46 row_bcast:31 row_mask:0xc bank_mask:0xf
	s_nop 0
	v_readlane_b32 s64, v46, 63
	s_nop 1
	v_mov_b32_e32 v46, s64
	s_waitcnt lgkmcnt(0)
	s_add_i32 s16, s16, 8
	s_cmp_lt_i32 s16, s17
	v_fmamk_f32 v46, v46, 0x3a800000, v197
	v_mul_f32_e32 v47, 0x4b800000, v46
	v_cmp_gt_f32_e32 vcc, s22, v46
	s_nop 1
	v_cndmask_b32_e32 v46, v46, v47, vcc
	v_rsq_f32_e32 v44, v46
	v_lshl_add_u64 v[46:47], v[162:163], 0, s[8:9]
	v_mul_f32_e32 v45, 0x45800000, v44
	v_cndmask_b32_e32 v44, v44, v45, vcc
	v_pk_mul_f32 v[38:39], v[132:133], v[44:45] op_sel_hi:[1,0]
	v_pk_mul_f32 v[40:41], v[130:131], v[44:45] op_sel_hi:[1,0]
	v_pk_mul_f32 v[38:39], v[12:13], v[38:39]
	v_pk_mul_f32 v[40:41], v[10:11], v[40:41]
	s_waitcnt vmcnt(9)
	v_pk_fma_f32 v[48:49], v[48:49], v[38:39], v[76:77]
	v_pk_fma_f32 v[42:43], v[42:43], v[40:41], v[74:75]
	v_pk_mul_f32 v[34:35], v[136:137], v[44:45] op_sel_hi:[1,0]
	v_pk_mul_f32 v[36:37], v[134:135], v[44:45] op_sel_hi:[1,0]
	v_cvt_pk_bf16_f32 v42, v42, v43
	v_cvt_pk_bf16_f32 v43, v48, v49
	v_pk_mul_f32 v[36:37], v[14:15], v[36:37]
	global_store_dwordx2 v[46:47], v[42:43], off
	v_pk_mul_f32 v[48:49], v[16:17], v[34:35]
	s_waitcnt vmcnt(6)
	v_pk_add_f32 v[42:43], v[80:81], 1.0 op_sel_hi:[1,0]
	v_pk_add_f32 v[38:39], v[78:79], 1.0 op_sel_hi:[1,0]
	v_pk_fma_f32 v[48:49], v[42:43], v[48:49], v[84:85]
	v_pk_fma_f32 v[42:43], v[38:39], v[36:37], v[82:83]
	s_waitcnt vmcnt(4)
	v_pk_add_f32 v[38:39], v[88:89], 1.0 op_sel_hi:[1,0]
	v_cvt_pk_bf16_f32 v42, v42, v43
	v_cvt_pk_bf16_f32 v43, v48, v49
	global_store_dwordx2 v[46:47], v[42:43], off offset:512
	v_pk_mul_f32 v[48:49], v[140:141], v[44:45] op_sel_hi:[1,0]
	v_pk_mul_f32 v[42:43], v[138:139], v[44:45] op_sel_hi:[1,0]
	v_pk_mul_f32 v[48:49], v[28:29], v[48:49]
	v_pk_mul_f32 v[42:43], v[26:27], v[42:43]
	v_pk_add_f32 v[40:41], v[86:87], 1.0 op_sel_hi:[1,0]
	s_waitcnt vmcnt(3)
	v_pk_fma_f32 v[48:49], v[38:39], v[48:49], v[96:97]
	v_pk_fma_f32 v[42:43], v[40:41], v[42:43], v[94:95]
	v_pk_add_f32 v[38:39], v[66:67], 1.0 op_sel_hi:[1,0]
	v_cvt_pk_bf16_f32 v42, v42, v43
	v_cvt_pk_bf16_f32 v43, v48, v49
	global_store_dwordx2 v[46:47], v[42:43], off offset:1024
	v_pk_mul_f32 v[48:49], v[144:145], v[44:45] op_sel_hi:[1,0]
	v_pk_mul_f32 v[42:43], v[142:143], v[44:45] op_sel_hi:[1,0]
	v_pk_mul_f32 v[48:49], v[32:33], v[48:49]
	v_pk_mul_f32 v[42:43], v[30:31], v[42:43]
	v_pk_add_f32 v[44:45], v[68:69], 1.0 op_sel_hi:[1,0]
	s_waitcnt vmcnt(3)
	v_pk_fma_f32 v[42:43], v[38:39], v[42:43], v[90:91]
	v_pk_fma_f32 v[48:49], v[44:45], v[48:49], v[92:93]
	v_cvt_pk_bf16_f32 v42, v42, v43
	v_cvt_pk_bf16_f32 v43, v48, v49
	global_store_dwordx2 v[46:47], v[42:43], off offset:1536
	s_mov_b64 vcc, s[98:99]
	s_cbranch_vccz .Leload_skip_3_u1
	s_waitcnt vmcnt(8)
	v_lshlrev_b32_e32 v62, 16, v64
	v_and_b32_e32 v63, 0xffff0000, v64
	v_lshlrev_b32_e32 v64, 16, v65
	v_and_b32_e32 v65, 0xffff0000, v65
	v_lshlrev_b32_e32 v58, 16, v60
	v_and_b32_e32 v59, 0xffff0000, v60
	v_lshlrev_b32_e32 v60, 16, v61
	v_and_b32_e32 v61, 0xffff0000, v61
	v_lshlrev_b32_e32 v54, 16, v56
	v_and_b32_e32 v55, 0xffff0000, v56
	v_lshlrev_b32_e32 v56, 16, v57
	v_and_b32_e32 v57, 0xffff0000, v57
	v_lshlrev_b32_e32 v50, 16, v52
	v_and_b32_e32 v51, 0xffff0000, v52
	v_lshlrev_b32_e32 v52, 16, v53
	v_and_b32_e32 v53, 0xffff0000, v53

.LBB0_2210_u2:
	s_mov_b64 s[98:99], 0
	s_add_i32 s6, s18, s16
	s_add_i32 s0, s16, 16
	s_cmp_ge_i32 s0, s17
	s_cbranch_scc1 .LBB0_2216_u2
	s_add_i32 s10, s6, 16
	s_cmpk_gt_i32 s10, 0x7fff
	s_mov_b64 s[12:13], -1
	s_cbranch_scc0 .LBB0_2213_u2
	s_add_i32 s0, s6, 0xffff8010
	s_lshl_b64 s[8:9], s[0:1], 12
	v_lshl_add_u64 v[46:47], v[164:165], 0, s[8:9]
	global_load_dwordx4 v[34:37], v[46:47], off nt
	global_load_dwordx4 v[38:41], v[46:47], off offset:1024 nt
	global_load_dwordx4 v[42:45], v[46:47], off offset:2048 nt
	s_nop 0
	global_load_dwordx4 v[46:49], v[46:47], off offset:3072 nt
	s_mov_b32 s11, s1
	s_lshl_b64 s[8:9], s[10:11], 11
	s_mov_b64 s[12:13], 0
.LBB0_2213_u2:
	s_andn2_b64 vcc, exec, s[12:13]
	s_cbranch_vccnz .LBB0_2215_u2
	s_ashr_i32 s11, s10, 31
	s_lshl_b64 s[8:9], s[10:11], 11
	s_waitcnt vmcnt(3)
	v_lshl_add_u64 v[34:35], v[156:157], 0, s[8:9]
	global_load_dwordx2 v[36:37], v[34:35], off nt
	global_load_dwordx2 v[40:41], v[34:35], off offset:512 nt
	global_load_dwordx2 v[44:45], v[34:35], off offset:1024 nt
	global_load_dwordx2 v[48:49], v[34:35], off offset:1536 nt
	s_mov_b64 s[98:99], -1

; #define GAS __attribute__((address_space(1)))
; DI unsigned pk2(float lo, float hi) { f32x2_t v = {lo, hi}; bf16x2_t b = __builtin_convertvector(v, bf16x2_t); return __builtin_bit_cast(unsigned, b); }
; DI float bflo(unsigned w) { return __uint_as_float(w << 16); }
; DI float bfhi(unsigned w) { return __uint_as_float(w & 0xffff0000u); }
; DI void phase_e(const Ctx& C, int nslab, int has_post, int pl, int ps, float pw, int has_pre, int ql, int qs, int nrows,
;                 const GAS float* xsrc, const GAS float* csrc, GAS float* xdst, GAS float* cdst, bool xs16, bool xd16) {
;     ...
;         if (has_post) {
;             f32x4 y[4]; float ss = 0.f;
; #pragma unroll
;             for (int j = 0; j < 4; ++j) {
;                 if (isx || nslab == 0) { y[j] = (f32x4){bflo(yw[j].x), bfhi(yw[j].x), bflo(yw[j].y), bfhi(yw[j].y)}; }
;                 else { y[j] = (f32x4){0.f, 0.f, 0.f, 0.f};
;                     for (int s = 0; s < nslab; ++s) { const u32x2 w = *(const GAS u32x2*)(YS + ((size_t)s * MC + (row - MX)) * 1024 + 256 * j + 4 * lane); y[j] += (f32x4){bflo(w.x), bfhi(w.x), bflo(w.y), bfhi(w.y)}; } }
;                 ss += (y[j][0] * y[j][0] + y[j][1] * y[j][1]) + (y[j][2] * y[j][2] + y[j][3] * y[j][3]); }
;             const float r = rsqrtf(wave_sum(ss) * (1.0f / 1024.0f) + EPS);
;             if (isx && xd16) { GAS bf16* d16 = (GAS bf16*)xdst + (size_t)row * 1024;
; #pragma unroll
;                 for (int j = 0; j < 4; ++j) { v[j] += pw * gt[j] * ((y[j] * r) * gpo[j]); u32x2 w; w.x = pk2(v[j][0], v[j][1]); w.y = pk2(v[j][2], v[j][3]); __builtin_nontemporal_store(w, (GAS u32x2*)(d16 + 256 * j + 4 * lane));
;                     v[j] = (f32x4){bflo(w.x), bfhi(w.x), bflo(w.y), bfhi(w.y)}; }
;             } else { GAS float* dst = isx ? xdst + (size_t)row * 1024 : cdst + (size_t)(row - MX) * 1024;
; #pragma unroll
;                 for (int j = 0; j < 4; ++j) { v[j] += pw * gt[j] * ((y[j] * r) * gpo[j]); __builtin_nontemporal_store(v[j], (GAS f32x4*)(dst + 256 * j + 4 * lane)); } }
.LBB0_2218_u2:
	v_and_b32_e32 v189, 0xffff0000, v137
	v_and_b32_e32 v188, 0xffff0000, v136
	v_and_b32_e32 v185, 0xffff0000, v135
	v_and_b32_e32 v184, 0xffff0000, v134
	v_lshlrev_b32_e32 v187, 16, v137
	v_lshlrev_b32_e32 v186, 16, v136
	v_pk_mul_f32 v[136:137], v[188:189], v[188:189]
	v_lshlrev_b32_e32 v183, 16, v135
	v_lshlrev_b32_e32 v182, 16, v134
	v_pk_mul_f32 v[134:135], v[184:185], v[184:185]
	v_lshlrev_b32_e32 v178, 16, v132
	v_and_b32_e32 v179, 0xffff0000, v132
	v_lshlrev_b32_e32 v180, 16, v133
	v_lshlrev_b32_e32 v174, 16, v130
	v_pk_fma_f32 v[136:137], v[186:187], v[186:187], v[136:137]
	v_pk_fma_f32 v[134:135], v[182:183], v[182:183], v[134:135]
	v_mul_f32_e32 v139, v178, v178
	v_mul_f32_e32 v141, v179, v179
	v_and_b32_e32 v181, 0xffff0000, v133
	v_mul_f32_e32 v132, v180, v180
	v_mov_b32_e32 v138, v174
	v_mov_b32_e32 v140, v174
	v_pk_add_f32 v[136:137], v[136:137], v[136:137] op_sel_hi:[0,1]
	v_pk_add_f32 v[134:135], v[134:135], v[134:135] op_sel_hi:[0,1]
	v_pk_fma_f32 v[132:133], v[180:181], v[180:181], v[132:133] op_sel_hi:[1,1,0]
	v_and_b32_e32 v175, 0xffff0000, v130
	v_lshlrev_b32_e32 v176, 16, v131
	v_and_b32_e32 v177, 0xffff0000, v131
	v_pk_add_f32 v[138:139], v[138:139], v[140:141]
	v_mul_f32_e32 v132, v175, v175
	v_mul_f32_e32 v134, v176, v176
	v_mul_f32_e32 v136, v177, v177
	v_mul_f32_e32 v130, v174, v174
	v_mov_b32_e32 v131, v139
	v_pk_add_f32 v[130:131], v[130:131], v[132:133]
	v_pk_add_f32 v[132:133], v[134:135], v[136:137]
	s_ashr_i32 s7, s6, 31
	v_pk_add_f32 v[130:131], v[130:131], v[132:133]
	s_cmpk_gt_i32 s6, 0x7fff
	v_add_f32_e32 v130, v130, v131
	s_nop 1
	v_add_f32_dpp v130, v130, v130 quad_perm:[1,0,3,2] row_mask:0xf bank_mask:0xf
	s_nop 1
	v_add_f32_dpp v130, v130, v130 quad_perm:[2,3,0,1] row_mask:0xf bank_mask:0xf
	s_nop 1
	v_add_f32_dpp v130, v130, v130 row_half_mirror row_mask:0xf bank_mask:0xf
	s_nop 1
	v_add_f32_dpp v130, v130, v130 row_mirror row_mask:0xf bank_mask:0xf
	s_nop 1
	v_add_f32_dpp v130, v130, v130 row_bcast:15 row_mask:0xa bank_mask:0xf
	s_nop 1
	v_add_f32_dpp v130, v130, v130 row_bcast:31 row_mask:0xc bank_mask:0xf
	s_nop 0
	v_readlane_b32 s64, v130, 63
	s_nop 1
	v_mov_b32_e32 v130, s64
	s_waitcnt lgkmcnt(0)
	s_mov_b64 s[10:11], -1
	v_fmamk_f32 v130, v130, 0x3a800000, v197
	v_mul_f32_e32 v131, 0x4b800000, v130
	v_cmp_gt_f32_e32 vcc, s22, v130
	s_nop 1
	v_cndmask_b32_e32 v130, v130, v131, vcc
	v_rsq_f32_e32 v130, v130
	s_nop 0
	v_mul_f32_e32 v131, 0x45800000, v130
	v_cndmask_b32_e32 v190, v130, v131, vcc
	s_cbranch_scc0 .LBB0_2220_u2
	v_mov_b32_e32 v130, v187
	v_mov_b32_e32 v131, v189
	v_mov_b32_e32 v132, v186
	v_mov_b32_e32 v133, v188
	v_pk_mul_f32 v[130:131], v[130:131], v[190:191] op_sel_hi:[1,0]
	v_pk_mul_f32 v[132:133], v[132:133], v[190:191] op_sel_hi:[1,0]
	v_pk_mul_f32 v[130:131], v[4:5], v[130:131]
	v_pk_mul_f32 v[134:135], v[2:3], v[132:133]
	s_waitcnt vmcnt(11)
	v_pk_fma_f32 v[132:133], v[100:101], v[130:131], v[116:117]
	v_pk_fma_f32 v[130:131], v[98:99], v[134:135], v[114:115]
	v_mov_b32_e32 v134, v183
	v_mov_b32_e32 v135, v185
	v_mov_b32_e32 v136, v182
	v_mov_b32_e32 v137, v184
	v_pk_mul_f32 v[134:135], v[134:135], v[190:191] op_sel_hi:[1,0]
	v_pk_mul_f32 v[136:137], v[136:137], v[190:191] op_sel_hi:[1,0]
	v_pk_mul_f32 v[134:135], v[8:9], v[134:135]
	v_pk_mul_f32 v[138:139], v[6:7], v[136:137]
	s_add_i32 s0, s6, 0xffff8000
	s_waitcnt vmcnt(7)
	v_pk_fma_f32 v[136:137], v[104:105], v[134:135], v[120:121]
	v_pk_fma_f32 v[134:135], v[102:103], v[138:139], v[118:119]
	v_pk_mul_f32 v[138:139], v[178:179], v[190:191] op_sel_hi:[1,0]
	v_pk_mul_f32 v[140:141], v[180:181], v[190:191] op_sel_hi:[1,0]
	v_pk_mul_f32 v[142:143], v[176:177], v[190:191] op_sel_hi:[1,0]
	v_pk_mul_f32 v[144:145], v[174:175], v[190:191] op_sel_hi:[1,0]
	s_lshl_b64 s[8:9], s[0:1], 12
	v_pk_mul_f32 v[138:139], v[18:19], v[138:139]
	v_pk_mul_f32 v[140:141], v[20:21], v[140:141]
	v_pk_mul_f32 v[200:201], v[22:23], v[144:145]
	v_pk_mul_f32 v[142:143], v[24:25], v[142:143]
	v_lshl_add_u64 v[198:199], v[164:165], 0, s[8:9]
	s_waitcnt vmcnt(6)
	v_pk_fma_f32 v[140:141], v[108:109], v[140:141], v[124:125]
	v_pk_fma_f32 v[138:139], v[106:107], v[138:139], v[122:123]
	s_waitcnt vmcnt(4)
	v_pk_fma_f32 v[144:145], v[112:113], v[142:143], v[128:129]
	v_pk_fma_f32 v[142:143], v[110:111], v[200:201], v[126:127]
	global_store_dwordx4 v[198:199], v[130:133], off nt
	global_store_dwordx4 v[198:199], v[134:137], off offset:1024 nt
	global_store_dwordx4 v[198:199], v[138:141], off offset:2048 nt
	global_store_dwordx4 v[198:199], v[142:145], off offset:3072 nt
	s_lshl_b64 s[8:9], s[6:7], 11
	s_mov_b64 s[10:11], 0
; #define GAS __attribute__((address_space(1)))
; DI unsigned pk2(float lo, float hi) { f32x2_t v = {lo, hi}; bf16x2_t b = __builtin_convertvector(v, bf16x2_t); return __builtin_bit_cast(unsigned, b); }
; DI float bflo(unsigned w) { return __uint_as_float(w << 16); }
; DI float bfhi(unsigned w) { return __uint_as_float(w & 0xffff0000u); }
; DI void phase_e(const Ctx& C, int nslab, int has_post, int pl, int ps, float pw, int has_pre, int ql, int qs, int nrows,
;                 const GAS float* xsrc, const GAS float* csrc, GAS float* xdst, GAS float* cdst, bool xs16, bool xd16) {
;     ...
;             if (isx && xd16) { GAS bf16* d16 = (GAS bf16*)xdst + (size_t)row * 1024;
; #pragma unroll
;                 for (int j = 0; j < 4; ++j) { v[j] += pw * gt[j] * ((y[j] * r) * gpo[j]); u32x2 w; w.x = pk2(v[j][0], v[j][1]); w.y = pk2(v[j][2], v[j][3]); __builtin_nontemporal_store(w, (GAS u32x2*)(d16 + 256 * j + 4 * lane));
;                     v[j] = (f32x4){bflo(w.x), bfhi(w.x), bflo(w.y), bfhi(w.y)}; }
.LBB0_2220_u2:
	s_andn2_b64 vcc, exec, s[10:11]
	s_cbranch_vccnz .LBB0_2209
	v_mov_b32_e32 v130, v187
	v_mov_b32_e32 v131, v189
	v_mov_b32_e32 v187, v188
	v_pk_mul_f32 v[130:131], v[130:131], v[190:191] op_sel_hi:[1,0]
	v_pk_mul_f32 v[132:133], v[186:187], v[190:191] op_sel_hi:[1,0]
	v_pk_mul_f32 v[130:131], v[4:5], v[130:131]
	v_pk_mul_f32 v[132:133], v[2:3], v[132:133]
	s_lshl_b64 s[8:9], s[6:7], 11
	s_waitcnt vmcnt(11)
	v_pk_fma_f32 v[116:117], v[100:101], v[130:131], v[116:117]
	v_pk_fma_f32 v[114:115], v[98:99], v[132:133], v[114:115]
	v_lshl_add_u64 v[142:143], v[160:161], 0, s[8:9]
	v_cvt_pk_bf16_f32 v114, v114, v115
	v_cvt_pk_bf16_f32 v115, v116, v117
	global_store_dwordx2 v[142:143], v[114:115], off nt
	v_lshlrev_b32_e32 v130, 16, v114
	v_and_b32_e32 v131, 0xffff0000, v114
	v_lshlrev_b32_e32 v132, 16, v115
	v_and_b32_e32 v133, 0xffff0000, v115
	v_mov_b32_e32 v114, v183
	v_mov_b32_e32 v115, v185
	v_mov_b32_e32 v183, v184
	v_pk_mul_f32 v[114:115], v[114:115], v[190:191] op_sel_hi:[1,0]
	v_pk_mul_f32 v[116:117], v[182:183], v[190:191] op_sel_hi:[1,0]
	v_pk_mul_f32 v[114:115], v[8:9], v[114:115]
	v_pk_mul_f32 v[116:117], v[6:7], v[116:117]
	s_waitcnt vmcnt(8)
	v_pk_fma_f32 v[120:121], v[104:105], v[114:115], v[120:121]
	v_pk_fma_f32 v[118:119], v[102:103], v[116:117], v[118:119]
	s_nop 0
	v_cvt_pk_bf16_f32 v118, v118, v119
	v_cvt_pk_bf16_f32 v119, v120, v121
	global_store_dwordx2 v[142:143], v[118:119], off offset:512 nt
	v_lshlrev_b32_e32 v134, 16, v118
	v_and_b32_e32 v135, 0xffff0000, v118
	v_lshlrev_b32_e32 v136, 16, v119
	v_and_b32_e32 v137, 0xffff0000, v119
	v_pk_mul_f32 v[118:119], v[178:179], v[190:191] op_sel_hi:[1,0]
	v_pk_mul_f32 v[120:121], v[180:181], v[190:191] op_sel_hi:[1,0]
	v_pk_mul_f32 v[118:119], v[18:19], v[118:119]
	v_pk_mul_f32 v[120:121], v[20:21], v[120:121]
	s_waitcnt vmcnt(8)
	v_pk_fma_f32 v[122:123], v[106:107], v[118:119], v[122:123]
	v_pk_fma_f32 v[124:125], v[108:109], v[120:121], v[124:125]
	v_cvt_pk_bf16_f32 v122, v122, v123
	v_cvt_pk_bf16_f32 v123, v124, v125
	global_store_dwordx2 v[142:143], v[122:123], off offset:1024 nt
	v_lshlrev_b32_e32 v138, 16, v122
	v_and_b32_e32 v139, 0xffff0000, v122
	v_lshlrev_b32_e32 v140, 16, v123
	v_and_b32_e32 v141, 0xffff0000, v123
	v_pk_mul_f32 v[122:123], v[176:177], v[190:191] op_sel_hi:[1,0]
	v_pk_mul_f32 v[124:125], v[174:175], v[190:191] op_sel_hi:[1,0]
	v_pk_mul_f32 v[122:123], v[24:25], v[122:123]
	v_pk_mul_f32 v[124:125], v[22:23], v[124:125]
	s_waitcnt vmcnt(7)
	v_pk_fma_f32 v[128:129], v[112:113], v[122:123], v[128:129]
	v_pk_fma_f32 v[126:127], v[110:111], v[124:125], v[126:127]
	s_nop 0
	v_cvt_pk_bf16_f32 v126, v126, v127
	v_cvt_pk_bf16_f32 v127, v128, v129
	global_store_dwordx2 v[142:143], v[126:127], off offset:1536 nt
	v_lshlrev_b32_e32 v142, 16, v126
	v_and_b32_e32 v143, 0xffff0000, v126
	v_lshlrev_b32_e32 v144, 16, v127
	v_and_b32_e32 v145, 0xffff0000, v127
	s_branch .LBB0_2209

; #define GAS __attribute__((address_space(1)))
; DI unsigned pk2(float lo, float hi) { f32x2_t v = {lo, hi}; bf16x2_t b = __builtin_convertvector(v, bf16x2_t); return __builtin_bit_cast(unsigned, b); }
; DI float bflo(unsigned w) { return __uint_as_float(w << 16); }
; DI float bfhi(unsigned w) { return __uint_as_float(w & 0xffff0000u); }
; DI void phase_e(const Ctx& C, int nslab, int has_post, int pl, int ps, float pw, int has_pre, int ql, int qs, int nrows,
;                 const GAS float* xsrc, const GAS float* csrc, GAS float* xdst, GAS float* cdst, bool xs16, bool xd16) {
;     ...
;         if (has_post) {
;             f32x4 y[4]; float ss = 0.f;
; #pragma unroll
;             for (int j = 0; j < 4; ++j) {
;                 if (isx || nslab == 0) { y[j] = (f32x4){bflo(yw[j].x), bfhi(yw[j].x), bflo(yw[j].y), bfhi(yw[j].y)}; }
;                 else { y[j] = (f32x4){0.f, 0.f, 0.f, 0.f};
;                     for (int s = 0; s < nslab; ++s) { const u32x2 w = *(const GAS u32x2*)(YS + ((size_t)s * MC + (row - MX)) * 1024 + 256 * j + 4 * lane); y[j] += (f32x4){bflo(w.x), bfhi(w.x), bflo(w.y), bfhi(w.y)}; } }
;                 ss += (y[j][0] * y[j][0] + y[j][1] * y[j][1]) + (y[j][2] * y[j][2] + y[j][3] * y[j][3]); }
;             const float r = rsqrtf(wave_sum(ss) * (1.0f / 1024.0f) + EPS);
;             if (isx && xd16) { GAS bf16* d16 = (GAS bf16*)xdst + (size_t)row * 1024;
; #pragma unroll
;                 for (int j = 0; j < 4; ++j) { v[j] += pw * gt[j] * ((y[j] * r) * gpo[j]); u32x2 w; w.x = pk2(v[j][0], v[j][1]); w.y = pk2(v[j][2], v[j][3]); __builtin_nontemporal_store(w, (GAS u32x2*)(d16 + 256 * j + 4 * lane));
;                     v[j] = (f32x4){bflo(w.x), bfhi(w.x), bflo(w.y), bfhi(w.y)}; }
;             } else { GAS float* dst = isx ? xdst + (size_t)row * 1024 : cdst + (size_t)(row - MX) * 1024;
; #pragma unroll
;                 for (int j = 0; j < 4; ++j) { v[j] += pw * gt[j] * ((y[j] * r) * gpo[j]); __builtin_nontemporal_store(v[j], (GAS f32x4*)(dst + 256 * j + 4 * lane)); } }
.LBB0_2444:
	v_lshlrev_b32_e32 v123, 16, v107
	v_lshlrev_b32_e32 v122, 16, v106
	v_and_b32_e32 v107, 0xffff0000, v107
	v_and_b32_e32 v106, 0xffff0000, v106
	v_pk_mul_f32 v[124:125], v[106:107], v[106:107]
	v_lshlrev_b32_e32 v127, 16, v109
	v_pk_fma_f32 v[124:125], v[122:123], v[122:123], v[124:125]
	v_lshlrev_b32_e32 v126, 16, v108
	v_and_b32_e32 v109, 0xffff0000, v109
	v_and_b32_e32 v108, 0xffff0000, v108
	v_pk_add_f32 v[124:125], v[124:125], v[124:125] op_sel_hi:[0,1]
	v_pk_mul_f32 v[128:129], v[108:109], v[108:109]
	v_lshlrev_b32_e32 v130, 16, v110
	v_and_b32_e32 v131, 0xffff0000, v110
	v_lshlrev_b32_e32 v110, 16, v111
	v_lshlrev_b32_e32 v132, 16, v112
	v_pk_fma_f32 v[128:129], v[126:127], v[126:127], v[128:129]
	v_mul_f32_e32 v133, v130, v130
	v_mul_f32_e32 v135, v131, v131
	v_and_b32_e32 v111, 0xffff0000, v111
	v_mul_f32_e32 v124, v110, v110
	v_mov_b32_e32 v134, v132
	v_pk_add_f32 v[128:129], v[128:129], v[128:129] op_sel_hi:[0,1]
	v_pk_fma_f32 v[136:137], v[110:111], v[110:111], v[124:125] op_sel_hi:[1,1,0]
	v_and_b32_e32 v121, 0xffff0000, v112
	v_lshlrev_b32_e32 v112, 16, v113
	v_and_b32_e32 v113, 0xffff0000, v113
	v_pk_add_f32 v[134:135], v[132:133], v[134:135]
	v_mul_f32_e32 v136, v121, v121
	v_mul_f32_e32 v128, v112, v112
	v_mul_f32_e32 v124, v113, v113
	v_mul_f32_e32 v138, v132, v132
	v_mov_b32_e32 v139, v135
	v_pk_add_f32 v[134:135], v[138:139], v[136:137]
	v_pk_add_f32 v[124:125], v[128:129], v[124:125]
	s_add_i32 s2, s19, 0xffff8000
	v_pk_add_f32 v[124:125], v[134:135], v[124:125]
	s_ashr_i32 s6, s19, 31
	v_add_f32_e32 v124, v124, v125
	s_nop 1
	v_add_f32_dpp v124, v124, v124 quad_perm:[1,0,3,2] row_mask:0xf bank_mask:0xf
	s_nop 1
	v_add_f32_dpp v124, v124, v124 quad_perm:[2,3,0,1] row_mask:0xf bank_mask:0xf
	s_nop 1
	v_add_f32_dpp v124, v124, v124 row_half_mirror row_mask:0xf bank_mask:0xf
	s_nop 1
	v_add_f32_dpp v124, v124, v124 row_mirror row_mask:0xf bank_mask:0xf
	s_nop 1
	v_add_f32_dpp v124, v124, v124 row_bcast:15 row_mask:0xa bank_mask:0xf
	s_nop 1
	v_add_f32_dpp v124, v124, v124 row_bcast:31 row_mask:0xc bank_mask:0xf
	s_nop 0
	v_readlane_b32 s64, v124, 63
	s_nop 1
	v_mov_b32_e32 v124, s64
	s_waitcnt lgkmcnt(0)
	s_cmp_lt_i32 s19, 0x8000
	v_mov_b32_e32 v136, v123
	v_mov_b32_e32 v123, v106
	s_cselect_b32 s7, s6, 0
	s_cselect_b32 s6, s19, s2
	v_mov_b32_e32 v137, v107
	s_cselect_b32 s2, s75, s1
	s_cselect_b32 s8, s74, s0
	s_lshl_b64 s[6:7], s[6:7], 12
	s_waitcnt vmcnt(1)
	v_pk_mul_f32 v[134:135], v[50:51], 0.5 op_sel_hi:[1,0]
	s_add_u32 s6, s8, s6
	v_pk_mul_f32 v[128:129], v[52:53], 0.5 op_sel_hi:[1,0]
	s_addc_u32 s7, s2, s7
	v_mov_b32_e32 v133, v121
	s_add_i32 s14, s14, 8
	s_cmp_lt_i32 s14, s15
	v_fmamk_f32 v124, v124, 0x3a800000, v120
	v_mul_f32_e32 v125, 0x4b800000, v124
	v_cmp_gt_f32_e32 vcc, s18, v124
	s_nop 1
	v_cndmask_b32_e32 v124, v124, v125, vcc
	v_rsq_f32_e32 v124, v124
	s_nop 0
	v_mul_f32_e32 v125, 0x45800000, v124
	v_cndmask_b32_e32 v124, v124, v125, vcc
	v_pk_mul_f32 v[106:107], v[122:123], v[124:125] op_sel_hi:[1,0]
	v_pk_mul_f32 v[136:137], v[136:137], v[124:125] op_sel_hi:[1,0]
	v_pk_mul_f32 v[106:107], v[2:3], v[106:107]
	v_pk_mul_f32 v[122:123], v[4:5], v[136:137]
	v_pk_fma_f32 v[66:67], v[134:135], v[106:107], v[66:67]
	v_mov_b32_e32 v106, v127
	v_mov_b32_e32 v107, v109
	v_mov_b32_e32 v127, v108
	v_pk_fma_f32 v[68:69], v[128:129], v[122:123], v[68:69]
	v_pk_mul_f32 v[106:107], v[106:107], v[124:125] op_sel_hi:[1,0]
	v_pk_mul_f32 v[108:109], v[126:127], v[124:125] op_sel_hi:[1,0]
	global_store_dwordx4 v82, v[66:69], s[6:7] nt
	v_pk_mul_f32 v[108:109], v[6:7], v[108:109]
	v_pk_mul_f32 v[106:107], v[8:9], v[106:107]
	v_pk_mul_f32 v[66:67], v[56:57], 0.5 op_sel_hi:[1,0]
	v_pk_mul_f32 v[68:69], v[54:55], 0.5 op_sel_hi:[1,0]
	v_pk_fma_f32 v[72:73], v[66:67], v[106:107], v[72:73]
	v_pk_fma_f32 v[70:71], v[68:69], v[108:109], v[70:71]
	v_pk_mul_f32 v[66:67], v[110:111], v[124:125] op_sel_hi:[1,0]
	v_pk_mul_f32 v[68:69], v[130:131], v[124:125] op_sel_hi:[1,0]
	global_store_dwordx4 v82, v[70:73], s[6:7] offset:1024 nt
	v_pk_mul_f32 v[68:69], v[10:11], v[68:69]
	v_pk_mul_f32 v[66:67], v[12:13], v[66:67]
	v_pk_mul_f32 v[70:71], v[60:61], 0.5 op_sel_hi:[1,0]
	v_pk_mul_f32 v[72:73], v[58:59], 0.5 op_sel_hi:[1,0]
	v_pk_fma_f32 v[76:77], v[70:71], v[66:67], v[76:77]
	v_pk_fma_f32 v[74:75], v[72:73], v[68:69], v[74:75]
	v_pk_mul_f32 v[70:71], v[112:113], v[124:125] op_sel_hi:[1,0]
	v_pk_mul_f32 v[72:73], v[132:133], v[124:125] op_sel_hi:[1,0]
	global_store_dwordx4 v82, v[74:77], s[6:7] offset:2048 nt
	v_pk_mul_f32 v[72:73], v[14:15], v[72:73]
	v_pk_mul_f32 v[70:71], v[16:17], v[70:71]
	s_waitcnt vmcnt(3)
	v_pk_mul_f32 v[74:75], v[64:65], 0.5 op_sel_hi:[1,0]
	v_pk_mul_f32 v[76:77], v[62:63], 0.5 op_sel_hi:[1,0]
	v_pk_fma_f32 v[80:81], v[74:75], v[70:71], v[80:81]
	v_pk_fma_f32 v[78:79], v[76:77], v[72:73], v[78:79]
	global_store_dwordx4 v82, v[78:81], s[6:7] offset:3072 nt
	s_mov_b64 vcc, s[98:99]
	s_cbranch_vccz .Leload_skip_4_u2
	s_waitcnt vmcnt(4)
	v_lshlrev_b32_e32 v34, 16, v36
	v_and_b32_e32 v35, 0xffff0000, v36
	v_lshlrev_b32_e32 v36, 16, v37
	v_and_b32_e32 v37, 0xffff0000, v37
	v_lshlrev_b32_e32 v38, 16, v40
	v_and_b32_e32 v39, 0xffff0000, v40
	v_lshlrev_b32_e32 v40, 16, v41
	v_and_b32_e32 v41, 0xffff0000, v41
	v_lshlrev_b32_e32 v42, 16, v44
	v_and_b32_e32 v43, 0xffff0000, v44
	v_lshlrev_b32_e32 v44, 16, v45
	v_and_b32_e32 v45, 0xffff0000, v45
	v_lshlrev_b32_e32 v46, 16, v48
	v_and_b32_e32 v47, 0xffff0000, v48
	v_lshlrev_b32_e32 v48, 16, v49
	v_and_b32_e32 v49, 0xffff0000, v49
.Leload_skip_4_u2:
	s_cbranch_scc0 .LBB0_2453

; #define GAS __attribute__((address_space(1)))
; DI float bflo(unsigned w) { return __uint_as_float(w << 16); }
; DI void phase_e(const Ctx& C, int nslab, int has_post, int pl, int ps, float pw, int has_pre, int ql, int qs, int nrows,
;                 const GAS float* xsrc, const GAS float* csrc, GAS float* xdst, GAS float* cdst, bool xs16, bool xd16) {
;     ...
;         if (mi != cur) { cur = mi;
; #pragma unroll
;             for (int j = 0; j < 4; ++j) {
;                 if (has_post) gt[j] = *(const GAS f32x4*)(mod + (size_t)(pl * 5 + mi) * 9216 + (3 * ps + 2) * 1024 + 256 * j + 4 * lane);
;                 if (has_pre) { sc[j] = *(const GAS f32x4*)(mod + (size_t)(ql * 5 + mi) * 9216 + (3 * qs + 1) * 1024 + 256 * j + 4 * lane);
;                                sh[j] = *(const GAS f32x4*)(mod + (size_t)(ql * 5 + mi) * 9216 + (3 * qs) * 1024 + 256 * j + 4 * lane); }
;             } }
;         if (has_post) {
;             f32x4 y[4]; float ss = 0.f;
; #pragma unroll
;             for (int j = 0; j < 4; ++j) {
;                 if (isx || nslab == 0) { y[j] = (f32x4){bflo(yw[j].x), bfhi(yw[j].x), bflo(yw[j].y), bfhi(yw[j].y)}; }
;                 else { y[j] = (f32x4){0.f, 0.f, 0.f, 0.f};
;                     for (int s = 0; s < nslab; ++s) { const u32x2 w = *(const GAS u32x2*)(YS + ((size_t)s * MC + (row - MX)) * 1024 + 256 * j + 4 * lane); y[j] += (f32x4){bflo(w.x), bfhi(w.x), bflo(w.y), bfhi(w.y)}; } }
;                 ss += (y[j][0] * y[j][0] + y[j][1] * y[j][1]) + (y[j][2] * y[j][2] + y[j][3] * y[j][3]); }
;             const float r = rsqrtf(wave_sum(ss) * (1.0f / 1024.0f) + EPS);
;             if (isx && xd16) { GAS bf16* d16 = (GAS bf16*)xdst + (size_t)row * 1024;
; #pragma unroll
;                 for (int j = 0; j < 4; ++j) { v[j] += pw * gt[j] * ((y[j] * r) * gpo[j]); u32x2 w; w.x = pk2(v[j][0], v[j][1]); w.y = pk2(v[j][2], v[j][3]); __builtin_nontemporal_store(w, (GAS u32x2*)(d16 + 256 * j + 4 * lane));
;                     v[j] = (f32x4){bflo(w.x), bfhi(w.x), bflo(w.y), bfhi(w.y)}; }
;             } else { GAS float* dst = isx ? xdst + (size_t)row * 1024 : cdst + (size_t)(row - MX) * 1024;
; #pragma unroll
;                 for (int j = 0; j < 4; ++j) { v[j] += pw * gt[j] * ((y[j] * r) * gpo[j]); __builtin_nontemporal_store(v[j], (GAS f32x4*)(dst + 256 * j + 4 * lane)); } }
.LBB0_2451:
	s_min_i32 s2, s19, 0x8000
	s_ashr_i32 s2, s2, 13
	s_cmp_eq_u32 s2, s17
	s_cbranch_scc1 .LBB0_2444_u0
	s_add_i32 s6, s2, 5
	s_mul_hi_i32 s7, s6, 0x9000
	s_mul_i32 s6, s6, 0x9000
	s_add_u32 s6, s12, s6
	s_addc_u32 s7, s13, s7
	v_lshl_add_u64 v[50:51], s[6:7], 0, v[82:83]
	v_lshl_add_u64 v[122:123], v[50:51], 0, s[4:5]
	v_add_co_u32_e32 v124, vcc, 0x8000, v50
	s_mov_b32 s17, s2
	s_nop 0
	v_addc_co_u32_e32 v125, vcc, 0, v51, vcc
	global_load_dwordx4 v[54:57], v[122:123], off offset:1024
	global_load_dwordx4 v[58:61], v[122:123], off offset:2048
	global_load_dwordx4 v[50:53], v[124:125], off
	global_load_dwordx4 v[62:65], v[122:123], off offset:3072
	s_branch .LBB0_2444_u0
.LBB0_2444_u0:
	v_lshlrev_b32_e32 v123, 16, v99
	v_lshlrev_b32_e32 v122, 16, v98
	v_and_b32_e32 v99, 0xffff0000, v99
	v_and_b32_e32 v98, 0xffff0000, v98
	v_pk_mul_f32 v[124:125], v[98:99], v[98:99]
	v_lshlrev_b32_e32 v127, 16, v91
	v_pk_fma_f32 v[124:125], v[122:123], v[122:123], v[124:125]
	v_lshlrev_b32_e32 v126, 16, v90
	v_and_b32_e32 v91, 0xffff0000, v91
	v_and_b32_e32 v90, 0xffff0000, v90
	v_pk_add_f32 v[124:125], v[124:125], v[124:125] op_sel_hi:[0,1]
	v_pk_mul_f32 v[128:129], v[90:91], v[90:91]
	v_lshlrev_b32_e32 v130, 16, v86
	v_and_b32_e32 v131, 0xffff0000, v86
	v_lshlrev_b32_e32 v86, 16, v87
	v_lshlrev_b32_e32 v132, 16, v84
	v_pk_fma_f32 v[128:129], v[126:127], v[126:127], v[128:129]
	v_mul_f32_e32 v133, v130, v130
	v_mul_f32_e32 v135, v131, v131
	v_and_b32_e32 v87, 0xffff0000, v87
	v_mul_f32_e32 v124, v86, v86
	v_mov_b32_e32 v134, v132
	v_pk_add_f32 v[128:129], v[128:129], v[128:129] op_sel_hi:[0,1]
	v_pk_fma_f32 v[136:137], v[86:87], v[86:87], v[124:125] op_sel_hi:[1,1,0]
	v_and_b32_e32 v121, 0xffff0000, v84
	v_lshlrev_b32_e32 v84, 16, v85
	v_and_b32_e32 v85, 0xffff0000, v85
	v_pk_add_f32 v[134:135], v[132:133], v[134:135]
	v_mul_f32_e32 v136, v121, v121
	v_mul_f32_e32 v128, v84, v84
	v_mul_f32_e32 v124, v85, v85
	v_mul_f32_e32 v138, v132, v132
	v_mov_b32_e32 v139, v135
	v_pk_add_f32 v[134:135], v[138:139], v[136:137]
	v_pk_add_f32 v[124:125], v[128:129], v[124:125]
	s_add_i32 s2, s19, 0xffff8000
	v_pk_add_f32 v[124:125], v[134:135], v[124:125]
	s_ashr_i32 s6, s19, 31
	v_add_f32_e32 v124, v124, v125
	s_nop 1
	v_add_f32_dpp v124, v124, v124 quad_perm:[1,0,3,2] row_mask:0xf bank_mask:0xf
	s_nop 1
	v_add_f32_dpp v124, v124, v124 quad_perm:[2,3,0,1] row_mask:0xf bank_mask:0xf
	s_nop 1
	v_add_f32_dpp v124, v124, v124 row_half_mirror row_mask:0xf bank_mask:0xf
	s_nop 1
	v_add_f32_dpp v124, v124, v124 row_mirror row_mask:0xf bank_mask:0xf
	s_nop 1
	v_add_f32_dpp v124, v124, v124 row_bcast:15 row_mask:0xa bank_mask:0xf
	s_nop 1
	v_add_f32_dpp v124, v124, v124 row_bcast:31 row_mask:0xc bank_mask:0xf
	s_nop 0
	v_readlane_b32 s64, v124, 63
	s_nop 1
	v_mov_b32_e32 v124, s64
	s_waitcnt lgkmcnt(0)
	s_cmp_lt_i32 s19, 0x8000
	v_mov_b32_e32 v136, v123
	v_mov_b32_e32 v123, v98
	s_cselect_b32 s7, s6, 0
	s_cselect_b32 s6, s19, s2
	v_mov_b32_e32 v137, v99
	s_cselect_b32 s2, s75, s1
	s_cselect_b32 s8, s74, s0
	s_lshl_b64 s[6:7], s[6:7], 12
	s_waitcnt vmcnt(1)
	v_pk_mul_f32 v[134:135], v[50:51], 0.5 op_sel_hi:[1,0]
	s_add_u32 s6, s8, s6
	v_pk_mul_f32 v[128:129], v[52:53], 0.5 op_sel_hi:[1,0]
	s_addc_u32 s7, s2, s7
	v_mov_b32_e32 v133, v121
	s_add_i32 s14, s14, 8
	s_cmp_lt_i32 s14, s15
	v_fmamk_f32 v124, v124, 0x3a800000, v120
	v_mul_f32_e32 v125, 0x4b800000, v124
	v_cmp_gt_f32_e32 vcc, s18, v124
	s_nop 1
	v_cndmask_b32_e32 v124, v124, v125, vcc
	v_rsq_f32_e32 v124, v124
	s_nop 0
	v_mul_f32_e32 v125, 0x45800000, v124
	v_cndmask_b32_e32 v124, v124, v125, vcc
	v_pk_mul_f32 v[98:99], v[122:123], v[124:125] op_sel_hi:[1,0]
	v_pk_mul_f32 v[136:137], v[136:137], v[124:125] op_sel_hi:[1,0]
	v_pk_mul_f32 v[98:99], v[2:3], v[98:99]
	v_pk_mul_f32 v[122:123], v[4:5], v[136:137]
	v_pk_fma_f32 v[30:31], v[134:135], v[98:99], v[30:31]
	v_mov_b32_e32 v98, v127
	v_mov_b32_e32 v99, v91
	v_mov_b32_e32 v127, v90
	v_pk_fma_f32 v[32:33], v[128:129], v[122:123], v[32:33]
	v_pk_mul_f32 v[98:99], v[98:99], v[124:125] op_sel_hi:[1,0]
	v_pk_mul_f32 v[90:91], v[126:127], v[124:125] op_sel_hi:[1,0]
	global_store_dwordx4 v82, v[30:33], s[6:7] nt
	v_pk_mul_f32 v[90:91], v[6:7], v[90:91]
	v_pk_mul_f32 v[98:99], v[8:9], v[98:99]
	v_pk_mul_f32 v[30:31], v[56:57], 0.5 op_sel_hi:[1,0]
	v_pk_mul_f32 v[32:33], v[54:55], 0.5 op_sel_hi:[1,0]
	v_pk_fma_f32 v[28:29], v[30:31], v[98:99], v[28:29]
	v_pk_fma_f32 v[26:27], v[32:33], v[90:91], v[26:27]
	v_pk_mul_f32 v[30:31], v[86:87], v[124:125] op_sel_hi:[1,0]
	v_pk_mul_f32 v[32:33], v[130:131], v[124:125] op_sel_hi:[1,0]
	global_store_dwordx4 v82, v[26:29], s[6:7] offset:1024 nt
	v_pk_mul_f32 v[32:33], v[10:11], v[32:33]
	v_pk_mul_f32 v[30:31], v[12:13], v[30:31]
	v_pk_mul_f32 v[26:27], v[60:61], 0.5 op_sel_hi:[1,0]
	v_pk_mul_f32 v[28:29], v[58:59], 0.5 op_sel_hi:[1,0]
	v_pk_fma_f32 v[24:25], v[26:27], v[30:31], v[24:25]
	v_pk_fma_f32 v[22:23], v[28:29], v[32:33], v[22:23]
	v_pk_mul_f32 v[26:27], v[84:85], v[124:125] op_sel_hi:[1,0]
	v_pk_mul_f32 v[28:29], v[132:133], v[124:125] op_sel_hi:[1,0]
	global_store_dwordx4 v82, v[22:25], s[6:7] offset:2048 nt
	v_pk_mul_f32 v[28:29], v[14:15], v[28:29]
	v_pk_mul_f32 v[26:27], v[16:17], v[26:27]
	s_waitcnt vmcnt(3)
	v_pk_mul_f32 v[22:23], v[64:65], 0.5 op_sel_hi:[1,0]
	v_pk_mul_f32 v[24:25], v[62:63], 0.5 op_sel_hi:[1,0]
	v_pk_fma_f32 v[20:21], v[22:23], v[26:27], v[20:21]
	v_pk_fma_f32 v[18:19], v[24:25], v[28:29], v[18:19]
	global_store_dwordx4 v82, v[18:21], s[6:7] offset:3072 nt
	s_mov_b64 vcc, s[98:99]
	s_cbranch_vccz .Leload_skip_4
	s_waitcnt vmcnt(4)
	v_lshlrev_b32_e32 v66, 16, v68
	v_and_b32_e32 v67, 0xffff0000, v68
	v_lshlrev_b32_e32 v68, 16, v69
	v_and_b32_e32 v69, 0xffff0000, v69
	v_lshlrev_b32_e32 v70, 16, v72
	v_and_b32_e32 v71, 0xffff0000, v72
	v_lshlrev_b32_e32 v72, 16, v73
	v_and_b32_e32 v73, 0xffff0000, v73
	v_lshlrev_b32_e32 v74, 16, v76
	v_and_b32_e32 v75, 0xffff0000, v76
	v_lshlrev_b32_e32 v76, 16, v77
	v_and_b32_e32 v77, 0xffff0000, v77
	v_lshlrev_b32_e32 v78, 16, v80
	v_and_b32_e32 v79, 0xffff0000, v80
	v_lshlrev_b32_e32 v80, 16, v81
	v_and_b32_e32 v81, 0xffff0000, v81

.LBB0_2445_u1:
	s_mov_b64 s[98:99], 0
	s_add_i32 s19, s16, s14
	s_add_i32 s2, s14, 16
	s_cmp_ge_i32 s2, s15
	s_cbranch_scc1 .LBB0_2451_u1
	s_add_i32 s8, s19, 16
	s_cmpk_gt_i32 s8, 0x7fff
	s_mov_b64 s[10:11], -1
	s_cbranch_scc0 .LBB0_2448_u1
	s_add_i32 s2, s19, 0xffff8010
	s_lshl_b64 s[6:7], s[2:3], 12
	v_lshl_add_u64 v[98:99], v[104:105], 0, s[6:7]
	global_load_dwordx4 v[30:33], v[98:99], off nt
	global_load_dwordx4 v[26:29], v[98:99], off offset:1024 nt
	global_load_dwordx4 v[22:25], v[98:99], off offset:2048 nt
	global_load_dwordx4 v[18:21], v[98:99], off offset:3072 nt
	s_mov_b32 s9, s3
	s_lshl_b64 s[6:7], s[8:9], 11
	s_mov_b64 s[10:11], 0
.LBB0_2448_u1:
	s_andn2_b64 vcc, exec, s[10:11]
	s_cbranch_vccnz .LBB0_2450_u1
	s_ashr_i32 s9, s8, 31
	s_lshl_b64 s[6:7], s[8:9], 11
	s_waitcnt vmcnt(3)
	v_lshl_add_u64 v[30:31], v[100:101], 0, s[6:7]
	global_load_dwordx2 v[32:33], v[30:31], off nt
	global_load_dwordx2 v[28:29], v[30:31], off offset:512 nt
	global_load_dwordx2 v[24:25], v[30:31], off offset:1024 nt
	global_load_dwordx2 v[20:21], v[30:31], off offset:1536 nt
	s_mov_b64 s[98:99], -1
.LBB0_2450_u1:
	v_lshl_add_u64 v[122:123], v[102:103], 0, s[6:7]
	global_load_dwordx2 v[98:99], v[122:123], off nt
	global_load_dwordx2 v[90:91], v[122:123], off offset:512 nt
	global_load_dwordx2 v[86:87], v[122:123], off offset:1024 nt
	global_load_dwordx2 v[84:85], v[122:123], off offset:1536 nt

; #define GAS __attribute__((address_space(1)))
; DI unsigned pk2(float lo, float hi) { f32x2_t v = {lo, hi}; bf16x2_t b = __builtin_convertvector(v, bf16x2_t); return __builtin_bit_cast(unsigned, b); }
; DI float bflo(unsigned w) { return __uint_as_float(w << 16); }
; DI float bfhi(unsigned w) { return __uint_as_float(w & 0xffff0000u); }
; DI void phase_e(const Ctx& C, int nslab, int has_post, int pl, int ps, float pw, int has_pre, int ql, int qs, int nrows,
;                 const GAS float* xsrc, const GAS float* csrc, GAS float* xdst, GAS float* cdst, bool xs16, bool xd16) {
;     ...
;         if (has_post) {
;             f32x4 y[4]; float ss = 0.f;
; #pragma unroll
;             for (int j = 0; j < 4; ++j) {
;                 if (isx || nslab == 0) { y[j] = (f32x4){bflo(yw[j].x), bfhi(yw[j].x), bflo(yw[j].y), bfhi(yw[j].y)}; }
;                 else { y[j] = (f32x4){0.f, 0.f, 0.f, 0.f};
;                     for (int s = 0; s < nslab; ++s) { const u32x2 w = *(const GAS u32x2*)(YS + ((size_t)s * MC + (row - MX)) * 1024 + 256 * j + 4 * lane); y[j] += (f32x4){bflo(w.x), bfhi(w.x), bflo(w.y), bfhi(w.y)}; } }
;                 ss += (y[j][0] * y[j][0] + y[j][1] * y[j][1]) + (y[j][2] * y[j][2] + y[j][3] * y[j][3]); }
;             const float r = rsqrtf(wave_sum(ss) * (1.0f / 1024.0f) + EPS);
;             if (isx && xd16) { GAS bf16* d16 = (GAS bf16*)xdst + (size_t)row * 1024;
; #pragma unroll
;                 for (int j = 0; j < 4; ++j) { v[j] += pw * gt[j] * ((y[j] * r) * gpo[j]); u32x2 w; w.x = pk2(v[j][0], v[j][1]); w.y = pk2(v[j][2], v[j][3]); __builtin_nontemporal_store(w, (GAS u32x2*)(d16 + 256 * j + 4 * lane));
;                     v[j] = (f32x4){bflo(w.x), bfhi(w.x), bflo(w.y), bfhi(w.y)}; }
;             } else { GAS float* dst = isx ? xdst + (size_t)row * 1024 : cdst + (size_t)(row - MX) * 1024;
; #pragma unroll
;                 for (int j = 0; j < 4; ++j) { v[j] += pw * gt[j] * ((y[j] * r) * gpo[j]); __builtin_nontemporal_store(v[j], (GAS f32x4*)(dst + 256 * j + 4 * lane)); } }
.LBB0_2444_u1:
	v_lshlrev_b32_e32 v123, 16, v89
	v_lshlrev_b32_e32 v122, 16, v88
	v_and_b32_e32 v89, 0xffff0000, v89
	v_and_b32_e32 v88, 0xffff0000, v88
	v_pk_mul_f32 v[124:125], v[88:89], v[88:89]
	v_lshlrev_b32_e32 v127, 16, v93
	v_pk_fma_f32 v[124:125], v[122:123], v[122:123], v[124:125]
	v_lshlrev_b32_e32 v126, 16, v92
	v_and_b32_e32 v93, 0xffff0000, v93
	v_and_b32_e32 v92, 0xffff0000, v92
	v_pk_add_f32 v[124:125], v[124:125], v[124:125] op_sel_hi:[0,1]
	v_pk_mul_f32 v[128:129], v[92:93], v[92:93]
	v_lshlrev_b32_e32 v130, 16, v94
	v_and_b32_e32 v131, 0xffff0000, v94
	v_lshlrev_b32_e32 v94, 16, v95
	v_lshlrev_b32_e32 v132, 16, v96
	v_pk_fma_f32 v[128:129], v[126:127], v[126:127], v[128:129]
	v_mul_f32_e32 v133, v130, v130
	v_mul_f32_e32 v135, v131, v131
	v_and_b32_e32 v95, 0xffff0000, v95
	v_mul_f32_e32 v124, v94, v94
	v_mov_b32_e32 v134, v132
	v_pk_add_f32 v[128:129], v[128:129], v[128:129] op_sel_hi:[0,1]
	v_pk_fma_f32 v[136:137], v[94:95], v[94:95], v[124:125] op_sel_hi:[1,1,0]
	v_and_b32_e32 v121, 0xffff0000, v96
	v_lshlrev_b32_e32 v96, 16, v97
	v_and_b32_e32 v97, 0xffff0000, v97
	v_pk_add_f32 v[134:135], v[132:133], v[134:135]
	v_mul_f32_e32 v136, v121, v121
	v_mul_f32_e32 v128, v96, v96
	v_mul_f32_e32 v124, v97, v97
	v_mul_f32_e32 v138, v132, v132
	v_mov_b32_e32 v139, v135
	v_pk_add_f32 v[134:135], v[138:139], v[136:137]
	v_pk_add_f32 v[124:125], v[128:129], v[124:125]
	s_add_i32 s2, s19, 0xffff8000
	v_pk_add_f32 v[124:125], v[134:135], v[124:125]
	s_ashr_i32 s6, s19, 31
	v_add_f32_e32 v124, v124, v125
	s_nop 1
	v_add_f32_dpp v124, v124, v124 quad_perm:[1,0,3,2] row_mask:0xf bank_mask:0xf
	s_nop 1
	v_add_f32_dpp v124, v124, v124 quad_perm:[2,3,0,1] row_mask:0xf bank_mask:0xf
	s_nop 1
	v_add_f32_dpp v124, v124, v124 row_half_mirror row_mask:0xf bank_mask:0xf
	s_nop 1
	v_add_f32_dpp v124, v124, v124 row_mirror row_mask:0xf bank_mask:0xf
	s_nop 1
	v_add_f32_dpp v124, v124, v124 row_bcast:15 row_mask:0xa bank_mask:0xf
	s_nop 1
	v_add_f32_dpp v124, v124, v124 row_bcast:31 row_mask:0xc bank_mask:0xf
	s_nop 0
	v_readlane_b32 s64, v124, 63
	s_nop 1
	v_mov_b32_e32 v124, s64
	s_waitcnt lgkmcnt(0)
	s_cmp_lt_i32 s19, 0x8000
	v_mov_b32_e32 v136, v123
	v_mov_b32_e32 v123, v88
	s_cselect_b32 s7, s6, 0
	s_cselect_b32 s6, s19, s2
	v_mov_b32_e32 v137, v89
	s_cselect_b32 s2, s75, s1
	s_cselect_b32 s8, s74, s0
	s_lshl_b64 s[6:7], s[6:7], 12
	s_waitcnt vmcnt(1)
	v_pk_mul_f32 v[134:135], v[50:51], 0.5 op_sel_hi:[1,0]
	s_add_u32 s6, s8, s6
	v_pk_mul_f32 v[128:129], v[52:53], 0.5 op_sel_hi:[1,0]
	s_addc_u32 s7, s2, s7
	v_mov_b32_e32 v133, v121
	s_add_i32 s14, s14, 8
	s_cmp_lt_i32 s14, s15
	v_fmamk_f32 v124, v124, 0x3a800000, v120
	v_mul_f32_e32 v125, 0x4b800000, v124
	v_cmp_gt_f32_e32 vcc, s18, v124
	s_nop 1
	v_cndmask_b32_e32 v124, v124, v125, vcc
	v_rsq_f32_e32 v124, v124
	s_nop 0
	v_mul_f32_e32 v125, 0x45800000, v124
	v_cndmask_b32_e32 v124, v124, v125, vcc
	v_pk_mul_f32 v[88:89], v[122:123], v[124:125] op_sel_hi:[1,0]
	v_pk_mul_f32 v[136:137], v[136:137], v[124:125] op_sel_hi:[1,0]
	v_pk_mul_f32 v[88:89], v[2:3], v[88:89]
	v_pk_mul_f32 v[122:123], v[4:5], v[136:137]
	v_pk_fma_f32 v[34:35], v[134:135], v[88:89], v[34:35]
	v_mov_b32_e32 v88, v127
	v_mov_b32_e32 v89, v93
	v_mov_b32_e32 v127, v92
	v_pk_fma_f32 v[36:37], v[128:129], v[122:123], v[36:37]
	v_pk_mul_f32 v[88:89], v[88:89], v[124:125] op_sel_hi:[1,0]
	v_pk_mul_f32 v[92:93], v[126:127], v[124:125] op_sel_hi:[1,0]
	global_store_dwordx4 v82, v[34:37], s[6:7] nt
	v_pk_mul_f32 v[92:93], v[6:7], v[92:93]
	v_pk_mul_f32 v[88:89], v[8:9], v[88:89]
	v_pk_mul_f32 v[34:35], v[56:57], 0.5 op_sel_hi:[1,0]
	v_pk_mul_f32 v[36:37], v[54:55], 0.5 op_sel_hi:[1,0]
	v_pk_fma_f32 v[40:41], v[34:35], v[88:89], v[40:41]
	v_pk_fma_f32 v[38:39], v[36:37], v[92:93], v[38:39]
	v_pk_mul_f32 v[34:35], v[94:95], v[124:125] op_sel_hi:[1,0]
	v_pk_mul_f32 v[36:37], v[130:131], v[124:125] op_sel_hi:[1,0]
	global_store_dwordx4 v82, v[38:41], s[6:7] offset:1024 nt
	v_pk_mul_f32 v[36:37], v[10:11], v[36:37]
	v_pk_mul_f32 v[34:35], v[12:13], v[34:35]
	v_pk_mul_f32 v[38:39], v[60:61], 0.5 op_sel_hi:[1,0]
	v_pk_mul_f32 v[40:41], v[58:59], 0.5 op_sel_hi:[1,0]
	v_pk_fma_f32 v[44:45], v[38:39], v[34:35], v[44:45]
	v_pk_fma_f32 v[42:43], v[40:41], v[36:37], v[42:43]
	v_pk_mul_f32 v[38:39], v[96:97], v[124:125] op_sel_hi:[1,0]
	v_pk_mul_f32 v[40:41], v[132:133], v[124:125] op_sel_hi:[1,0]
	global_store_dwordx4 v82, v[42:45], s[6:7] offset:2048 nt
	v_pk_mul_f32 v[40:41], v[14:15], v[40:41]
	v_pk_mul_f32 v[38:39], v[16:17], v[38:39]
	s_waitcnt vmcnt(3)
	v_pk_mul_f32 v[42:43], v[64:65], 0.5 op_sel_hi:[1,0]
	v_pk_mul_f32 v[44:45], v[62:63], 0.5 op_sel_hi:[1,0]
	v_pk_fma_f32 v[48:49], v[42:43], v[38:39], v[48:49]
	v_pk_fma_f32 v[46:47], v[44:45], v[40:41], v[46:47]
	global_store_dwordx4 v82, v[46:49], s[6:7] offset:3072 nt
	s_mov_b64 vcc, s[98:99]
	s_cbranch_vccz .Leload_skip_4_u1
	s_waitcnt vmcnt(4)
	v_lshlrev_b32_e32 v30, 16, v32
	v_and_b32_e32 v31, 0xffff0000, v32
	v_lshlrev_b32_e32 v32, 16, v33
	v_and_b32_e32 v33, 0xffff0000, v33
	v_lshlrev_b32_e32 v26, 16, v28
	v_and_b32_e32 v27, 0xffff0000, v28
	v_lshlrev_b32_e32 v28, 16, v29
	v_and_b32_e32 v29, 0xffff0000, v29
	v_lshlrev_b32_e32 v22, 16, v24
	v_and_b32_e32 v23, 0xffff0000, v24
	v_lshlrev_b32_e32 v24, 16, v25
	v_and_b32_e32 v25, 0xffff0000, v25
	v_lshlrev_b32_e32 v18, 16, v20
	v_and_b32_e32 v19, 0xffff0000, v20
	v_lshlrev_b32_e32 v20, 16, v21
	v_and_b32_e32 v21, 0xffff0000, v21

.LBB0_2445_u2:
	s_mov_b64 s[98:99], 0
	s_add_i32 s19, s16, s14
	s_add_i32 s2, s14, 16
	s_cmp_ge_i32 s2, s15
	s_cbranch_scc1 .LBB0_2451_u2
	s_add_i32 s8, s19, 16
	s_cmpk_gt_i32 s8, 0x7fff
	s_mov_b64 s[10:11], -1
	s_cbranch_scc0 .LBB0_2448_u2
	s_add_i32 s2, s19, 0xffff8010
	s_lshl_b64 s[6:7], s[2:3], 12
	v_lshl_add_u64 v[88:89], v[104:105], 0, s[6:7]
	global_load_dwordx4 v[34:37], v[88:89], off nt
	global_load_dwordx4 v[38:41], v[88:89], off offset:1024 nt
	global_load_dwordx4 v[42:45], v[88:89], off offset:2048 nt
	global_load_dwordx4 v[46:49], v[88:89], off offset:3072 nt
	s_mov_b32 s9, s3
	s_lshl_b64 s[6:7], s[8:9], 11
	s_mov_b64 s[10:11], 0
.LBB0_2448_u2:
	s_andn2_b64 vcc, exec, s[10:11]
	s_cbranch_vccnz .LBB0_2450_u2
	s_ashr_i32 s9, s8, 31
	s_lshl_b64 s[6:7], s[8:9], 11
	s_waitcnt vmcnt(3)
	v_lshl_add_u64 v[34:35], v[100:101], 0, s[6:7]
	global_load_dwordx2 v[36:37], v[34:35], off nt
	global_load_dwordx2 v[40:41], v[34:35], off offset:512 nt
	global_load_dwordx2 v[44:45], v[34:35], off offset:1024 nt
	global_load_dwordx2 v[48:49], v[34:35], off offset:1536 nt
	s_mov_b64 s[98:99], -1
.LBB0_2450_u2:
	v_lshl_add_u64 v[122:123], v[102:103], 0, s[6:7]
	global_load_dwordx2 v[88:89], v[122:123], off nt
	global_load_dwordx2 v[92:93], v[122:123], off offset:512 nt
	global_load_dwordx2 v[94:95], v[122:123], off offset:1024 nt
	global_load_dwordx2 v[96:97], v[122:123], off offset:1536 nt
